# czero: peel first K-loop trip of every GEMM unit (except P1), first-touch MFMA takes C=0, the 128 accumulator zero-init v_movs leave the normal path
# speedup vs baseline: 1.0059x; 1.0059x over previous
; #define PG8_STAGE(bufoff, gbase, voff) do { _Pragma("unroll") for (int _i = 0; _i < 2; ++_i) \
;         __builtin_amdgcn_global_load_lds((const unsigned*)((const char*)(gbase) + (voff)[_i]), (PG8_LAS unsigned*)(lds + (bufoff) + ldsw + _i * 8192), 16, 0, 0); } while (0)
; #define PG8_LDA(dst, b, h) do { _Pragma("unroll") for (int m = 0; m < 4; ++m) _Pragma("unroll") for (int k = 0; k < 2; ++k) dst[m][k] = *(const PG8_LAS bf16x8*)(lds + PG8_SA(b, h) + aoff + m * 2048 + k * 1024); } while (0)
; #define PG8_LDB(dst, b, h) do { _Pragma("unroll") for (int n = 0; n < 2; ++n) _Pragma("unroll") for (int k = 0; k < 2; ++k) dst[n][k] = *(const PG8_LAS bf16x8*)(lds + PG8_SB(b, h) + boff + n * 2048 + k * 1024); } while (0)
; #define PG8_MMA(ai, bj, At, Bt) do { __builtin_amdgcn_s_setprio(1); _Pragma("unroll") for (int m = 0; m < 4; ++m) _Pragma("unroll") for (int n = 0; n < 2; ++n) _Pragma("unroll") for (int k = 0; k < 2; ++k) \
;         acc[ai][bj][m][n] = __builtin_amdgcn_mfma_f32_16x16x32_bf16(Bt[n][k], At[m][k], acc[ai][bj][m][n], 0, 0, 0); __builtin_amdgcn_s_setprio(0); } while (0)
; #define PG8_WAIT_V(n) asm volatile("s_waitcnt vmcnt(" #n ")" ::: "memory")
; #define PG8_BAR __builtin_amdgcn_s_barrier()
; template <class Epi, class Sched, bool ALIGN_EPI = false, bool SP2 = false>
; __device__ __forceinline__ void gemm_phase(PG8_LAS unsigned char* lds, const Gemm g, const Sched& S, const Epi& E) {
;     ...
;         for (int t = 0; t < nt; t += 2) {
;             const bool last = (t == nt - 2);
;             const char* a1 = cA + (size_t)(t + 1) * kstep;
;             const char* a2 = last ? nA : cA + (size_t)(t + 2) * kstep; const char* b2 = last ? nB : cB + (size_t)(t + 2) * kstep;
;             const char* a3 = a2 + kstep; const char* b3 = b2 + kstep;
;             if (last && has_next) S.a_ready(nxt);
;             if constexpr (SP2) {
;             PG8_LDB(B0, 0, 0); PG8_LDB(B1, 0, 1); PG8_SCHED; PG8_LDA(At, 0, 0); PG8_STAGE(PG8_SA(1, 1), a1 + hstep, voffA);
;             PG8_WAIT_V(8); PG8_WAIT_L(0); PG8_BAR; PG8_MMA(0, 0, At, B0); PG8_MMA(0, 1, At, B1); PG8_BAR; PG8_SCHED;
;     ...
; #pragma unroll
;         for (int a = 0; a < 2; ++a)
; #pragma unroll
;             for (int b = 0; b < 2; ++b)
; #pragma unroll
;                 for (int m = 0; m < 4; ++m)
; #pragma unroll
;                     for (int n = 0; n < 2; ++n) acc[a][b][m][n] = (f32x4){0.f, 0.f, 0.f, 0.f};
.LBB0_458:
	s_andn2_b64 vcc, exec, s[42:43]
	s_cbranch_vccz .Lcz_go_460
	v_mov_b32_e32 v123, 0
	v_mov_b32_e32 v122, v123
	v_mov_b32_e32 v121, v123
	v_mov_b32_e32 v120, v123
	v_mov_b32_e32 v127, v123
	v_mov_b32_e32 v126, v123
	v_mov_b32_e32 v125, v123
	v_mov_b32_e32 v124, v123
	v_mov_b32_e32 v111, v123
	v_mov_b32_e32 v110, v123
	v_mov_b32_e32 v109, v123
	v_mov_b32_e32 v108, v123
	v_mov_b32_e32 v107, v123
	v_mov_b32_e32 v106, v123
	v_mov_b32_e32 v105, v123
	v_mov_b32_e32 v104, v123
	v_mov_b32_e32 v95, v123
	v_mov_b32_e32 v94, v123
	v_mov_b32_e32 v93, v123
	v_mov_b32_e32 v92, v123
	v_mov_b32_e32 v91, v123
	v_mov_b32_e32 v90, v123
	v_mov_b32_e32 v89, v123
	v_mov_b32_e32 v88, v123
	v_mov_b32_e32 v79, v123
	v_mov_b32_e32 v78, v123
	v_mov_b32_e32 v77, v123
	v_mov_b32_e32 v76, v123
	v_mov_b32_e32 v75, v123
	v_mov_b32_e32 v74, v123
	v_mov_b32_e32 v73, v123
	v_mov_b32_e32 v72, v123
	v_mov_b32_e32 v119, v123
	v_mov_b32_e32 v118, v123
	v_mov_b32_e32 v117, v123
	v_mov_b32_e32 v116, v123
	v_mov_b32_e32 v115, v123
	v_mov_b32_e32 v114, v123
	v_mov_b32_e32 v113, v123
	v_mov_b32_e32 v112, v123
	v_mov_b32_e32 v103, v123
	v_mov_b32_e32 v102, v123
	v_mov_b32_e32 v101, v123
	v_mov_b32_e32 v100, v123
	v_mov_b32_e32 v99, v123
	v_mov_b32_e32 v98, v123
	v_mov_b32_e32 v97, v123
	v_mov_b32_e32 v96, v123
	v_mov_b32_e32 v87, v123
	v_mov_b32_e32 v86, v123
	v_mov_b32_e32 v85, v123
	v_mov_b32_e32 v84, v123
	v_mov_b32_e32 v83, v123
	v_mov_b32_e32 v82, v123
	v_mov_b32_e32 v81, v123
	v_mov_b32_e32 v80, v123
	v_mov_b32_e32 v71, v123
	v_mov_b32_e32 v70, v123
	v_mov_b32_e32 v69, v123
	v_mov_b32_e32 v68, v123
	v_mov_b32_e32 v67, v123
	v_mov_b32_e32 v66, v123
	v_mov_b32_e32 v65, v123
	v_mov_b32_e32 v64, v123
	v_mov_b32_e32 v63, v123
	v_mov_b32_e32 v62, v123
	v_mov_b32_e32 v61, v123
	v_mov_b32_e32 v60, v123
	v_mov_b32_e32 v59, v123
	v_mov_b32_e32 v58, v123
	v_mov_b32_e32 v57, v123
	v_mov_b32_e32 v56, v123
	v_mov_b32_e32 v47, v123
	v_mov_b32_e32 v46, v123
	v_mov_b32_e32 v45, v123
	v_mov_b32_e32 v44, v123
	v_mov_b32_e32 v43, v123
	v_mov_b32_e32 v42, v123
	v_mov_b32_e32 v41, v123
	v_mov_b32_e32 v40, v123
	v_mov_b32_e32 v31, v123
	v_mov_b32_e32 v30, v123
	v_mov_b32_e32 v29, v123
	v_mov_b32_e32 v28, v123
	v_mov_b32_e32 v27, v123
	v_mov_b32_e32 v26, v123
	v_mov_b32_e32 v25, v123
	v_mov_b32_e32 v24, v123
	v_mov_b32_e32 v15, v123
	v_mov_b32_e32 v14, v123
	v_mov_b32_e32 v13, v123
	v_mov_b32_e32 v12, v123
	v_mov_b32_e32 v11, v123
	v_mov_b32_e32 v10, v123
	v_mov_b32_e32 v9, v123
	v_mov_b32_e32 v8, v123
	v_mov_b32_e32 v55, v123
	v_mov_b32_e32 v54, v123
	v_mov_b32_e32 v53, v123
	v_mov_b32_e32 v52, v123
	v_mov_b32_e32 v51, v123
	v_mov_b32_e32 v50, v123
	v_mov_b32_e32 v49, v123
	v_mov_b32_e32 v48, v123
	v_mov_b32_e32 v39, v123
	v_mov_b32_e32 v38, v123
	v_mov_b32_e32 v37, v123
	v_mov_b32_e32 v36, v123
	v_mov_b32_e32 v35, v123
	v_mov_b32_e32 v34, v123
	v_mov_b32_e32 v33, v123
	v_mov_b32_e32 v32, v123
	v_mov_b32_e32 v23, v123
	v_mov_b32_e32 v22, v123
	v_mov_b32_e32 v21, v123
	v_mov_b32_e32 v20, v123
	v_mov_b32_e32 v19, v123
	v_mov_b32_e32 v18, v123
	v_mov_b32_e32 v17, v123
	v_mov_b32_e32 v16, v123
	v_mov_b32_e32 v7, v123
	v_mov_b32_e32 v6, v123
	v_mov_b32_e32 v5, v123
	v_mov_b32_e32 v4, v123
	v_mov_b32_e32 v3, v123
	v_mov_b32_e32 v2, v123
	v_mov_b32_e32 v1, v123
	v_mov_b32_e32 v0, v123
	s_branch .LBB0_461
.Lcz_go_460:
	s_add_u32 s0, s62, 0x80
	s_addc_u32 s1, s63, 0
	s_add_u32 s62, s60, 0x100
	s_addc_u32 s63, s61, 0
	s_mov_b32 s60, 0
	ds_read_b128 v[146:149], v154
	ds_read_b128 v[158:161], v154 offset:1024
	ds_read_b128 v[162:165], v154 offset:2048
	ds_read_b128 v[166:169], v154 offset:3072
	ds_read_b128 v[170:173], v155
	ds_read_b128 v[174:177], v155 offset:1024
	ds_read_b128 v[178:181], v155 offset:2048
	ds_read_b128 v[182:185], v155 offset:3072
	s_add_i32 s97, s60, 2
	s_add_u32 s16, s0, 0x80
	s_addc_u32 s17, s1, 0
	s_cmp_eq_u32 s80, s60
	s_cselect_b32 s60, s56, s16
	s_cselect_b32 s61, s57, s17
	s_cselect_b32 vcc_hi, s59, s63
	s_cselect_b32 vcc_lo, s58, s62
	v_lshl_add_u64 v[150:151], s[0:1], 0, v[138:139]
	s_add_i32 m0, s72, 0xc000
	ds_read_b128 v[186:189], v156
	ds_read_b128 v[190:193], v156 offset:1024
	ds_read_b128 v[194:197], v156 offset:2048
	ds_read_b128 v[202:205], v156 offset:3072
	ds_read_b128 v[206:209], v156 offset:4096
	ds_read_b128 v[210:213], v156 offset:5120
	ds_read_b128 v[214:217], v156 offset:6144
	ds_read_b128 v[218:221], v156 offset:7168
	global_load_lds_dwordx4 v[150:151], off
	v_lshl_add_u64 v[150:151], s[0:1], 0, v[140:141]
	s_add_i32 m0, s72, 0xe000
	s_nop 0
	global_load_lds_dwordx4 v[150:151], off
	s_waitcnt vmcnt(8)
	s_waitcnt lgkmcnt(0)
	s_barrier
; #define PG8_STAGE(bufoff, gbase, voff) do { _Pragma("unroll") for (int _i = 0; _i < 2; ++_i) \
;         __builtin_amdgcn_global_load_lds((const unsigned*)((const char*)(gbase) + (voff)[_i]), (PG8_LAS unsigned*)(lds + (bufoff) + ldsw + _i * 8192), 16, 0, 0); } while (0)
; #define PG8_LDA(dst, b, h) do { _Pragma("unroll") for (int m = 0; m < 4; ++m) _Pragma("unroll") for (int k = 0; k < 2; ++k) dst[m][k] = *(const PG8_LAS bf16x8*)(lds + PG8_SA(b, h) + aoff + m * 2048 + k * 1024); } while (0)
; #define PG8_MMA(ai, bj, At, Bt) do { __builtin_amdgcn_s_setprio(1); _Pragma("unroll") for (int m = 0; m < 4; ++m) _Pragma("unroll") for (int n = 0; n < 2; ++n) _Pragma("unroll") for (int k = 0; k < 2; ++k) \
;         acc[ai][bj][m][n] = __builtin_amdgcn_mfma_f32_16x16x32_bf16(Bt[n][k], At[m][k], acc[ai][bj][m][n], 0, 0, 0); __builtin_amdgcn_s_setprio(0); } while (0)
; #define PG8_WAIT_V(n) asm volatile("s_waitcnt vmcnt(" #n ")" ::: "memory")
; #define PG8_WAIT_L(n) asm volatile("s_waitcnt lgkmcnt(" #n ")" ::: "memory")
; #define PG8_BAR __builtin_amdgcn_s_barrier()
; #define PG8_SCHED __builtin_amdgcn_sched_barrier(0)
; template <class Epi, class Sched, bool ALIGN_EPI = false, bool SP2 = false>
; __device__ __forceinline__ void gemm_phase(PG8_LAS unsigned char* lds, const Gemm g, const Sched& S, const Epi& E) {
;     ...
;             PG8_WAIT_V(8); PG8_WAIT_L(0); PG8_BAR; PG8_MMA(0, 0, At, B0); PG8_MMA(0, 1, At, B1); PG8_BAR; PG8_SCHED;
;             PG8_LDA(At, 0, 1); PG8_STAGE(PG8_SB(0, 0), b2, voffB); PG8_STAGE(PG8_SB(0, 1), b2 + hstep, voffB); PG8_STAGE(PG8_SA(0, 0), a2, voffA);
;             PG8_WAIT_V(8); PG8_WAIT_L(0); PG8_BAR; PG8_MMA(1, 0, At, B0); PG8_MMA(1, 1, At, B1); PG8_BAR; PG8_SCHED;
	s_setprio 1
	s_waitcnt lgkmcnt(0)
	v_mfma_f32_16x16x32_bf16 v[120:123], v[146:149], v[186:189], 0
	v_mfma_f32_16x16x32_bf16 v[124:127], v[162:165], v[186:189], 0
	v_mfma_f32_16x16x32_bf16 v[108:111], v[146:149], v[194:197], 0
	v_mfma_f32_16x16x32_bf16 v[104:107], v[162:165], v[194:197], 0
	v_mfma_f32_16x16x32_bf16 v[92:95], v[146:149], v[206:209], 0
	v_mfma_f32_16x16x32_bf16 v[88:91], v[162:165], v[206:209], 0
	v_mfma_f32_16x16x32_bf16 v[76:79], v[146:149], v[214:217], 0
	v_mfma_f32_16x16x32_bf16 v[72:75], v[162:165], v[214:217], 0
	v_mfma_f32_16x16x32_bf16 v[120:123], v[158:161], v[190:193], v[120:123]
	v_mfma_f32_16x16x32_bf16 v[124:127], v[166:169], v[190:193], v[124:127]
	v_mfma_f32_16x16x32_bf16 v[108:111], v[158:161], v[202:205], v[108:111]
	v_mfma_f32_16x16x32_bf16 v[104:107], v[166:169], v[202:205], v[104:107]
	v_mfma_f32_16x16x32_bf16 v[92:95], v[158:161], v[210:213], v[92:95]
	v_mfma_f32_16x16x32_bf16 v[88:91], v[166:169], v[210:213], v[88:91]
	v_mfma_f32_16x16x32_bf16 v[76:79], v[158:161], v[218:221], v[76:79]
	v_mfma_f32_16x16x32_bf16 v[72:75], v[166:169], v[218:221], v[72:75]
	s_setprio 0
	s_setprio 1
	v_mfma_f32_16x16x32_bf16 v[116:119], v[170:173], v[186:189], 0
	v_mfma_f32_16x16x32_bf16 v[112:115], v[178:181], v[186:189], 0
	v_mfma_f32_16x16x32_bf16 v[100:103], v[170:173], v[194:197], 0
	v_mfma_f32_16x16x32_bf16 v[96:99], v[178:181], v[194:197], 0
	v_mfma_f32_16x16x32_bf16 v[84:87], v[170:173], v[206:209], 0
	v_mfma_f32_16x16x32_bf16 v[80:83], v[178:181], v[206:209], 0
	v_mfma_f32_16x16x32_bf16 v[68:71], v[170:173], v[214:217], 0
	v_mfma_f32_16x16x32_bf16 v[64:67], v[178:181], v[214:217], 0
	v_mfma_f32_16x16x32_bf16 v[116:119], v[174:177], v[190:193], v[116:119]
	v_mfma_f32_16x16x32_bf16 v[112:115], v[182:185], v[190:193], v[112:115]
	v_mfma_f32_16x16x32_bf16 v[100:103], v[174:177], v[202:205], v[100:103]
	v_mfma_f32_16x16x32_bf16 v[96:99], v[182:185], v[202:205], v[96:99]
	v_mfma_f32_16x16x32_bf16 v[84:87], v[174:177], v[210:213], v[84:87]
	v_mfma_f32_16x16x32_bf16 v[80:83], v[182:185], v[210:213], v[80:83]
	v_mfma_f32_16x16x32_bf16 v[68:71], v[174:177], v[218:221], v[68:71]
	v_mfma_f32_16x16x32_bf16 v[64:67], v[182:185], v[218:221], v[64:67]
	s_setprio 0
	s_barrier
	s_add_i32 s16, s83, s49
	v_lshl_add_u64 v[150:151], vcc, 0, v[132:133]
	s_mov_b32 m0, s16
	ds_read_b128 v[186:189], v156 offset:16384
	ds_read_b128 v[190:193], v156 offset:17408
	ds_read_b128 v[194:197], v156 offset:18432
	ds_read_b128 v[202:205], v156 offset:19456
	ds_read_b128 v[206:209], v156 offset:20480
	ds_read_b128 v[210:213], v156 offset:21504
	ds_read_b128 v[214:217], v156 offset:22528
	ds_read_b128 v[218:221], v156 offset:23552
	global_load_lds_dwordx4 v[150:151], off
	s_add_i32 m0, s16, 0x2000
	v_lshl_add_u64 v[198:199], vcc, 0, v[128:129]
	s_add_u32 vcc_lo, vcc_lo, s8
	s_addc_u32 vcc_hi, vcc_hi, s9
	s_add_i32 s16, s84, s49
	global_load_lds_dwordx4 v[198:199], off
	v_lshl_add_u64 v[222:223], vcc, 0, v[132:133]
	s_mov_b32 m0, s16
	v_lshl_add_u64 v[224:225], vcc, 0, v[128:129]
	global_load_lds_dwordx4 v[222:223], off
	s_add_i32 m0, s16, 0x2000
	v_lshl_add_u64 v[226:227], s[60:61], 0, v[134:135]
	global_load_lds_dwordx4 v[224:225], off
	s_mov_b32 m0, s72
	v_lshl_add_u64 v[228:229], s[60:61], 0, v[130:131]
	global_load_lds_dwordx4 v[226:227], off
	s_mov_b32 m0, s73
	s_nop 0
	global_load_lds_dwordx4 v[228:229], off
	s_waitcnt vmcnt(8)
	s_waitcnt lgkmcnt(0)
	s_barrier
	s_setprio 1
	s_waitcnt lgkmcnt(0)
	v_mfma_f32_16x16x32_bf16 v[60:63], v[146:149], v[186:189], 0
	v_mfma_f32_16x16x32_bf16 v[56:59], v[162:165], v[186:189], 0
	v_mfma_f32_16x16x32_bf16 v[44:47], v[146:149], v[194:197], 0
	v_mfma_f32_16x16x32_bf16 v[40:43], v[162:165], v[194:197], 0
	v_mfma_f32_16x16x32_bf16 v[28:31], v[146:149], v[206:209], 0
	v_mfma_f32_16x16x32_bf16 v[24:27], v[162:165], v[206:209], 0
	v_mfma_f32_16x16x32_bf16 v[12:15], v[146:149], v[214:217], 0
	v_mfma_f32_16x16x32_bf16 v[8:11], v[162:165], v[214:217], 0
	v_mfma_f32_16x16x32_bf16 v[60:63], v[158:161], v[190:193], v[60:63]
	v_mfma_f32_16x16x32_bf16 v[56:59], v[166:169], v[190:193], v[56:59]
	v_mfma_f32_16x16x32_bf16 v[44:47], v[158:161], v[202:205], v[44:47]
	v_mfma_f32_16x16x32_bf16 v[40:43], v[166:169], v[202:205], v[40:43]
	v_mfma_f32_16x16x32_bf16 v[28:31], v[158:161], v[210:213], v[28:31]
	v_mfma_f32_16x16x32_bf16 v[24:27], v[166:169], v[210:213], v[24:27]
	v_mfma_f32_16x16x32_bf16 v[12:15], v[158:161], v[218:221], v[12:15]
	v_mfma_f32_16x16x32_bf16 v[8:11], v[166:169], v[218:221], v[8:11]
	s_setprio 0
	s_setprio 1
	v_mfma_f32_16x16x32_bf16 v[52:55], v[170:173], v[186:189], 0
	v_mfma_f32_16x16x32_bf16 v[48:51], v[178:181], v[186:189], 0
	v_mfma_f32_16x16x32_bf16 v[36:39], v[170:173], v[194:197], 0
	v_mfma_f32_16x16x32_bf16 v[32:35], v[178:181], v[194:197], 0
	v_mfma_f32_16x16x32_bf16 v[20:23], v[170:173], v[206:209], 0
	v_mfma_f32_16x16x32_bf16 v[16:19], v[178:181], v[206:209], 0
	v_mfma_f32_16x16x32_bf16 v[4:7], v[170:173], v[214:217], 0
	v_mfma_f32_16x16x32_bf16 v[0:3], v[178:181], v[214:217], 0
	v_mfma_f32_16x16x32_bf16 v[52:55], v[174:177], v[190:193], v[52:55]
	v_mfma_f32_16x16x32_bf16 v[48:51], v[182:185], v[190:193], v[48:51]
	v_mfma_f32_16x16x32_bf16 v[36:39], v[174:177], v[202:205], v[36:39]
	v_mfma_f32_16x16x32_bf16 v[32:35], v[182:185], v[202:205], v[32:35]
	v_mfma_f32_16x16x32_bf16 v[20:23], v[174:177], v[210:213], v[20:23]
	v_mfma_f32_16x16x32_bf16 v[16:19], v[182:185], v[210:213], v[16:19]
	v_mfma_f32_16x16x32_bf16 v[4:7], v[174:177], v[218:221], v[4:7]
	v_mfma_f32_16x16x32_bf16 v[0:3], v[182:185], v[218:221], v[0:3]
	s_setprio 0
	s_barrier
; #define PG8_STAGE(bufoff, gbase, voff) do { _Pragma("unroll") for (int _i = 0; _i < 2; ++_i) \
;         __builtin_amdgcn_global_load_lds((const unsigned*)((const char*)(gbase) + (voff)[_i]), (PG8_LAS unsigned*)(lds + (bufoff) + ldsw + _i * 8192), 16, 0, 0); } while (0)
; #define PG8_LDA(dst, b, h) do { _Pragma("unroll") for (int m = 0; m < 4; ++m) _Pragma("unroll") for (int k = 0; k < 2; ++k) dst[m][k] = *(const PG8_LAS bf16x8*)(lds + PG8_SA(b, h) + aoff + m * 2048 + k * 1024); } while (0)
; #define PG8_LDB(dst, b, h) do { _Pragma("unroll") for (int n = 0; n < 2; ++n) _Pragma("unroll") for (int k = 0; k < 2; ++k) dst[n][k] = *(const PG8_LAS bf16x8*)(lds + PG8_SB(b, h) + boff + n * 2048 + k * 1024); } while (0)
; #define PG8_MMA(ai, bj, At, Bt) do { __builtin_amdgcn_s_setprio(1); _Pragma("unroll") for (int m = 0; m < 4; ++m) _Pragma("unroll") for (int n = 0; n < 2; ++n) _Pragma("unroll") for (int k = 0; k < 2; ++k) \
;         acc[ai][bj][m][n] = __builtin_amdgcn_mfma_f32_16x16x32_bf16(Bt[n][k], At[m][k], acc[ai][bj][m][n], 0, 0, 0); __builtin_amdgcn_s_setprio(0); } while (0)
; #define PG8_WAIT_V(n) asm volatile("s_waitcnt vmcnt(" #n ")" ::: "memory")
; #define PG8_WAIT_L(n) asm volatile("s_waitcnt lgkmcnt(" #n ")" ::: "memory")
; #define PG8_BAR __builtin_amdgcn_s_barrier()
; #define PG8_SCHED __builtin_amdgcn_sched_barrier(0)
; template <class Epi, class Sched, bool ALIGN_EPI = false, bool SP2 = false>
; __device__ __forceinline__ void gemm_phase(PG8_LAS unsigned char* lds, const Gemm g, const Sched& S, const Epi& E) {
;     ...
;             PG8_LDB(B0, 1, 0); PG8_LDB(B1, 1, 1); PG8_SCHED; PG8_LDA(At, 1, 0); PG8_STAGE(PG8_SA(0, 1), a2 + hstep, voffA);
;             PG8_WAIT_V(8); PG8_WAIT_L(0); PG8_BAR; PG8_MMA(0, 0, At, B0); PG8_MMA(0, 1, At, B1); PG8_BAR; PG8_SCHED;
	s_add_i32 s16, 0, 0x18000
	s_add_i32 s17, 0, 0x1c000
	v_add_u32_e32 v166, s16, v153
	v_add_u32_e32 v182, s17, v153
	ds_read_b128 v[146:149], v166
	ds_read_b128 v[158:161], v166 offset:1024
	ds_read_b128 v[162:165], v166 offset:2048
	ds_read_b128 v[166:169], v166 offset:3072
	ds_read_b128 v[170:173], v182
	ds_read_b128 v[174:177], v182 offset:1024
	ds_read_b128 v[178:181], v182 offset:2048
	ds_read_b128 v[182:185], v182 offset:3072
	s_add_u32 s60, s60, s8
	s_addc_u32 s61, s61, s9
	s_mov_b32 m0, s74
	v_lshl_add_u64 v[230:231], s[60:61], 0, v[134:135]
	ds_read_b128 v[186:189], v156 offset:32768
	ds_read_b128 v[190:193], v156 offset:33792
	ds_read_b128 v[194:197], v156 offset:34816
	ds_read_b128 v[202:205], v156 offset:35840
	ds_read_b128 v[206:209], v156 offset:36864
	ds_read_b128 v[210:213], v156 offset:37888
	ds_read_b128 v[214:217], v156 offset:38912
	ds_read_b128 v[218:221], v156 offset:39936
	global_load_lds_dwordx4 v[230:231], off
	v_lshl_add_u64 v[230:231], s[60:61], 0, v[130:131]
	s_mov_b32 m0, s75
	s_nop 0
	global_load_lds_dwordx4 v[230:231], off
	s_waitcnt vmcnt(8)
	s_waitcnt lgkmcnt(0)
	s_barrier
	s_setprio 1
	s_waitcnt lgkmcnt(0)
	v_mfma_f32_16x16x32_bf16 v[120:123], v[146:149], v[186:189], v[120:123]
	v_mfma_f32_16x16x32_bf16 v[124:127], v[162:165], v[186:189], v[124:127]
	v_mfma_f32_16x16x32_bf16 v[108:111], v[146:149], v[194:197], v[108:111]
	v_mfma_f32_16x16x32_bf16 v[104:107], v[162:165], v[194:197], v[104:107]
	v_mfma_f32_16x16x32_bf16 v[92:95], v[146:149], v[206:209], v[92:95]
	v_mfma_f32_16x16x32_bf16 v[88:91], v[162:165], v[206:209], v[88:91]
	v_mfma_f32_16x16x32_bf16 v[76:79], v[146:149], v[214:217], v[76:79]
	v_mfma_f32_16x16x32_bf16 v[72:75], v[162:165], v[214:217], v[72:75]
	v_mfma_f32_16x16x32_bf16 v[120:123], v[158:161], v[190:193], v[120:123]
	v_mfma_f32_16x16x32_bf16 v[124:127], v[166:169], v[190:193], v[124:127]
	v_mfma_f32_16x16x32_bf16 v[108:111], v[158:161], v[202:205], v[108:111]
	v_mfma_f32_16x16x32_bf16 v[104:107], v[166:169], v[202:205], v[104:107]
	v_mfma_f32_16x16x32_bf16 v[92:95], v[158:161], v[210:213], v[92:95]
	v_mfma_f32_16x16x32_bf16 v[88:91], v[166:169], v[210:213], v[88:91]
	v_mfma_f32_16x16x32_bf16 v[76:79], v[158:161], v[218:221], v[76:79]
	v_mfma_f32_16x16x32_bf16 v[72:75], v[166:169], v[218:221], v[72:75]
	s_setprio 0
	s_setprio 1
	v_mfma_f32_16x16x32_bf16 v[116:119], v[170:173], v[186:189], v[116:119]
	v_mfma_f32_16x16x32_bf16 v[112:115], v[178:181], v[186:189], v[112:115]
	v_mfma_f32_16x16x32_bf16 v[100:103], v[170:173], v[194:197], v[100:103]
	v_mfma_f32_16x16x32_bf16 v[96:99], v[178:181], v[194:197], v[96:99]
	v_mfma_f32_16x16x32_bf16 v[84:87], v[170:173], v[206:209], v[84:87]
	v_mfma_f32_16x16x32_bf16 v[80:83], v[178:181], v[206:209], v[80:83]
	v_mfma_f32_16x16x32_bf16 v[68:71], v[170:173], v[214:217], v[68:71]
	v_mfma_f32_16x16x32_bf16 v[64:67], v[178:181], v[214:217], v[64:67]
	v_mfma_f32_16x16x32_bf16 v[116:119], v[174:177], v[190:193], v[116:119]
	v_mfma_f32_16x16x32_bf16 v[112:115], v[182:185], v[190:193], v[112:115]
	v_mfma_f32_16x16x32_bf16 v[100:103], v[174:177], v[202:205], v[100:103]
	v_mfma_f32_16x16x32_bf16 v[96:99], v[182:185], v[202:205], v[96:99]
	v_mfma_f32_16x16x32_bf16 v[84:87], v[174:177], v[210:213], v[84:87]
	v_mfma_f32_16x16x32_bf16 v[80:83], v[182:185], v[210:213], v[80:83]
	v_mfma_f32_16x16x32_bf16 v[68:71], v[174:177], v[218:221], v[68:71]
	v_mfma_f32_16x16x32_bf16 v[64:67], v[182:185], v[218:221], v[64:67]
	s_setprio 0
	s_barrier
; #define PG8_STAGE(bufoff, gbase, voff) do { _Pragma("unroll") for (int _i = 0; _i < 2; ++_i) \
;         __builtin_amdgcn_global_load_lds((const unsigned*)((const char*)(gbase) + (voff)[_i]), (PG8_LAS unsigned*)(lds + (bufoff) + ldsw + _i * 8192), 16, 0, 0); } while (0)
; #define PG8_LDA(dst, b, h) do { _Pragma("unroll") for (int m = 0; m < 4; ++m) _Pragma("unroll") for (int k = 0; k < 2; ++k) dst[m][k] = *(const PG8_LAS bf16x8*)(lds + PG8_SA(b, h) + aoff + m * 2048 + k * 1024); } while (0)
; #define PG8_MMA(ai, bj, At, Bt) do { __builtin_amdgcn_s_setprio(1); _Pragma("unroll") for (int m = 0; m < 4; ++m) _Pragma("unroll") for (int n = 0; n < 2; ++n) _Pragma("unroll") for (int k = 0; k < 2; ++k) \
;         acc[ai][bj][m][n] = __builtin_amdgcn_mfma_f32_16x16x32_bf16(Bt[n][k], At[m][k], acc[ai][bj][m][n], 0, 0, 0); __builtin_amdgcn_s_setprio(0); } while (0)
; #define PG8_WAIT_V(n) asm volatile("s_waitcnt vmcnt(" #n ")" ::: "memory")
; #define PG8_WAIT_L(n) asm volatile("s_waitcnt lgkmcnt(" #n ")" ::: "memory")
; #define PG8_BAR __builtin_amdgcn_s_barrier()
; #define PG8_SCHED __builtin_amdgcn_sched_barrier(0)
; template <class Epi, class Sched, bool ALIGN_EPI = false, bool SP2 = false>
; __device__ __forceinline__ void gemm_phase(PG8_LAS unsigned char* lds, const Gemm g, const Sched& S, const Epi& E) {
;     ...
;             PG8_LDA(At, 1, 1); PG8_STAGE(PG8_SB(1, 0), b3, voffB); PG8_STAGE(PG8_SB(1, 1), b3 + hstep, voffB); PG8_STAGE(PG8_SA(1, 0), a3, voffA);
;             PG8_WAIT_V(8); PG8_WAIT_L(0); PG8_BAR; PG8_MMA(1, 0, At, B0); PG8_MMA(1, 1, At, B1); PG8_BAR; PG8_SCHED;
	s_add_i32 s16, s16, s49
	v_lshl_add_u64 v[150:151], v[150:151], 0, s[14:15]
	s_mov_b32 m0, s16
	ds_read_b128 v[186:189], v156 offset:49152
	ds_read_b128 v[190:193], v156 offset:50176
	ds_read_b128 v[194:197], v156 offset:51200
	ds_read_b128 v[202:205], v156 offset:52224
	ds_read_b128 v[206:209], v156 offset:53248
	ds_read_b128 v[210:213], v156 offset:54272
	ds_read_b128 v[214:217], v156 offset:55296
	ds_read_b128 v[218:221], v156 offset:56320
	global_load_lds_dwordx4 v[150:151], off
	v_lshl_add_u64 v[150:151], v[198:199], 0, s[14:15]
	s_add_i32 m0, s16, 0x2000
	s_add_i32 s16, s17, s49
	global_load_lds_dwordx4 v[150:151], off
	v_lshl_add_u64 v[150:151], v[222:223], 0, s[14:15]
	s_mov_b32 m0, s16
	s_nop 0
	global_load_lds_dwordx4 v[150:151], off
	v_lshl_add_u64 v[150:151], v[224:225], 0, s[14:15]
	s_add_i32 m0, s16, 0x2000
	s_nop 0
	global_load_lds_dwordx4 v[150:151], off
	v_lshl_add_u64 v[150:151], v[226:227], 0, s[14:15]
	s_mov_b32 m0, s77
	s_nop 0
	global_load_lds_dwordx4 v[150:151], off
	v_lshl_add_u64 v[150:151], v[228:229], 0, s[14:15]
	s_mov_b32 m0, s78
	s_nop 0
	global_load_lds_dwordx4 v[150:151], off
	s_waitcnt vmcnt(8)
	s_waitcnt lgkmcnt(0)
	s_barrier
	s_setprio 1
	s_waitcnt lgkmcnt(0)
	v_mfma_f32_16x16x32_bf16 v[60:63], v[146:149], v[186:189], v[60:63]
	v_mfma_f32_16x16x32_bf16 v[56:59], v[162:165], v[186:189], v[56:59]
	v_mfma_f32_16x16x32_bf16 v[44:47], v[146:149], v[194:197], v[44:47]
	v_mfma_f32_16x16x32_bf16 v[40:43], v[162:165], v[194:197], v[40:43]
	v_mfma_f32_16x16x32_bf16 v[28:31], v[146:149], v[206:209], v[28:31]
	v_mfma_f32_16x16x32_bf16 v[24:27], v[162:165], v[206:209], v[24:27]
	v_mfma_f32_16x16x32_bf16 v[12:15], v[146:149], v[214:217], v[12:15]
	v_mfma_f32_16x16x32_bf16 v[8:11], v[162:165], v[214:217], v[8:11]
	v_mfma_f32_16x16x32_bf16 v[60:63], v[158:161], v[190:193], v[60:63]
	v_mfma_f32_16x16x32_bf16 v[56:59], v[166:169], v[190:193], v[56:59]
	v_mfma_f32_16x16x32_bf16 v[44:47], v[158:161], v[202:205], v[44:47]
	v_mfma_f32_16x16x32_bf16 v[40:43], v[166:169], v[202:205], v[40:43]
	v_mfma_f32_16x16x32_bf16 v[28:31], v[158:161], v[210:213], v[28:31]
	v_mfma_f32_16x16x32_bf16 v[24:27], v[166:169], v[210:213], v[24:27]
	v_mfma_f32_16x16x32_bf16 v[12:15], v[158:161], v[218:221], v[12:15]
	v_mfma_f32_16x16x32_bf16 v[8:11], v[166:169], v[218:221], v[8:11]
	s_setprio 0
	s_setprio 1
	v_mfma_f32_16x16x32_bf16 v[52:55], v[170:173], v[186:189], v[52:55]
	v_mfma_f32_16x16x32_bf16 v[48:51], v[178:181], v[186:189], v[48:51]
	v_mfma_f32_16x16x32_bf16 v[36:39], v[170:173], v[194:197], v[36:39]
	v_mfma_f32_16x16x32_bf16 v[32:35], v[178:181], v[194:197], v[32:35]
	v_mfma_f32_16x16x32_bf16 v[20:23], v[170:173], v[206:209], v[20:23]
	v_mfma_f32_16x16x32_bf16 v[16:19], v[178:181], v[206:209], v[16:19]
	v_mfma_f32_16x16x32_bf16 v[4:7], v[170:173], v[214:217], v[4:7]
	v_mfma_f32_16x16x32_bf16 v[0:3], v[178:181], v[214:217], v[0:3]
	v_mfma_f32_16x16x32_bf16 v[52:55], v[174:177], v[190:193], v[52:55]
	v_mfma_f32_16x16x32_bf16 v[48:51], v[182:185], v[190:193], v[48:51]
	v_mfma_f32_16x16x32_bf16 v[36:39], v[174:177], v[202:205], v[36:39]
	v_mfma_f32_16x16x32_bf16 v[32:35], v[182:185], v[202:205], v[32:35]
	v_mfma_f32_16x16x32_bf16 v[20:23], v[174:177], v[210:213], v[20:23]
	v_mfma_f32_16x16x32_bf16 v[16:19], v[182:185], v[210:213], v[16:19]
	v_mfma_f32_16x16x32_bf16 v[4:7], v[174:177], v[218:221], v[4:7]
	v_mfma_f32_16x16x32_bf16 v[0:3], v[182:185], v[218:221], v[0:3]
	s_setprio 0
	s_barrier
	s_add_u32 s0, s0, 0x100
	s_addc_u32 s1, s1, 0
	s_add_u32 s62, s62, 0x100
	s_addc_u32 s63, s63, 0
	s_cmp_ge_i32 s97, s79
	s_mov_b32 s60, s97
	s_cbranch_scc1 .LBB0_461

; #define PG8_STAGE(bufoff, gbase, voff) do { _Pragma("unroll") for (int _i = 0; _i < 2; ++_i) \
;         __builtin_amdgcn_global_load_lds((const unsigned*)((const char*)(gbase) + (voff)[_i]), (PG8_LAS unsigned*)(lds + (bufoff) + ldsw + _i * 8192), 16, 0, 0); } while (0)
; #define PG8_LDA(dst, b, h) do { _Pragma("unroll") for (int m = 0; m < 4; ++m) _Pragma("unroll") for (int k = 0; k < 2; ++k) dst[m][k] = *(const PG8_LAS bf16x8*)(lds + PG8_SA(b, h) + aoff + m * 2048 + k * 1024); } while (0)
; #define PG8_LDB(dst, b, h) do { _Pragma("unroll") for (int n = 0; n < 2; ++n) _Pragma("unroll") for (int k = 0; k < 2; ++k) dst[n][k] = *(const PG8_LAS bf16x8*)(lds + PG8_SB(b, h) + boff + n * 2048 + k * 1024); } while (0)
; #define PG8_MMA(ai, bj, At, Bt) do { __builtin_amdgcn_s_setprio(1); _Pragma("unroll") for (int m = 0; m < 4; ++m) _Pragma("unroll") for (int n = 0; n < 2; ++n) _Pragma("unroll") for (int k = 0; k < 2; ++k) \
;         acc[ai][bj][m][n] = __builtin_amdgcn_mfma_f32_16x16x32_bf16(Bt[n][k], At[m][k], acc[ai][bj][m][n], 0, 0, 0); __builtin_amdgcn_s_setprio(0); } while (0)
; #define PG8_WAIT_V(n) asm volatile("s_waitcnt vmcnt(" #n ")" ::: "memory")
; #define PG8_BAR __builtin_amdgcn_s_barrier()
; template <class Epi, class Sched, bool ALIGN_EPI = false, bool SP2 = false>
; __device__ __forceinline__ void gemm_phase(PG8_LAS unsigned char* lds, const Gemm g, const Sched& S, const Epi& E) {
;     ...
;         for (int t = 0; t < nt; t += 2) {
;             const bool last = (t == nt - 2);
;             const char* a1 = cA + (size_t)(t + 1) * kstep;
;             const char* a2 = last ? nA : cA + (size_t)(t + 2) * kstep; const char* b2 = last ? nB : cB + (size_t)(t + 2) * kstep;
;             const char* a3 = a2 + kstep; const char* b3 = b2 + kstep;
;             if (last && has_next) S.a_ready(nxt);
;             if constexpr (SP2) {
;             PG8_LDB(B0, 0, 0); PG8_LDB(B1, 0, 1); PG8_SCHED; PG8_LDA(At, 0, 0); PG8_STAGE(PG8_SA(1, 1), a1 + hstep, voffA);
;             PG8_WAIT_V(8); PG8_WAIT_L(0); PG8_BAR; PG8_MMA(0, 0, At, B0); PG8_MMA(0, 1, At, B1); PG8_BAR; PG8_SCHED;
;     ...
; #pragma unroll
;         for (int a = 0; a < 2; ++a)
; #pragma unroll
;             for (int b = 0; b < 2; ++b)
; #pragma unroll
;                 for (int m = 0; m < 4; ++m)
; #pragma unroll
;                     for (int n = 0; n < 2; ++n) acc[a][b][m][n] = (f32x4){0.f, 0.f, 0.f, 0.f};
.LBB0_533:
	s_andn2_b64 vcc, exec, s[44:45]
	s_cbranch_vccz .Lcz_go_535
	v_mov_b32_e32 v123, 0
	v_mov_b32_e32 v122, v123
	v_mov_b32_e32 v121, v123
	v_mov_b32_e32 v120, v123
	v_mov_b32_e32 v127, v123
	v_mov_b32_e32 v126, v123
	v_mov_b32_e32 v125, v123
	v_mov_b32_e32 v124, v123
	v_mov_b32_e32 v111, v123
	v_mov_b32_e32 v110, v123
	v_mov_b32_e32 v109, v123
	v_mov_b32_e32 v108, v123
	v_mov_b32_e32 v107, v123
	v_mov_b32_e32 v106, v123
	v_mov_b32_e32 v105, v123
	v_mov_b32_e32 v104, v123
	v_mov_b32_e32 v95, v123
	v_mov_b32_e32 v94, v123
	v_mov_b32_e32 v93, v123
	v_mov_b32_e32 v92, v123
	v_mov_b32_e32 v91, v123
	v_mov_b32_e32 v90, v123
	v_mov_b32_e32 v89, v123
	v_mov_b32_e32 v88, v123
	v_mov_b32_e32 v79, v123
	v_mov_b32_e32 v78, v123
	v_mov_b32_e32 v77, v123
	v_mov_b32_e32 v76, v123
	v_mov_b32_e32 v75, v123
	v_mov_b32_e32 v74, v123
	v_mov_b32_e32 v73, v123
	v_mov_b32_e32 v72, v123
	v_mov_b32_e32 v119, v123
	v_mov_b32_e32 v118, v123
	v_mov_b32_e32 v117, v123
	v_mov_b32_e32 v116, v123
	v_mov_b32_e32 v115, v123
	v_mov_b32_e32 v114, v123
	v_mov_b32_e32 v113, v123
	v_mov_b32_e32 v112, v123
	v_mov_b32_e32 v103, v123
	v_mov_b32_e32 v102, v123
	v_mov_b32_e32 v101, v123
	v_mov_b32_e32 v100, v123
	v_mov_b32_e32 v99, v123
	v_mov_b32_e32 v98, v123
	v_mov_b32_e32 v97, v123
	v_mov_b32_e32 v96, v123
	v_mov_b32_e32 v87, v123
	v_mov_b32_e32 v86, v123
	v_mov_b32_e32 v85, v123
	v_mov_b32_e32 v84, v123
	v_mov_b32_e32 v83, v123
	v_mov_b32_e32 v82, v123
	v_mov_b32_e32 v81, v123
	v_mov_b32_e32 v80, v123
	v_mov_b32_e32 v71, v123
	v_mov_b32_e32 v70, v123
	v_mov_b32_e32 v69, v123
	v_mov_b32_e32 v68, v123
	v_mov_b32_e32 v67, v123
	v_mov_b32_e32 v66, v123
	v_mov_b32_e32 v65, v123
	v_mov_b32_e32 v64, v123
	v_mov_b32_e32 v63, v123
	v_mov_b32_e32 v62, v123
	v_mov_b32_e32 v61, v123
	v_mov_b32_e32 v60, v123
	v_mov_b32_e32 v59, v123
	v_mov_b32_e32 v58, v123
	v_mov_b32_e32 v57, v123
	v_mov_b32_e32 v56, v123
	v_mov_b32_e32 v47, v123
	v_mov_b32_e32 v46, v123
	v_mov_b32_e32 v45, v123
	v_mov_b32_e32 v44, v123
	v_mov_b32_e32 v43, v123
	v_mov_b32_e32 v42, v123
	v_mov_b32_e32 v41, v123
	v_mov_b32_e32 v40, v123
	v_mov_b32_e32 v31, v123
	v_mov_b32_e32 v30, v123
	v_mov_b32_e32 v29, v123
	v_mov_b32_e32 v28, v123
	v_mov_b32_e32 v27, v123
	v_mov_b32_e32 v26, v123
	v_mov_b32_e32 v25, v123
	v_mov_b32_e32 v24, v123
	v_mov_b32_e32 v15, v123
	v_mov_b32_e32 v14, v123
	v_mov_b32_e32 v13, v123
	v_mov_b32_e32 v12, v123
	v_mov_b32_e32 v11, v123
	v_mov_b32_e32 v10, v123
	v_mov_b32_e32 v9, v123
	v_mov_b32_e32 v8, v123
	v_mov_b32_e32 v55, v123
	v_mov_b32_e32 v54, v123
	v_mov_b32_e32 v53, v123
	v_mov_b32_e32 v52, v123
	v_mov_b32_e32 v51, v123
	v_mov_b32_e32 v50, v123
	v_mov_b32_e32 v49, v123
	v_mov_b32_e32 v48, v123
	v_mov_b32_e32 v39, v123
	v_mov_b32_e32 v38, v123
	v_mov_b32_e32 v37, v123
	v_mov_b32_e32 v36, v123
	v_mov_b32_e32 v35, v123
	v_mov_b32_e32 v34, v123
	v_mov_b32_e32 v33, v123
	v_mov_b32_e32 v32, v123
	v_mov_b32_e32 v23, v123
	v_mov_b32_e32 v22, v123
	v_mov_b32_e32 v21, v123
	v_mov_b32_e32 v20, v123
	v_mov_b32_e32 v19, v123
	v_mov_b32_e32 v18, v123
	v_mov_b32_e32 v17, v123
	v_mov_b32_e32 v16, v123
	v_mov_b32_e32 v7, v123
	v_mov_b32_e32 v6, v123
	v_mov_b32_e32 v5, v123
	v_mov_b32_e32 v4, v123
	v_mov_b32_e32 v3, v123
	v_mov_b32_e32 v2, v123
	v_mov_b32_e32 v1, v123
	v_mov_b32_e32 v0, v123
	s_branch .LBB0_536
.Lcz_go_535:
	s_add_u32 s58, s58, 0x80
	s_addc_u32 s59, s59, 0
	s_add_u32 s95, s60, 0x100
	s_addc_u32 s96, s61, 0
	s_mov_b32 s60, 0
	ds_read_b128 v[128:131], v166
	ds_read_b128 v[156:159], v166 offset:1024
	ds_read_b128 v[160:163], v166 offset:2048
	ds_read_b128 v[170:173], v166 offset:3072
	ds_read_b128 v[174:177], v167
	ds_read_b128 v[178:181], v167 offset:1024
	ds_read_b128 v[182:185], v167 offset:2048
	ds_read_b128 v[186:189], v167 offset:3072
	s_add_i32 s97, s60, 2
	s_add_u32 s16, s58, 0x80
	s_addc_u32 s17, s59, 0
	s_cmp_eq_u32 s76, s60
	s_cselect_b32 s60, s0, s16
	s_cselect_b32 s61, s1, s17
	s_cselect_b32 vcc_hi, s57, s96
	s_cselect_b32 vcc_lo, s56, s95
	v_lshl_add_u64 v[198:199], s[58:59], 0, v[148:149]
	s_add_i32 m0, s62, 0xc000
	ds_read_b128 v[190:193], v168
	ds_read_b128 v[194:197], v168 offset:1024
	ds_read_b128 v[202:205], v168 offset:2048
	ds_read_b128 v[206:209], v168 offset:3072
	ds_read_b128 v[210:213], v168 offset:4096
	ds_read_b128 v[214:217], v168 offset:5120
	ds_read_b128 v[218:221], v168 offset:6144
	ds_read_b128 v[222:225], v168 offset:7168
	global_load_lds_dwordx4 v[198:199], off
	v_lshl_add_u64 v[198:199], s[58:59], 0, v[150:151]
	s_add_i32 m0, s62, 0xe000
	s_nop 0
	global_load_lds_dwordx4 v[198:199], off
	s_waitcnt vmcnt(8)
	s_waitcnt lgkmcnt(0)
	s_barrier
; #define PG8_STAGE(bufoff, gbase, voff) do { _Pragma("unroll") for (int _i = 0; _i < 2; ++_i) \
;         __builtin_amdgcn_global_load_lds((const unsigned*)((const char*)(gbase) + (voff)[_i]), (PG8_LAS unsigned*)(lds + (bufoff) + ldsw + _i * 8192), 16, 0, 0); } while (0)
; #define PG8_LDA(dst, b, h) do { _Pragma("unroll") for (int m = 0; m < 4; ++m) _Pragma("unroll") for (int k = 0; k < 2; ++k) dst[m][k] = *(const PG8_LAS bf16x8*)(lds + PG8_SA(b, h) + aoff + m * 2048 + k * 1024); } while (0)
; #define PG8_MMA(ai, bj, At, Bt) do { __builtin_amdgcn_s_setprio(1); _Pragma("unroll") for (int m = 0; m < 4; ++m) _Pragma("unroll") for (int n = 0; n < 2; ++n) _Pragma("unroll") for (int k = 0; k < 2; ++k) \
;         acc[ai][bj][m][n] = __builtin_amdgcn_mfma_f32_16x16x32_bf16(Bt[n][k], At[m][k], acc[ai][bj][m][n], 0, 0, 0); __builtin_amdgcn_s_setprio(0); } while (0)
; #define PG8_WAIT_V(n) asm volatile("s_waitcnt vmcnt(" #n ")" ::: "memory")
; #define PG8_WAIT_L(n) asm volatile("s_waitcnt lgkmcnt(" #n ")" ::: "memory")
; #define PG8_BAR __builtin_amdgcn_s_barrier()
; #define PG8_SCHED __builtin_amdgcn_sched_barrier(0)
; template <class Epi, class Sched, bool ALIGN_EPI = false, bool SP2 = false>
; __device__ __forceinline__ void gemm_phase(PG8_LAS unsigned char* lds, const Gemm g, const Sched& S, const Epi& E) {
;     ...
;             PG8_WAIT_V(8); PG8_WAIT_L(0); PG8_BAR; PG8_MMA(0, 0, At, B0); PG8_MMA(0, 1, At, B1); PG8_BAR; PG8_SCHED;
;             PG8_LDA(At, 0, 1); PG8_STAGE(PG8_SB(0, 0), b2, voffB); PG8_STAGE(PG8_SB(0, 1), b2 + hstep, voffB); PG8_STAGE(PG8_SA(0, 0), a2, voffA);
;             PG8_WAIT_V(8); PG8_WAIT_L(0); PG8_BAR; PG8_MMA(1, 0, At, B0); PG8_MMA(1, 1, At, B1); PG8_BAR; PG8_SCHED;
	s_setprio 1
	s_waitcnt lgkmcnt(0)
	v_mfma_f32_16x16x32_bf16 v[120:123], v[128:131], v[190:193], 0
	v_mfma_f32_16x16x32_bf16 v[124:127], v[160:163], v[190:193], 0
	v_mfma_f32_16x16x32_bf16 v[108:111], v[128:131], v[202:205], 0
	v_mfma_f32_16x16x32_bf16 v[104:107], v[160:163], v[202:205], 0
	v_mfma_f32_16x16x32_bf16 v[92:95], v[128:131], v[210:213], 0
	v_mfma_f32_16x16x32_bf16 v[88:91], v[160:163], v[210:213], 0
	v_mfma_f32_16x16x32_bf16 v[76:79], v[128:131], v[218:221], 0
	v_mfma_f32_16x16x32_bf16 v[72:75], v[160:163], v[218:221], 0
	v_mfma_f32_16x16x32_bf16 v[120:123], v[156:159], v[194:197], v[120:123]
	v_mfma_f32_16x16x32_bf16 v[124:127], v[170:173], v[194:197], v[124:127]
	v_mfma_f32_16x16x32_bf16 v[108:111], v[156:159], v[206:209], v[108:111]
	v_mfma_f32_16x16x32_bf16 v[104:107], v[170:173], v[206:209], v[104:107]
	v_mfma_f32_16x16x32_bf16 v[92:95], v[156:159], v[214:217], v[92:95]
	v_mfma_f32_16x16x32_bf16 v[88:91], v[170:173], v[214:217], v[88:91]
	v_mfma_f32_16x16x32_bf16 v[76:79], v[156:159], v[222:225], v[76:79]
	v_mfma_f32_16x16x32_bf16 v[72:75], v[170:173], v[222:225], v[72:75]
	s_setprio 0
	s_setprio 1
	v_mfma_f32_16x16x32_bf16 v[116:119], v[174:177], v[190:193], 0
	v_mfma_f32_16x16x32_bf16 v[112:115], v[182:185], v[190:193], 0
	v_mfma_f32_16x16x32_bf16 v[100:103], v[174:177], v[202:205], 0
	v_mfma_f32_16x16x32_bf16 v[96:99], v[182:185], v[202:205], 0
	v_mfma_f32_16x16x32_bf16 v[84:87], v[174:177], v[210:213], 0
	v_mfma_f32_16x16x32_bf16 v[80:83], v[182:185], v[210:213], 0
	v_mfma_f32_16x16x32_bf16 v[68:71], v[174:177], v[218:221], 0
	v_mfma_f32_16x16x32_bf16 v[64:67], v[182:185], v[218:221], 0
	v_mfma_f32_16x16x32_bf16 v[116:119], v[178:181], v[194:197], v[116:119]
	v_mfma_f32_16x16x32_bf16 v[112:115], v[186:189], v[194:197], v[112:115]
	v_mfma_f32_16x16x32_bf16 v[100:103], v[178:181], v[206:209], v[100:103]
	v_mfma_f32_16x16x32_bf16 v[96:99], v[186:189], v[206:209], v[96:99]
	v_mfma_f32_16x16x32_bf16 v[84:87], v[178:181], v[214:217], v[84:87]
	v_mfma_f32_16x16x32_bf16 v[80:83], v[186:189], v[214:217], v[80:83]
	v_mfma_f32_16x16x32_bf16 v[68:71], v[178:181], v[222:225], v[68:71]
	v_mfma_f32_16x16x32_bf16 v[64:67], v[186:189], v[222:225], v[64:67]
	s_setprio 0
	s_barrier
	s_add_i32 s16, s79, s49
	v_lshl_add_u64 v[198:199], vcc, 0, v[134:135]
	s_mov_b32 m0, s16
	ds_read_b128 v[190:193], v168 offset:16384
	ds_read_b128 v[194:197], v168 offset:17408
	ds_read_b128 v[202:205], v168 offset:18432
	ds_read_b128 v[206:209], v168 offset:19456
	ds_read_b128 v[210:213], v168 offset:20480
	ds_read_b128 v[214:217], v168 offset:21504
	ds_read_b128 v[218:221], v168 offset:22528
	ds_read_b128 v[222:225], v168 offset:23552
	global_load_lds_dwordx4 v[198:199], off
	s_add_i32 m0, s16, 0x2000
	v_lshl_add_u64 v[226:227], vcc, 0, v[138:139]
	s_add_u32 vcc_lo, vcc_lo, s8
	s_addc_u32 vcc_hi, vcc_hi, s9
	s_add_i32 s16, s80, s49
	global_load_lds_dwordx4 v[226:227], off
	v_lshl_add_u64 v[228:229], vcc, 0, v[134:135]
	s_mov_b32 m0, s16
	v_lshl_add_u64 v[230:231], vcc, 0, v[138:139]
	global_load_lds_dwordx4 v[228:229], off
	s_add_i32 m0, s16, 0x2000
	v_lshl_add_u64 v[232:233], s[60:61], 0, v[132:133]
	global_load_lds_dwordx4 v[230:231], off
	s_mov_b32 m0, s62
	v_lshl_add_u64 v[236:237], s[60:61], 0, v[136:137]
	global_load_lds_dwordx4 v[232:233], off
	s_mov_b32 m0, s63
	s_nop 0
	global_load_lds_dwordx4 v[236:237], off
	s_waitcnt vmcnt(8)
	s_waitcnt lgkmcnt(0)
	s_barrier
	s_setprio 1
	s_waitcnt lgkmcnt(0)
	v_mfma_f32_16x16x32_bf16 v[60:63], v[128:131], v[190:193], 0
	v_mfma_f32_16x16x32_bf16 v[56:59], v[160:163], v[190:193], 0
	v_mfma_f32_16x16x32_bf16 v[44:47], v[128:131], v[202:205], 0
	v_mfma_f32_16x16x32_bf16 v[40:43], v[160:163], v[202:205], 0
	v_mfma_f32_16x16x32_bf16 v[28:31], v[128:131], v[210:213], 0
	v_mfma_f32_16x16x32_bf16 v[24:27], v[160:163], v[210:213], 0
	v_mfma_f32_16x16x32_bf16 v[12:15], v[128:131], v[218:221], 0
	v_mfma_f32_16x16x32_bf16 v[8:11], v[160:163], v[218:221], 0
	v_mfma_f32_16x16x32_bf16 v[60:63], v[156:159], v[194:197], v[60:63]
	v_mfma_f32_16x16x32_bf16 v[56:59], v[170:173], v[194:197], v[56:59]
	v_mfma_f32_16x16x32_bf16 v[44:47], v[156:159], v[206:209], v[44:47]
	v_mfma_f32_16x16x32_bf16 v[40:43], v[170:173], v[206:209], v[40:43]
	v_mfma_f32_16x16x32_bf16 v[28:31], v[156:159], v[214:217], v[28:31]
	v_mfma_f32_16x16x32_bf16 v[24:27], v[170:173], v[214:217], v[24:27]
	v_mfma_f32_16x16x32_bf16 v[12:15], v[156:159], v[222:225], v[12:15]
	v_mfma_f32_16x16x32_bf16 v[8:11], v[170:173], v[222:225], v[8:11]
	s_setprio 0
	s_setprio 1
	v_mfma_f32_16x16x32_bf16 v[52:55], v[174:177], v[190:193], 0
	v_mfma_f32_16x16x32_bf16 v[48:51], v[182:185], v[190:193], 0
	v_mfma_f32_16x16x32_bf16 v[36:39], v[174:177], v[202:205], 0
	v_mfma_f32_16x16x32_bf16 v[32:35], v[182:185], v[202:205], 0
	v_mfma_f32_16x16x32_bf16 v[20:23], v[174:177], v[210:213], 0
	v_mfma_f32_16x16x32_bf16 v[16:19], v[182:185], v[210:213], 0
	v_mfma_f32_16x16x32_bf16 v[4:7], v[174:177], v[218:221], 0
	v_mfma_f32_16x16x32_bf16 v[0:3], v[182:185], v[218:221], 0
	v_mfma_f32_16x16x32_bf16 v[52:55], v[178:181], v[194:197], v[52:55]
	v_mfma_f32_16x16x32_bf16 v[48:51], v[186:189], v[194:197], v[48:51]
	v_mfma_f32_16x16x32_bf16 v[36:39], v[178:181], v[206:209], v[36:39]
	v_mfma_f32_16x16x32_bf16 v[32:35], v[186:189], v[206:209], v[32:35]
	v_mfma_f32_16x16x32_bf16 v[20:23], v[178:181], v[214:217], v[20:23]
	v_mfma_f32_16x16x32_bf16 v[16:19], v[186:189], v[214:217], v[16:19]
	v_mfma_f32_16x16x32_bf16 v[4:7], v[178:181], v[222:225], v[4:7]
	v_mfma_f32_16x16x32_bf16 v[0:3], v[186:189], v[222:225], v[0:3]
	s_setprio 0
	s_barrier
; #define PG8_STAGE(bufoff, gbase, voff) do { _Pragma("unroll") for (int _i = 0; _i < 2; ++_i) \
;         __builtin_amdgcn_global_load_lds((const unsigned*)((const char*)(gbase) + (voff)[_i]), (PG8_LAS unsigned*)(lds + (bufoff) + ldsw + _i * 8192), 16, 0, 0); } while (0)
; #define PG8_LDA(dst, b, h) do { _Pragma("unroll") for (int m = 0; m < 4; ++m) _Pragma("unroll") for (int k = 0; k < 2; ++k) dst[m][k] = *(const PG8_LAS bf16x8*)(lds + PG8_SA(b, h) + aoff + m * 2048 + k * 1024); } while (0)
; #define PG8_LDB(dst, b, h) do { _Pragma("unroll") for (int n = 0; n < 2; ++n) _Pragma("unroll") for (int k = 0; k < 2; ++k) dst[n][k] = *(const PG8_LAS bf16x8*)(lds + PG8_SB(b, h) + boff + n * 2048 + k * 1024); } while (0)
; #define PG8_MMA(ai, bj, At, Bt) do { __builtin_amdgcn_s_setprio(1); _Pragma("unroll") for (int m = 0; m < 4; ++m) _Pragma("unroll") for (int n = 0; n < 2; ++n) _Pragma("unroll") for (int k = 0; k < 2; ++k) \
;         acc[ai][bj][m][n] = __builtin_amdgcn_mfma_f32_16x16x32_bf16(Bt[n][k], At[m][k], acc[ai][bj][m][n], 0, 0, 0); __builtin_amdgcn_s_setprio(0); } while (0)
; #define PG8_WAIT_V(n) asm volatile("s_waitcnt vmcnt(" #n ")" ::: "memory")
; #define PG8_WAIT_L(n) asm volatile("s_waitcnt lgkmcnt(" #n ")" ::: "memory")
; #define PG8_BAR __builtin_amdgcn_s_barrier()
; #define PG8_SCHED __builtin_amdgcn_sched_barrier(0)
; template <class Epi, class Sched, bool ALIGN_EPI = false, bool SP2 = false>
; __device__ __forceinline__ void gemm_phase(PG8_LAS unsigned char* lds, const Gemm g, const Sched& S, const Epi& E) {
;     ...
;             PG8_LDB(B0, 1, 0); PG8_LDB(B1, 1, 1); PG8_SCHED; PG8_LDA(At, 1, 0); PG8_STAGE(PG8_SA(0, 1), a2 + hstep, voffA);
;             PG8_WAIT_V(8); PG8_WAIT_L(0); PG8_BAR; PG8_MMA(0, 0, At, B0); PG8_MMA(0, 1, At, B1); PG8_BAR; PG8_SCHED;
	s_add_i32 s16, 0, 0x18000
	v_add_u32_e32 v140, s16, v165
	s_add_i32 s17, 0, 0x1c000
	ds_read_b128 v[128:131], v140
	ds_read_b128 v[156:159], v140 offset:1024
	ds_read_b128 v[160:163], v140 offset:2048
	ds_read_b128 v[170:173], v140 offset:3072
	v_add_u32_e32 v140, s17, v165
	ds_read_b128 v[174:177], v140
	ds_read_b128 v[178:181], v140 offset:1024
	ds_read_b128 v[182:185], v140 offset:2048
	ds_read_b128 v[186:189], v140 offset:3072
	s_add_u32 s60, s60, s8
	s_addc_u32 s61, s61, s9
	s_mov_b32 m0, s70
	v_lshl_add_u64 v[238:239], s[60:61], 0, v[132:133]
	ds_read_b128 v[190:193], v168 offset:32768
	ds_read_b128 v[194:197], v168 offset:33792
	ds_read_b128 v[202:205], v168 offset:34816
	ds_read_b128 v[206:209], v168 offset:35840
	ds_read_b128 v[210:213], v168 offset:36864
	ds_read_b128 v[214:217], v168 offset:37888
	ds_read_b128 v[218:221], v168 offset:38912
	ds_read_b128 v[222:225], v168 offset:39936
	global_load_lds_dwordx4 v[238:239], off
	v_lshl_add_u64 v[238:239], s[60:61], 0, v[136:137]
	s_mov_b32 m0, s71
	s_nop 0
	global_load_lds_dwordx4 v[238:239], off
	s_waitcnt vmcnt(8)
	s_waitcnt lgkmcnt(0)
	s_barrier
	s_setprio 1
	s_waitcnt lgkmcnt(0)
	v_mfma_f32_16x16x32_bf16 v[120:123], v[128:131], v[190:193], v[120:123]
	v_mfma_f32_16x16x32_bf16 v[124:127], v[160:163], v[190:193], v[124:127]
	v_mfma_f32_16x16x32_bf16 v[108:111], v[128:131], v[202:205], v[108:111]
	v_mfma_f32_16x16x32_bf16 v[104:107], v[160:163], v[202:205], v[104:107]
	v_mfma_f32_16x16x32_bf16 v[92:95], v[128:131], v[210:213], v[92:95]
	v_mfma_f32_16x16x32_bf16 v[88:91], v[160:163], v[210:213], v[88:91]
	v_mfma_f32_16x16x32_bf16 v[76:79], v[128:131], v[218:221], v[76:79]
	v_mfma_f32_16x16x32_bf16 v[72:75], v[160:163], v[218:221], v[72:75]
	v_mfma_f32_16x16x32_bf16 v[120:123], v[156:159], v[194:197], v[120:123]
	v_mfma_f32_16x16x32_bf16 v[124:127], v[170:173], v[194:197], v[124:127]
	v_mfma_f32_16x16x32_bf16 v[108:111], v[156:159], v[206:209], v[108:111]
	v_mfma_f32_16x16x32_bf16 v[104:107], v[170:173], v[206:209], v[104:107]
	v_mfma_f32_16x16x32_bf16 v[92:95], v[156:159], v[214:217], v[92:95]
	v_mfma_f32_16x16x32_bf16 v[88:91], v[170:173], v[214:217], v[88:91]
	v_mfma_f32_16x16x32_bf16 v[76:79], v[156:159], v[222:225], v[76:79]
	v_mfma_f32_16x16x32_bf16 v[72:75], v[170:173], v[222:225], v[72:75]
	s_setprio 0
	s_setprio 1
	v_mfma_f32_16x16x32_bf16 v[116:119], v[174:177], v[190:193], v[116:119]
	v_mfma_f32_16x16x32_bf16 v[112:115], v[182:185], v[190:193], v[112:115]
	v_mfma_f32_16x16x32_bf16 v[100:103], v[174:177], v[202:205], v[100:103]
	v_mfma_f32_16x16x32_bf16 v[96:99], v[182:185], v[202:205], v[96:99]
	v_mfma_f32_16x16x32_bf16 v[84:87], v[174:177], v[210:213], v[84:87]
	v_mfma_f32_16x16x32_bf16 v[80:83], v[182:185], v[210:213], v[80:83]
	v_mfma_f32_16x16x32_bf16 v[68:71], v[174:177], v[218:221], v[68:71]
	v_mfma_f32_16x16x32_bf16 v[64:67], v[182:185], v[218:221], v[64:67]
	v_mfma_f32_16x16x32_bf16 v[116:119], v[178:181], v[194:197], v[116:119]
	v_mfma_f32_16x16x32_bf16 v[112:115], v[186:189], v[194:197], v[112:115]
	v_mfma_f32_16x16x32_bf16 v[100:103], v[178:181], v[206:209], v[100:103]
	v_mfma_f32_16x16x32_bf16 v[96:99], v[186:189], v[206:209], v[96:99]
	v_mfma_f32_16x16x32_bf16 v[84:87], v[178:181], v[214:217], v[84:87]
	v_mfma_f32_16x16x32_bf16 v[80:83], v[186:189], v[214:217], v[80:83]
	v_mfma_f32_16x16x32_bf16 v[68:71], v[178:181], v[222:225], v[68:71]
	v_mfma_f32_16x16x32_bf16 v[64:67], v[186:189], v[222:225], v[64:67]
	s_setprio 0
	s_barrier
; #define PG8_STAGE(bufoff, gbase, voff) do { _Pragma("unroll") for (int _i = 0; _i < 2; ++_i) \
;         __builtin_amdgcn_global_load_lds((const unsigned*)((const char*)(gbase) + (voff)[_i]), (PG8_LAS unsigned*)(lds + (bufoff) + ldsw + _i * 8192), 16, 0, 0); } while (0)
; #define PG8_LDA(dst, b, h) do { _Pragma("unroll") for (int m = 0; m < 4; ++m) _Pragma("unroll") for (int k = 0; k < 2; ++k) dst[m][k] = *(const PG8_LAS bf16x8*)(lds + PG8_SA(b, h) + aoff + m * 2048 + k * 1024); } while (0)
; #define PG8_MMA(ai, bj, At, Bt) do { __builtin_amdgcn_s_setprio(1); _Pragma("unroll") for (int m = 0; m < 4; ++m) _Pragma("unroll") for (int n = 0; n < 2; ++n) _Pragma("unroll") for (int k = 0; k < 2; ++k) \
;         acc[ai][bj][m][n] = __builtin_amdgcn_mfma_f32_16x16x32_bf16(Bt[n][k], At[m][k], acc[ai][bj][m][n], 0, 0, 0); __builtin_amdgcn_s_setprio(0); } while (0)
; #define PG8_WAIT_V(n) asm volatile("s_waitcnt vmcnt(" #n ")" ::: "memory")
; #define PG8_WAIT_L(n) asm volatile("s_waitcnt lgkmcnt(" #n ")" ::: "memory")
; #define PG8_BAR __builtin_amdgcn_s_barrier()
; #define PG8_SCHED __builtin_amdgcn_sched_barrier(0)
; template <class Epi, class Sched, bool ALIGN_EPI = false, bool SP2 = false>
; __device__ __forceinline__ void gemm_phase(PG8_LAS unsigned char* lds, const Gemm g, const Sched& S, const Epi& E) {
;     ...
;         for (int t = 0; t < nt; t += 2) {
;             const bool last = (t == nt - 2);
;             const char* a1 = cA + (size_t)(t + 1) * kstep;
;             const char* a2 = last ? nA : cA + (size_t)(t + 2) * kstep; const char* b2 = last ? nB : cB + (size_t)(t + 2) * kstep;
;             const char* a3 = a2 + kstep; const char* b3 = b2 + kstep;
;     ...
;             PG8_LDA(At, 1, 1); PG8_STAGE(PG8_SB(1, 0), b3, voffB); PG8_STAGE(PG8_SB(1, 1), b3 + hstep, voffB); PG8_STAGE(PG8_SA(1, 0), a3, voffA);
;             PG8_WAIT_V(8); PG8_WAIT_L(0); PG8_BAR; PG8_MMA(1, 0, At, B0); PG8_MMA(1, 1, At, B1); PG8_BAR; PG8_SCHED;
	s_add_i32 s16, s16, s49
	v_lshl_add_u64 v[198:199], v[198:199], 0, s[42:43]
	s_mov_b32 m0, s16
	ds_read_b128 v[190:193], v168 offset:49152
	ds_read_b128 v[194:197], v168 offset:50176
	ds_read_b128 v[202:205], v168 offset:51200
	ds_read_b128 v[206:209], v168 offset:52224
	ds_read_b128 v[210:213], v168 offset:53248
	ds_read_b128 v[214:217], v168 offset:54272
	ds_read_b128 v[218:221], v168 offset:55296
	ds_read_b128 v[222:225], v168 offset:56320
	global_load_lds_dwordx4 v[198:199], off
	v_lshl_add_u64 v[198:199], v[226:227], 0, s[42:43]
	s_add_i32 m0, s16, 0x2000
	s_add_i32 s16, s17, s49
	global_load_lds_dwordx4 v[198:199], off
	v_lshl_add_u64 v[198:199], v[228:229], 0, s[42:43]
	s_mov_b32 m0, s16
	s_nop 0
	global_load_lds_dwordx4 v[198:199], off
	v_lshl_add_u64 v[198:199], v[230:231], 0, s[42:43]
	s_add_i32 m0, s16, 0x2000
	s_nop 0
	global_load_lds_dwordx4 v[198:199], off
	v_lshl_add_u64 v[198:199], v[232:233], 0, s[42:43]
	s_mov_b32 m0, s72
	s_nop 0
	global_load_lds_dwordx4 v[198:199], off
	v_lshl_add_u64 v[198:199], v[236:237], 0, s[42:43]
	s_mov_b32 m0, s73
	s_nop 0
	global_load_lds_dwordx4 v[198:199], off
	s_waitcnt vmcnt(8)
	s_waitcnt lgkmcnt(0)
	s_barrier
	s_setprio 1
	s_waitcnt lgkmcnt(0)
	v_mfma_f32_16x16x32_bf16 v[60:63], v[128:131], v[190:193], v[60:63]
	v_mfma_f32_16x16x32_bf16 v[56:59], v[160:163], v[190:193], v[56:59]
	v_mfma_f32_16x16x32_bf16 v[44:47], v[128:131], v[202:205], v[44:47]
	v_mfma_f32_16x16x32_bf16 v[40:43], v[160:163], v[202:205], v[40:43]
	v_mfma_f32_16x16x32_bf16 v[28:31], v[128:131], v[210:213], v[28:31]
	v_mfma_f32_16x16x32_bf16 v[24:27], v[160:163], v[210:213], v[24:27]
	v_mfma_f32_16x16x32_bf16 v[12:15], v[128:131], v[218:221], v[12:15]
	v_mfma_f32_16x16x32_bf16 v[8:11], v[160:163], v[218:221], v[8:11]
	v_mfma_f32_16x16x32_bf16 v[60:63], v[156:159], v[194:197], v[60:63]
	v_mfma_f32_16x16x32_bf16 v[56:59], v[170:173], v[194:197], v[56:59]
	v_mfma_f32_16x16x32_bf16 v[44:47], v[156:159], v[206:209], v[44:47]
	v_mfma_f32_16x16x32_bf16 v[40:43], v[170:173], v[206:209], v[40:43]
	v_mfma_f32_16x16x32_bf16 v[28:31], v[156:159], v[214:217], v[28:31]
	v_mfma_f32_16x16x32_bf16 v[24:27], v[170:173], v[214:217], v[24:27]
	v_mfma_f32_16x16x32_bf16 v[12:15], v[156:159], v[222:225], v[12:15]
	v_mfma_f32_16x16x32_bf16 v[8:11], v[170:173], v[222:225], v[8:11]
	s_setprio 0
	s_setprio 1
	v_mfma_f32_16x16x32_bf16 v[52:55], v[174:177], v[190:193], v[52:55]
	v_mfma_f32_16x16x32_bf16 v[48:51], v[182:185], v[190:193], v[48:51]
	v_mfma_f32_16x16x32_bf16 v[36:39], v[174:177], v[202:205], v[36:39]
	v_mfma_f32_16x16x32_bf16 v[32:35], v[182:185], v[202:205], v[32:35]
	v_mfma_f32_16x16x32_bf16 v[20:23], v[174:177], v[210:213], v[20:23]
	v_mfma_f32_16x16x32_bf16 v[16:19], v[182:185], v[210:213], v[16:19]
	v_mfma_f32_16x16x32_bf16 v[4:7], v[174:177], v[218:221], v[4:7]
	v_mfma_f32_16x16x32_bf16 v[0:3], v[182:185], v[218:221], v[0:3]
	v_mfma_f32_16x16x32_bf16 v[52:55], v[178:181], v[194:197], v[52:55]
	v_mfma_f32_16x16x32_bf16 v[48:51], v[186:189], v[194:197], v[48:51]
	v_mfma_f32_16x16x32_bf16 v[36:39], v[178:181], v[206:209], v[36:39]
	v_mfma_f32_16x16x32_bf16 v[32:35], v[186:189], v[206:209], v[32:35]
	v_mfma_f32_16x16x32_bf16 v[20:23], v[178:181], v[214:217], v[20:23]
	v_mfma_f32_16x16x32_bf16 v[16:19], v[186:189], v[214:217], v[16:19]
	v_mfma_f32_16x16x32_bf16 v[4:7], v[178:181], v[222:225], v[4:7]
	v_mfma_f32_16x16x32_bf16 v[0:3], v[186:189], v[222:225], v[0:3]
	s_setprio 0
	s_barrier
	s_add_u32 s58, s58, 0x100
	s_addc_u32 s59, s59, 0
	s_add_u32 s95, s95, 0x100
	s_addc_u32 s96, s96, 0
	s_cmp_ge_i32 s97, s74
	s_mov_b32 s60, s97
	s_cbranch_scc1 .LBB0_536

; #define PG8_STAGE(bufoff, gbase, voff) do { _Pragma("unroll") for (int _i = 0; _i < 2; ++_i) \
;         __builtin_amdgcn_global_load_lds((const unsigned*)((const char*)(gbase) + (voff)[_i]), (PG8_LAS unsigned*)(lds + (bufoff) + ldsw + _i * 8192), 16, 0, 0); } while (0)
; #define PG8_LDA(dst, b, h) do { _Pragma("unroll") for (int m = 0; m < 4; ++m) _Pragma("unroll") for (int k = 0; k < 2; ++k) dst[m][k] = *(const PG8_LAS bf16x8*)(lds + PG8_SA(b, h) + aoff + m * 2048 + k * 1024); } while (0)
; #define PG8_LDB(dst, b, h) do { _Pragma("unroll") for (int n = 0; n < 2; ++n) _Pragma("unroll") for (int k = 0; k < 2; ++k) dst[n][k] = *(const PG8_LAS bf16x8*)(lds + PG8_SB(b, h) + boff + n * 2048 + k * 1024); } while (0)
; #define PG8_MMA(ai, bj, At, Bt) do { __builtin_amdgcn_s_setprio(1); _Pragma("unroll") for (int m = 0; m < 4; ++m) _Pragma("unroll") for (int n = 0; n < 2; ++n) _Pragma("unroll") for (int k = 0; k < 2; ++k) \
;         acc[ai][bj][m][n] = __builtin_amdgcn_mfma_f32_16x16x32_bf16(Bt[n][k], At[m][k], acc[ai][bj][m][n], 0, 0, 0); __builtin_amdgcn_s_setprio(0); } while (0)
; #define PG8_WAIT_V(n) asm volatile("s_waitcnt vmcnt(" #n ")" ::: "memory")
; #define PG8_BAR __builtin_amdgcn_s_barrier()
; template <class Epi, class Sched, bool ALIGN_EPI = false, bool SP2 = false>
; __device__ __forceinline__ void gemm_phase(PG8_LAS unsigned char* lds, const Gemm g, const Sched& S, const Epi& E) {
;     ...
;         for (int t = 0; t < nt; t += 2) {
;             const bool last = (t == nt - 2);
;             const char* a1 = cA + (size_t)(t + 1) * kstep;
;             const char* a2 = last ? nA : cA + (size_t)(t + 2) * kstep; const char* b2 = last ? nB : cB + (size_t)(t + 2) * kstep;
;             const char* a3 = a2 + kstep; const char* b3 = b2 + kstep;
;             if (last && has_next) S.a_ready(nxt);
;             if constexpr (SP2) {
;             PG8_LDB(B0, 0, 0); PG8_LDB(B1, 0, 1); PG8_SCHED; PG8_LDA(At, 0, 0); PG8_STAGE(PG8_SA(1, 1), a1 + hstep, voffA);
;             PG8_WAIT_V(8); PG8_WAIT_L(0); PG8_BAR; PG8_MMA(0, 0, At, B0); PG8_MMA(0, 1, At, B1); PG8_BAR; PG8_SCHED;
;     ...
; #pragma unroll
;         for (int a = 0; a < 2; ++a)
; #pragma unroll
;             for (int b = 0; b < 2; ++b)
; #pragma unroll
;                 for (int m = 0; m < 4; ++m)
; #pragma unroll
;                     for (int n = 0; n < 2; ++n) acc[a][b][m][n] = (f32x4){0.f, 0.f, 0.f, 0.f};
.LBB0_726:
	s_andn2_b64 vcc, exec, s[46:47]
	s_cbranch_vccz .Lcz_go_728
	v_mov_b32_e32 v123, 0
	v_mov_b32_e32 v122, v123
	v_mov_b32_e32 v121, v123
	v_mov_b32_e32 v120, v123
	v_mov_b32_e32 v127, v123
	v_mov_b32_e32 v126, v123
	v_mov_b32_e32 v125, v123
	v_mov_b32_e32 v124, v123
	v_mov_b32_e32 v111, v123
	v_mov_b32_e32 v110, v123
	v_mov_b32_e32 v109, v123
	v_mov_b32_e32 v108, v123
	v_mov_b32_e32 v107, v123
	v_mov_b32_e32 v106, v123
	v_mov_b32_e32 v105, v123
	v_mov_b32_e32 v104, v123
	v_mov_b32_e32 v95, v123
	v_mov_b32_e32 v94, v123
	v_mov_b32_e32 v93, v123
	v_mov_b32_e32 v92, v123
	v_mov_b32_e32 v91, v123
	v_mov_b32_e32 v90, v123
	v_mov_b32_e32 v89, v123
	v_mov_b32_e32 v88, v123
	v_mov_b32_e32 v79, v123
	v_mov_b32_e32 v78, v123
	v_mov_b32_e32 v77, v123
	v_mov_b32_e32 v76, v123
	v_mov_b32_e32 v75, v123
	v_mov_b32_e32 v74, v123
	v_mov_b32_e32 v73, v123
	v_mov_b32_e32 v72, v123
	v_mov_b32_e32 v119, v123
	v_mov_b32_e32 v118, v123
	v_mov_b32_e32 v117, v123
	v_mov_b32_e32 v116, v123
	v_mov_b32_e32 v115, v123
	v_mov_b32_e32 v114, v123
	v_mov_b32_e32 v113, v123
	v_mov_b32_e32 v112, v123
	v_mov_b32_e32 v103, v123
	v_mov_b32_e32 v102, v123
	v_mov_b32_e32 v101, v123
	v_mov_b32_e32 v100, v123
	v_mov_b32_e32 v99, v123
	v_mov_b32_e32 v98, v123
	v_mov_b32_e32 v97, v123
	v_mov_b32_e32 v96, v123
	v_mov_b32_e32 v87, v123
	v_mov_b32_e32 v86, v123
	v_mov_b32_e32 v85, v123
	v_mov_b32_e32 v84, v123
	v_mov_b32_e32 v83, v123
	v_mov_b32_e32 v82, v123
	v_mov_b32_e32 v81, v123
	v_mov_b32_e32 v80, v123
	v_mov_b32_e32 v71, v123
	v_mov_b32_e32 v70, v123
	v_mov_b32_e32 v69, v123
	v_mov_b32_e32 v68, v123
	v_mov_b32_e32 v67, v123
	v_mov_b32_e32 v66, v123
	v_mov_b32_e32 v65, v123
	v_mov_b32_e32 v64, v123
	v_mov_b32_e32 v63, v123
	v_mov_b32_e32 v62, v123
	v_mov_b32_e32 v61, v123
	v_mov_b32_e32 v60, v123
	v_mov_b32_e32 v59, v123
	v_mov_b32_e32 v58, v123
	v_mov_b32_e32 v57, v123
	v_mov_b32_e32 v56, v123
	v_mov_b32_e32 v47, v123
	v_mov_b32_e32 v46, v123
	v_mov_b32_e32 v45, v123
	v_mov_b32_e32 v44, v123
	v_mov_b32_e32 v43, v123
	v_mov_b32_e32 v42, v123
	v_mov_b32_e32 v41, v123
	v_mov_b32_e32 v40, v123
	v_mov_b32_e32 v31, v123
	v_mov_b32_e32 v30, v123
	v_mov_b32_e32 v29, v123
	v_mov_b32_e32 v28, v123
	v_mov_b32_e32 v27, v123
	v_mov_b32_e32 v26, v123
	v_mov_b32_e32 v25, v123
	v_mov_b32_e32 v24, v123
	v_mov_b32_e32 v15, v123
	v_mov_b32_e32 v14, v123
	v_mov_b32_e32 v13, v123
	v_mov_b32_e32 v12, v123
	v_mov_b32_e32 v11, v123
	v_mov_b32_e32 v10, v123
	v_mov_b32_e32 v9, v123
	v_mov_b32_e32 v8, v123
	v_mov_b32_e32 v55, v123
	v_mov_b32_e32 v54, v123
	v_mov_b32_e32 v53, v123
	v_mov_b32_e32 v52, v123
	v_mov_b32_e32 v51, v123
	v_mov_b32_e32 v50, v123
	v_mov_b32_e32 v49, v123
	v_mov_b32_e32 v48, v123
	v_mov_b32_e32 v39, v123
	v_mov_b32_e32 v38, v123
	v_mov_b32_e32 v37, v123
	v_mov_b32_e32 v36, v123
	v_mov_b32_e32 v35, v123
	v_mov_b32_e32 v34, v123
	v_mov_b32_e32 v33, v123
	v_mov_b32_e32 v32, v123
	v_mov_b32_e32 v23, v123
	v_mov_b32_e32 v22, v123
	v_mov_b32_e32 v21, v123
	v_mov_b32_e32 v20, v123
	v_mov_b32_e32 v19, v123
	v_mov_b32_e32 v18, v123
	v_mov_b32_e32 v17, v123
	v_mov_b32_e32 v16, v123
	v_mov_b32_e32 v7, v123
	v_mov_b32_e32 v6, v123
	v_mov_b32_e32 v5, v123
	v_mov_b32_e32 v4, v123
	v_mov_b32_e32 v3, v123
	v_mov_b32_e32 v2, v123
	v_mov_b32_e32 v1, v123
	v_mov_b32_e32 v0, v123
	s_branch .LBB0_729
.Lcz_go_728:
	s_add_u32 s6, s6, 0x80
	s_addc_u32 s7, s7, 0
	s_add_u32 s79, s52, 0x100
	s_addc_u32 s80, s53, 0
	s_mov_b32 s52, 0
	ds_read_b128 v[128:131], v169
	ds_read_b128 v[148:151], v169 offset:1024
	ds_read_b128 v[152:155], v169 offset:2048
	ds_read_b128 v[156:159], v169 offset:3072
	ds_read_b128 v[160:163], v170
	ds_read_b128 v[172:175], v170 offset:1024
	ds_read_b128 v[176:179], v170 offset:2048
	ds_read_b128 v[180:183], v170 offset:3072
	s_add_i32 s81, s52, 2
	s_add_u32 s16, s6, 0x80
	s_addc_u32 s17, s7, 0
	s_cmp_eq_u32 s69, s52
	s_cselect_b32 s52, s0, s16
	s_cselect_b32 s53, s1, s17
	s_cselect_b32 s83, s51, s80
	s_cselect_b32 s82, s50, s79
	v_lshl_add_u64 v[164:165], s[6:7], 0, v[140:141]
	s_add_i32 m0, s56, 0xc000
	ds_read_b128 v[184:187], v171
	ds_read_b128 v[188:191], v171 offset:1024
	ds_read_b128 v[192:195], v171 offset:2048
	ds_read_b128 v[196:199], v171 offset:3072
	ds_read_b128 v[202:205], v171 offset:4096
	ds_read_b128 v[206:209], v171 offset:5120
	ds_read_b128 v[210:213], v171 offset:6144
	ds_read_b128 v[214:217], v171 offset:7168
	global_load_lds_dwordx4 v[164:165], off
	v_lshl_add_u64 v[164:165], s[6:7], 0, v[142:143]
	s_add_i32 m0, s56, 0xe000
	s_nop 0
	global_load_lds_dwordx4 v[164:165], off
	s_waitcnt vmcnt(8)
	s_waitcnt lgkmcnt(0)
	s_barrier
; #define PG8_STAGE(bufoff, gbase, voff) do { _Pragma("unroll") for (int _i = 0; _i < 2; ++_i) \
;         __builtin_amdgcn_global_load_lds((const unsigned*)((const char*)(gbase) + (voff)[_i]), (PG8_LAS unsigned*)(lds + (bufoff) + ldsw + _i * 8192), 16, 0, 0); } while (0)
; #define PG8_LDA(dst, b, h) do { _Pragma("unroll") for (int m = 0; m < 4; ++m) _Pragma("unroll") for (int k = 0; k < 2; ++k) dst[m][k] = *(const PG8_LAS bf16x8*)(lds + PG8_SA(b, h) + aoff + m * 2048 + k * 1024); } while (0)
; #define PG8_MMA(ai, bj, At, Bt) do { __builtin_amdgcn_s_setprio(1); _Pragma("unroll") for (int m = 0; m < 4; ++m) _Pragma("unroll") for (int n = 0; n < 2; ++n) _Pragma("unroll") for (int k = 0; k < 2; ++k) \
;         acc[ai][bj][m][n] = __builtin_amdgcn_mfma_f32_16x16x32_bf16(Bt[n][k], At[m][k], acc[ai][bj][m][n], 0, 0, 0); __builtin_amdgcn_s_setprio(0); } while (0)
; #define PG8_WAIT_V(n) asm volatile("s_waitcnt vmcnt(" #n ")" ::: "memory")
; #define PG8_WAIT_L(n) asm volatile("s_waitcnt lgkmcnt(" #n ")" ::: "memory")
; #define PG8_BAR __builtin_amdgcn_s_barrier()
; #define PG8_SCHED __builtin_amdgcn_sched_barrier(0)
; template <class Epi, class Sched, bool ALIGN_EPI = false, bool SP2 = false>
; __device__ __forceinline__ void gemm_phase(PG8_LAS unsigned char* lds, const Gemm g, const Sched& S, const Epi& E) {
;     ...
;             PG8_WAIT_V(8); PG8_WAIT_L(0); PG8_BAR; PG8_MMA(0, 0, At, B0); PG8_MMA(0, 1, At, B1); PG8_BAR; PG8_SCHED;
;             PG8_LDA(At, 0, 1); PG8_STAGE(PG8_SB(0, 0), b2, voffB); PG8_STAGE(PG8_SB(0, 1), b2 + hstep, voffB); PG8_STAGE(PG8_SA(0, 0), a2, voffA);
;             PG8_WAIT_V(8); PG8_WAIT_L(0); PG8_BAR; PG8_MMA(1, 0, At, B0); PG8_MMA(1, 1, At, B1); PG8_BAR; PG8_SCHED;
	s_setprio 1
	s_waitcnt lgkmcnt(0)
	v_mfma_f32_16x16x32_bf16 v[120:123], v[128:131], v[184:187], 0
	v_mfma_f32_16x16x32_bf16 v[124:127], v[152:155], v[184:187], 0
	v_mfma_f32_16x16x32_bf16 v[108:111], v[128:131], v[192:195], 0
	v_mfma_f32_16x16x32_bf16 v[104:107], v[152:155], v[192:195], 0
	v_mfma_f32_16x16x32_bf16 v[92:95], v[128:131], v[202:205], 0
	v_mfma_f32_16x16x32_bf16 v[88:91], v[152:155], v[202:205], 0
	v_mfma_f32_16x16x32_bf16 v[76:79], v[128:131], v[210:213], 0
	v_mfma_f32_16x16x32_bf16 v[72:75], v[152:155], v[210:213], 0
	v_mfma_f32_16x16x32_bf16 v[120:123], v[148:151], v[188:191], v[120:123]
	v_mfma_f32_16x16x32_bf16 v[124:127], v[156:159], v[188:191], v[124:127]
	v_mfma_f32_16x16x32_bf16 v[108:111], v[148:151], v[196:199], v[108:111]
	v_mfma_f32_16x16x32_bf16 v[104:107], v[156:159], v[196:199], v[104:107]
	v_mfma_f32_16x16x32_bf16 v[92:95], v[148:151], v[206:209], v[92:95]
	v_mfma_f32_16x16x32_bf16 v[88:91], v[156:159], v[206:209], v[88:91]
	v_mfma_f32_16x16x32_bf16 v[76:79], v[148:151], v[214:217], v[76:79]
	v_mfma_f32_16x16x32_bf16 v[72:75], v[156:159], v[214:217], v[72:75]
	s_setprio 0
	s_setprio 1
	v_mfma_f32_16x16x32_bf16 v[116:119], v[160:163], v[184:187], 0
	v_mfma_f32_16x16x32_bf16 v[112:115], v[176:179], v[184:187], 0
	v_mfma_f32_16x16x32_bf16 v[100:103], v[160:163], v[192:195], 0
	v_mfma_f32_16x16x32_bf16 v[96:99], v[176:179], v[192:195], 0
	v_mfma_f32_16x16x32_bf16 v[84:87], v[160:163], v[202:205], 0
	v_mfma_f32_16x16x32_bf16 v[80:83], v[176:179], v[202:205], 0
	v_mfma_f32_16x16x32_bf16 v[68:71], v[160:163], v[210:213], 0
	v_mfma_f32_16x16x32_bf16 v[64:67], v[176:179], v[210:213], 0
	v_mfma_f32_16x16x32_bf16 v[116:119], v[172:175], v[188:191], v[116:119]
	v_mfma_f32_16x16x32_bf16 v[112:115], v[180:183], v[188:191], v[112:115]
	v_mfma_f32_16x16x32_bf16 v[100:103], v[172:175], v[196:199], v[100:103]
	v_mfma_f32_16x16x32_bf16 v[96:99], v[180:183], v[196:199], v[96:99]
	v_mfma_f32_16x16x32_bf16 v[84:87], v[172:175], v[206:209], v[84:87]
	v_mfma_f32_16x16x32_bf16 v[80:83], v[180:183], v[206:209], v[80:83]
	v_mfma_f32_16x16x32_bf16 v[68:71], v[172:175], v[214:217], v[68:71]
	v_mfma_f32_16x16x32_bf16 v[64:67], v[180:183], v[214:217], v[64:67]
	s_setprio 0
	s_barrier
	s_add_i32 s16, s71, s55
	v_lshl_add_u64 v[164:165], s[82:83], 0, v[134:135]
	s_mov_b32 m0, s16
	ds_read_b128 v[184:187], v171 offset:16384
	ds_read_b128 v[188:191], v171 offset:17408
	ds_read_b128 v[192:195], v171 offset:18432
	ds_read_b128 v[196:199], v171 offset:19456
	ds_read_b128 v[202:205], v171 offset:20480
	ds_read_b128 v[206:209], v171 offset:21504
	ds_read_b128 v[210:213], v171 offset:22528
	ds_read_b128 v[214:217], v171 offset:23552
	global_load_lds_dwordx4 v[164:165], off
	s_add_i32 m0, s16, 0x2000
	v_lshl_add_u64 v[218:219], s[82:83], 0, v[138:139]
	s_add_u32 s82, s82, s10
	s_addc_u32 s83, s83, s11
	s_add_i32 s16, s72, s55
	global_load_lds_dwordx4 v[218:219], off
	v_lshl_add_u64 v[220:221], s[82:83], 0, v[134:135]
	s_mov_b32 m0, s16
	v_lshl_add_u64 v[222:223], s[82:83], 0, v[138:139]
	global_load_lds_dwordx4 v[220:221], off
	s_add_i32 m0, s16, 0x2000
	v_lshl_add_u64 v[224:225], s[52:53], 0, v[132:133]
	global_load_lds_dwordx4 v[222:223], off
	s_mov_b32 m0, s56
	v_lshl_add_u64 v[226:227], s[52:53], 0, v[136:137]
	global_load_lds_dwordx4 v[224:225], off
	s_mov_b32 m0, s57
	s_nop 0
	global_load_lds_dwordx4 v[226:227], off
	s_waitcnt vmcnt(8)
	s_waitcnt lgkmcnt(0)
	s_barrier
	s_setprio 1
	s_waitcnt lgkmcnt(0)
	v_mfma_f32_16x16x32_bf16 v[60:63], v[128:131], v[184:187], 0
	v_mfma_f32_16x16x32_bf16 v[56:59], v[152:155], v[184:187], 0
	v_mfma_f32_16x16x32_bf16 v[44:47], v[128:131], v[192:195], 0
	v_mfma_f32_16x16x32_bf16 v[40:43], v[152:155], v[192:195], 0
	v_mfma_f32_16x16x32_bf16 v[28:31], v[128:131], v[202:205], 0
	v_mfma_f32_16x16x32_bf16 v[24:27], v[152:155], v[202:205], 0
	v_mfma_f32_16x16x32_bf16 v[12:15], v[128:131], v[210:213], 0
	v_mfma_f32_16x16x32_bf16 v[8:11], v[152:155], v[210:213], 0
	v_mfma_f32_16x16x32_bf16 v[60:63], v[148:151], v[188:191], v[60:63]
	v_mfma_f32_16x16x32_bf16 v[56:59], v[156:159], v[188:191], v[56:59]
	v_mfma_f32_16x16x32_bf16 v[44:47], v[148:151], v[196:199], v[44:47]
	v_mfma_f32_16x16x32_bf16 v[40:43], v[156:159], v[196:199], v[40:43]
	v_mfma_f32_16x16x32_bf16 v[28:31], v[148:151], v[206:209], v[28:31]
	v_mfma_f32_16x16x32_bf16 v[24:27], v[156:159], v[206:209], v[24:27]
	v_mfma_f32_16x16x32_bf16 v[12:15], v[148:151], v[214:217], v[12:15]
	v_mfma_f32_16x16x32_bf16 v[8:11], v[156:159], v[214:217], v[8:11]
	s_setprio 0
	s_setprio 1
	v_mfma_f32_16x16x32_bf16 v[52:55], v[160:163], v[184:187], 0
	v_mfma_f32_16x16x32_bf16 v[48:51], v[176:179], v[184:187], 0
	v_mfma_f32_16x16x32_bf16 v[36:39], v[160:163], v[192:195], 0
	v_mfma_f32_16x16x32_bf16 v[32:35], v[176:179], v[192:195], 0
	v_mfma_f32_16x16x32_bf16 v[20:23], v[160:163], v[202:205], 0
	v_mfma_f32_16x16x32_bf16 v[16:19], v[176:179], v[202:205], 0
	v_mfma_f32_16x16x32_bf16 v[4:7], v[160:163], v[210:213], 0
	v_mfma_f32_16x16x32_bf16 v[0:3], v[176:179], v[210:213], 0
	v_mfma_f32_16x16x32_bf16 v[52:55], v[172:175], v[188:191], v[52:55]
	v_mfma_f32_16x16x32_bf16 v[48:51], v[180:183], v[188:191], v[48:51]
	v_mfma_f32_16x16x32_bf16 v[36:39], v[172:175], v[196:199], v[36:39]
	v_mfma_f32_16x16x32_bf16 v[32:35], v[180:183], v[196:199], v[32:35]
	v_mfma_f32_16x16x32_bf16 v[20:23], v[172:175], v[206:209], v[20:23]
	v_mfma_f32_16x16x32_bf16 v[16:19], v[180:183], v[206:209], v[16:19]
	v_mfma_f32_16x16x32_bf16 v[4:7], v[172:175], v[214:217], v[4:7]
	v_mfma_f32_16x16x32_bf16 v[0:3], v[180:183], v[214:217], v[0:3]
	s_setprio 0
	s_barrier
; #define PG8_STAGE(bufoff, gbase, voff) do { _Pragma("unroll") for (int _i = 0; _i < 2; ++_i) \
;         __builtin_amdgcn_global_load_lds((const unsigned*)((const char*)(gbase) + (voff)[_i]), (PG8_LAS unsigned*)(lds + (bufoff) + ldsw + _i * 8192), 16, 0, 0); } while (0)
; #define PG8_LDA(dst, b, h) do { _Pragma("unroll") for (int m = 0; m < 4; ++m) _Pragma("unroll") for (int k = 0; k < 2; ++k) dst[m][k] = *(const PG8_LAS bf16x8*)(lds + PG8_SA(b, h) + aoff + m * 2048 + k * 1024); } while (0)
; #define PG8_LDB(dst, b, h) do { _Pragma("unroll") for (int n = 0; n < 2; ++n) _Pragma("unroll") for (int k = 0; k < 2; ++k) dst[n][k] = *(const PG8_LAS bf16x8*)(lds + PG8_SB(b, h) + boff + n * 2048 + k * 1024); } while (0)
; #define PG8_MMA(ai, bj, At, Bt) do { __builtin_amdgcn_s_setprio(1); _Pragma("unroll") for (int m = 0; m < 4; ++m) _Pragma("unroll") for (int n = 0; n < 2; ++n) _Pragma("unroll") for (int k = 0; k < 2; ++k) \
;         acc[ai][bj][m][n] = __builtin_amdgcn_mfma_f32_16x16x32_bf16(Bt[n][k], At[m][k], acc[ai][bj][m][n], 0, 0, 0); __builtin_amdgcn_s_setprio(0); } while (0)
; #define PG8_WAIT_V(n) asm volatile("s_waitcnt vmcnt(" #n ")" ::: "memory")
; #define PG8_WAIT_L(n) asm volatile("s_waitcnt lgkmcnt(" #n ")" ::: "memory")
; #define PG8_BAR __builtin_amdgcn_s_barrier()
; #define PG8_SCHED __builtin_amdgcn_sched_barrier(0)
; template <class Epi, class Sched, bool ALIGN_EPI = false, bool SP2 = false>
; __device__ __forceinline__ void gemm_phase(PG8_LAS unsigned char* lds, const Gemm g, const Sched& S, const Epi& E) {
;     ...
;             PG8_LDB(B0, 1, 0); PG8_LDB(B1, 1, 1); PG8_SCHED; PG8_LDA(At, 1, 0); PG8_STAGE(PG8_SA(0, 1), a2 + hstep, voffA);
;             PG8_WAIT_V(8); PG8_WAIT_L(0); PG8_BAR; PG8_MMA(0, 0, At, B0); PG8_MMA(0, 1, At, B1); PG8_BAR; PG8_SCHED;
	s_add_i32 s16, 0, 0x18000
	s_add_i32 s17, 0, 0x1c000
	v_add_u32_e32 v156, s16, v167
	v_add_u32_e32 v180, s17, v167
	ds_read_b128 v[128:131], v156
	ds_read_b128 v[148:151], v156 offset:1024
	ds_read_b128 v[152:155], v156 offset:2048
	ds_read_b128 v[156:159], v156 offset:3072
	ds_read_b128 v[160:163], v180
	ds_read_b128 v[172:175], v180 offset:1024
	ds_read_b128 v[176:179], v180 offset:2048
	ds_read_b128 v[180:183], v180 offset:3072
	s_add_u32 s52, s52, s10
	s_addc_u32 s53, s53, s11
	s_mov_b32 m0, s58
	v_lshl_add_u64 v[228:229], s[52:53], 0, v[132:133]
	ds_read_b128 v[184:187], v171 offset:32768
	ds_read_b128 v[188:191], v171 offset:33792
	ds_read_b128 v[192:195], v171 offset:34816
	ds_read_b128 v[196:199], v171 offset:35840
	ds_read_b128 v[202:205], v171 offset:36864
	ds_read_b128 v[206:209], v171 offset:37888
	ds_read_b128 v[210:213], v171 offset:38912
	ds_read_b128 v[214:217], v171 offset:39936
	global_load_lds_dwordx4 v[228:229], off
	v_lshl_add_u64 v[228:229], s[52:53], 0, v[136:137]
	s_mov_b32 m0, s59
	s_nop 0
	global_load_lds_dwordx4 v[228:229], off
	s_waitcnt vmcnt(8)
	s_waitcnt lgkmcnt(0)
	s_barrier
	s_setprio 1
	s_waitcnt lgkmcnt(0)
	v_mfma_f32_16x16x32_bf16 v[120:123], v[128:131], v[184:187], v[120:123]
	v_mfma_f32_16x16x32_bf16 v[124:127], v[152:155], v[184:187], v[124:127]
	v_mfma_f32_16x16x32_bf16 v[108:111], v[128:131], v[192:195], v[108:111]
	v_mfma_f32_16x16x32_bf16 v[104:107], v[152:155], v[192:195], v[104:107]
	v_mfma_f32_16x16x32_bf16 v[92:95], v[128:131], v[202:205], v[92:95]
	v_mfma_f32_16x16x32_bf16 v[88:91], v[152:155], v[202:205], v[88:91]
	v_mfma_f32_16x16x32_bf16 v[76:79], v[128:131], v[210:213], v[76:79]
	v_mfma_f32_16x16x32_bf16 v[72:75], v[152:155], v[210:213], v[72:75]
	v_mfma_f32_16x16x32_bf16 v[120:123], v[148:151], v[188:191], v[120:123]
	v_mfma_f32_16x16x32_bf16 v[124:127], v[156:159], v[188:191], v[124:127]
	v_mfma_f32_16x16x32_bf16 v[108:111], v[148:151], v[196:199], v[108:111]
	v_mfma_f32_16x16x32_bf16 v[104:107], v[156:159], v[196:199], v[104:107]
	v_mfma_f32_16x16x32_bf16 v[92:95], v[148:151], v[206:209], v[92:95]
	v_mfma_f32_16x16x32_bf16 v[88:91], v[156:159], v[206:209], v[88:91]
	v_mfma_f32_16x16x32_bf16 v[76:79], v[148:151], v[214:217], v[76:79]
	v_mfma_f32_16x16x32_bf16 v[72:75], v[156:159], v[214:217], v[72:75]
	s_setprio 0
	s_setprio 1
	v_mfma_f32_16x16x32_bf16 v[116:119], v[160:163], v[184:187], v[116:119]
	v_mfma_f32_16x16x32_bf16 v[112:115], v[176:179], v[184:187], v[112:115]
	v_mfma_f32_16x16x32_bf16 v[100:103], v[160:163], v[192:195], v[100:103]
	v_mfma_f32_16x16x32_bf16 v[96:99], v[176:179], v[192:195], v[96:99]
	v_mfma_f32_16x16x32_bf16 v[84:87], v[160:163], v[202:205], v[84:87]
	v_mfma_f32_16x16x32_bf16 v[80:83], v[176:179], v[202:205], v[80:83]
	v_mfma_f32_16x16x32_bf16 v[68:71], v[160:163], v[210:213], v[68:71]
	v_mfma_f32_16x16x32_bf16 v[64:67], v[176:179], v[210:213], v[64:67]
	v_mfma_f32_16x16x32_bf16 v[116:119], v[172:175], v[188:191], v[116:119]
	v_mfma_f32_16x16x32_bf16 v[112:115], v[180:183], v[188:191], v[112:115]
	v_mfma_f32_16x16x32_bf16 v[100:103], v[172:175], v[196:199], v[100:103]
	v_mfma_f32_16x16x32_bf16 v[96:99], v[180:183], v[196:199], v[96:99]
	v_mfma_f32_16x16x32_bf16 v[84:87], v[172:175], v[206:209], v[84:87]
	v_mfma_f32_16x16x32_bf16 v[80:83], v[180:183], v[206:209], v[80:83]
	v_mfma_f32_16x16x32_bf16 v[68:71], v[172:175], v[214:217], v[68:71]
	v_mfma_f32_16x16x32_bf16 v[64:67], v[180:183], v[214:217], v[64:67]
	s_setprio 0
	s_barrier
; #define PG8_STAGE(bufoff, gbase, voff) do { _Pragma("unroll") for (int _i = 0; _i < 2; ++_i) \
;         __builtin_amdgcn_global_load_lds((const unsigned*)((const char*)(gbase) + (voff)[_i]), (PG8_LAS unsigned*)(lds + (bufoff) + ldsw + _i * 8192), 16, 0, 0); } while (0)
; #define PG8_LDA(dst, b, h) do { _Pragma("unroll") for (int m = 0; m < 4; ++m) _Pragma("unroll") for (int k = 0; k < 2; ++k) dst[m][k] = *(const PG8_LAS bf16x8*)(lds + PG8_SA(b, h) + aoff + m * 2048 + k * 1024); } while (0)
; #define PG8_MMA(ai, bj, At, Bt) do { __builtin_amdgcn_s_setprio(1); _Pragma("unroll") for (int m = 0; m < 4; ++m) _Pragma("unroll") for (int n = 0; n < 2; ++n) _Pragma("unroll") for (int k = 0; k < 2; ++k) \
;         acc[ai][bj][m][n] = __builtin_amdgcn_mfma_f32_16x16x32_bf16(Bt[n][k], At[m][k], acc[ai][bj][m][n], 0, 0, 0); __builtin_amdgcn_s_setprio(0); } while (0)
; #define PG8_WAIT_V(n) asm volatile("s_waitcnt vmcnt(" #n ")" ::: "memory")
; #define PG8_WAIT_L(n) asm volatile("s_waitcnt lgkmcnt(" #n ")" ::: "memory")
; #define PG8_BAR __builtin_amdgcn_s_barrier()
; #define PG8_SCHED __builtin_amdgcn_sched_barrier(0)
; template <class Epi, class Sched, bool ALIGN_EPI = false, bool SP2 = false>
; __device__ __forceinline__ void gemm_phase(PG8_LAS unsigned char* lds, const Gemm g, const Sched& S, const Epi& E) {
;     ...
;         for (int t = 0; t < nt; t += 2) {
;             const bool last = (t == nt - 2);
;     ...
;             PG8_LDA(At, 1, 1); PG8_STAGE(PG8_SB(1, 0), b3, voffB); PG8_STAGE(PG8_SB(1, 1), b3 + hstep, voffB); PG8_STAGE(PG8_SA(1, 0), a3, voffA);
;             PG8_WAIT_V(8); PG8_WAIT_L(0); PG8_BAR; PG8_MMA(1, 0, At, B0); PG8_MMA(1, 1, At, B1); PG8_BAR; PG8_SCHED;
	s_add_i32 s16, s16, s55
	v_lshl_add_u64 v[164:165], v[164:165], 0, s[44:45]
	s_mov_b32 m0, s16
	ds_read_b128 v[184:187], v171 offset:49152
	ds_read_b128 v[188:191], v171 offset:50176
	ds_read_b128 v[192:195], v171 offset:51200
	ds_read_b128 v[196:199], v171 offset:52224
	ds_read_b128 v[202:205], v171 offset:53248
	ds_read_b128 v[206:209], v171 offset:54272
	ds_read_b128 v[210:213], v171 offset:55296
	ds_read_b128 v[214:217], v171 offset:56320
	global_load_lds_dwordx4 v[164:165], off
	v_lshl_add_u64 v[164:165], v[218:219], 0, s[44:45]
	s_add_i32 m0, s16, 0x2000
	s_add_i32 s16, s17, s55
	global_load_lds_dwordx4 v[164:165], off
	v_lshl_add_u64 v[164:165], v[220:221], 0, s[44:45]
	s_mov_b32 m0, s16
	s_nop 0
	global_load_lds_dwordx4 v[164:165], off
	v_lshl_add_u64 v[164:165], v[222:223], 0, s[44:45]
	s_add_i32 m0, s16, 0x2000
	s_nop 0
	global_load_lds_dwordx4 v[164:165], off
	v_lshl_add_u64 v[164:165], v[224:225], 0, s[44:45]
	s_mov_b32 m0, s62
	s_nop 0
	global_load_lds_dwordx4 v[164:165], off
	v_lshl_add_u64 v[164:165], v[226:227], 0, s[44:45]
	s_mov_b32 m0, s63
	s_nop 0
	global_load_lds_dwordx4 v[164:165], off
	s_waitcnt vmcnt(8)
	s_waitcnt lgkmcnt(0)
	s_barrier
	s_setprio 1
	s_waitcnt lgkmcnt(0)
	v_mfma_f32_16x16x32_bf16 v[60:63], v[128:131], v[184:187], v[60:63]
	v_mfma_f32_16x16x32_bf16 v[56:59], v[152:155], v[184:187], v[56:59]
	v_mfma_f32_16x16x32_bf16 v[44:47], v[128:131], v[192:195], v[44:47]
	v_mfma_f32_16x16x32_bf16 v[40:43], v[152:155], v[192:195], v[40:43]
	v_mfma_f32_16x16x32_bf16 v[28:31], v[128:131], v[202:205], v[28:31]
	v_mfma_f32_16x16x32_bf16 v[24:27], v[152:155], v[202:205], v[24:27]
	v_mfma_f32_16x16x32_bf16 v[12:15], v[128:131], v[210:213], v[12:15]
	v_mfma_f32_16x16x32_bf16 v[8:11], v[152:155], v[210:213], v[8:11]
	v_mfma_f32_16x16x32_bf16 v[60:63], v[148:151], v[188:191], v[60:63]
	v_mfma_f32_16x16x32_bf16 v[56:59], v[156:159], v[188:191], v[56:59]
	v_mfma_f32_16x16x32_bf16 v[44:47], v[148:151], v[196:199], v[44:47]
	v_mfma_f32_16x16x32_bf16 v[40:43], v[156:159], v[196:199], v[40:43]
	v_mfma_f32_16x16x32_bf16 v[28:31], v[148:151], v[206:209], v[28:31]
	v_mfma_f32_16x16x32_bf16 v[24:27], v[156:159], v[206:209], v[24:27]
	v_mfma_f32_16x16x32_bf16 v[12:15], v[148:151], v[214:217], v[12:15]
	v_mfma_f32_16x16x32_bf16 v[8:11], v[156:159], v[214:217], v[8:11]
	s_setprio 0
	s_setprio 1
	v_mfma_f32_16x16x32_bf16 v[52:55], v[160:163], v[184:187], v[52:55]
	v_mfma_f32_16x16x32_bf16 v[48:51], v[176:179], v[184:187], v[48:51]
	v_mfma_f32_16x16x32_bf16 v[36:39], v[160:163], v[192:195], v[36:39]
	v_mfma_f32_16x16x32_bf16 v[32:35], v[176:179], v[192:195], v[32:35]
	v_mfma_f32_16x16x32_bf16 v[20:23], v[160:163], v[202:205], v[20:23]
	v_mfma_f32_16x16x32_bf16 v[16:19], v[176:179], v[202:205], v[16:19]
	v_mfma_f32_16x16x32_bf16 v[4:7], v[160:163], v[210:213], v[4:7]
	v_mfma_f32_16x16x32_bf16 v[0:3], v[176:179], v[210:213], v[0:3]
	v_mfma_f32_16x16x32_bf16 v[52:55], v[172:175], v[188:191], v[52:55]
	v_mfma_f32_16x16x32_bf16 v[48:51], v[180:183], v[188:191], v[48:51]
	v_mfma_f32_16x16x32_bf16 v[36:39], v[172:175], v[196:199], v[36:39]
	v_mfma_f32_16x16x32_bf16 v[32:35], v[180:183], v[196:199], v[32:35]
	v_mfma_f32_16x16x32_bf16 v[20:23], v[172:175], v[206:209], v[20:23]
	v_mfma_f32_16x16x32_bf16 v[16:19], v[180:183], v[206:209], v[16:19]
	v_mfma_f32_16x16x32_bf16 v[4:7], v[172:175], v[214:217], v[4:7]
	v_mfma_f32_16x16x32_bf16 v[0:3], v[180:183], v[214:217], v[0:3]
	s_setprio 0
	s_barrier
	s_add_u32 s6, s6, 0x100
	s_addc_u32 s7, s7, 0
	s_add_u32 s79, s79, 0x100
	s_addc_u32 s80, s80, 0
	s_cmp_ge_i32 s81, s68
	s_mov_b32 s52, s81
	s_cbranch_scc1 .LBB0_729

; #define PG8_STAGE(bufoff, gbase, voff) do { _Pragma("unroll") for (int _i = 0; _i < 2; ++_i) \
;         __builtin_amdgcn_global_load_lds((const unsigned*)((const char*)(gbase) + (voff)[_i]), (PG8_LAS unsigned*)(lds + (bufoff) + ldsw + _i * 8192), 16, 0, 0); } while (0)
; #define PG8_LDA(dst, b, h) do { _Pragma("unroll") for (int m = 0; m < 4; ++m) _Pragma("unroll") for (int k = 0; k < 2; ++k) dst[m][k] = *(const PG8_LAS bf16x8*)(lds + PG8_SA(b, h) + aoff + m * 2048 + k * 1024); } while (0)
; #define PG8_LDB(dst, b, h) do { _Pragma("unroll") for (int n = 0; n < 2; ++n) _Pragma("unroll") for (int k = 0; k < 2; ++k) dst[n][k] = *(const PG8_LAS bf16x8*)(lds + PG8_SB(b, h) + boff + n * 2048 + k * 1024); } while (0)
; #define PG8_MMA(ai, bj, At, Bt) do { __builtin_amdgcn_s_setprio(1); _Pragma("unroll") for (int m = 0; m < 4; ++m) _Pragma("unroll") for (int n = 0; n < 2; ++n) _Pragma("unroll") for (int k = 0; k < 2; ++k) \
;         acc[ai][bj][m][n] = __builtin_amdgcn_mfma_f32_16x16x32_bf16(Bt[n][k], At[m][k], acc[ai][bj][m][n], 0, 0, 0); __builtin_amdgcn_s_setprio(0); } while (0)
; #define PG8_WAIT_V(n) asm volatile("s_waitcnt vmcnt(" #n ")" ::: "memory")
; #define PG8_BAR __builtin_amdgcn_s_barrier()
; template <class Epi, class Sched, bool ALIGN_EPI = false, bool SP2 = false>
; __device__ __forceinline__ void gemm_phase(PG8_LAS unsigned char* lds, const Gemm g, const Sched& S, const Epi& E) {
;     ...
;         for (int t = 0; t < nt; t += 2) {
;             const bool last = (t == nt - 2);
;             const char* a1 = cA + (size_t)(t + 1) * kstep;
;             const char* a2 = last ? nA : cA + (size_t)(t + 2) * kstep; const char* b2 = last ? nB : cB + (size_t)(t + 2) * kstep;
;             const char* a3 = a2 + kstep; const char* b3 = b2 + kstep;
;             if (last && has_next) S.a_ready(nxt);
;             if constexpr (SP2) {
;             PG8_LDB(B0, 0, 0); PG8_LDB(B1, 0, 1); PG8_SCHED; PG8_LDA(At, 0, 0); PG8_STAGE(PG8_SA(1, 1), a1 + hstep, voffA);
;             PG8_WAIT_V(8); PG8_WAIT_L(0); PG8_BAR; PG8_MMA(0, 0, At, B0); PG8_MMA(0, 1, At, B1); PG8_BAR; PG8_SCHED;
;     ...
; #pragma unroll
;         for (int a = 0; a < 2; ++a)
; #pragma unroll
;             for (int b = 0; b < 2; ++b)
; #pragma unroll
;                 for (int m = 0; m < 4; ++m)
; #pragma unroll
;                     for (int n = 0; n < 2; ++n) acc[a][b][m][n] = (f32x4){0.f, 0.f, 0.f, 0.f};
.LBB0_873:
	s_andn2_b64 vcc, exec, s[44:45]
	s_waitcnt lgkmcnt(0)
	s_cbranch_vccz .Lcz_go_875
	v_mov_b32_e32 v127, 0
	v_mov_b32_e32 v126, v127
	v_mov_b32_e32 v125, v127
	v_mov_b32_e32 v124, v127
	v_mov_b32_e32 v123, v127
	v_mov_b32_e32 v122, v127
	v_mov_b32_e32 v121, v127
	v_mov_b32_e32 v120, v127
	v_mov_b32_e32 v111, v127
	v_mov_b32_e32 v110, v127
	v_mov_b32_e32 v109, v127
	v_mov_b32_e32 v108, v127
	v_mov_b32_e32 v107, v127
	v_mov_b32_e32 v106, v127
	v_mov_b32_e32 v105, v127
	v_mov_b32_e32 v104, v127
	v_mov_b32_e32 v95, v127
	v_mov_b32_e32 v94, v127
	v_mov_b32_e32 v93, v127
	v_mov_b32_e32 v92, v127
	v_mov_b32_e32 v91, v127
	v_mov_b32_e32 v90, v127
	v_mov_b32_e32 v89, v127
	v_mov_b32_e32 v88, v127
	v_mov_b32_e32 v79, v127
	v_mov_b32_e32 v78, v127
	v_mov_b32_e32 v77, v127
	v_mov_b32_e32 v76, v127
	v_mov_b32_e32 v75, v127
	v_mov_b32_e32 v74, v127
	v_mov_b32_e32 v73, v127
	v_mov_b32_e32 v72, v127
	v_mov_b32_e32 v119, v127
	v_mov_b32_e32 v118, v127
	v_mov_b32_e32 v117, v127
	v_mov_b32_e32 v116, v127
	v_mov_b32_e32 v115, v127
	v_mov_b32_e32 v114, v127
	v_mov_b32_e32 v113, v127
	v_mov_b32_e32 v112, v127
	v_mov_b32_e32 v103, v127
	v_mov_b32_e32 v102, v127
	v_mov_b32_e32 v101, v127
	v_mov_b32_e32 v100, v127
	v_mov_b32_e32 v99, v127
	v_mov_b32_e32 v98, v127
	v_mov_b32_e32 v97, v127
	v_mov_b32_e32 v96, v127
	v_mov_b32_e32 v87, v127
	v_mov_b32_e32 v86, v127
	v_mov_b32_e32 v85, v127
	v_mov_b32_e32 v84, v127
	v_mov_b32_e32 v83, v127
	v_mov_b32_e32 v82, v127
	v_mov_b32_e32 v81, v127
	v_mov_b32_e32 v80, v127
	v_mov_b32_e32 v71, v127
	v_mov_b32_e32 v70, v127
	v_mov_b32_e32 v69, v127
	v_mov_b32_e32 v68, v127
	v_mov_b32_e32 v67, v127
	v_mov_b32_e32 v66, v127
	v_mov_b32_e32 v65, v127
	v_mov_b32_e32 v64, v127
	v_mov_b32_e32 v63, v127
	v_mov_b32_e32 v62, v127
	v_mov_b32_e32 v61, v127
	v_mov_b32_e32 v60, v127
	v_mov_b32_e32 v59, v127
	v_mov_b32_e32 v58, v127
	v_mov_b32_e32 v57, v127
	v_mov_b32_e32 v56, v127
	v_mov_b32_e32 v47, v127
	v_mov_b32_e32 v46, v127
	v_mov_b32_e32 v45, v127
	v_mov_b32_e32 v44, v127
	v_mov_b32_e32 v43, v127
	v_mov_b32_e32 v42, v127
	v_mov_b32_e32 v41, v127
	v_mov_b32_e32 v40, v127
	v_mov_b32_e32 v31, v127
	v_mov_b32_e32 v30, v127
	v_mov_b32_e32 v29, v127
	v_mov_b32_e32 v28, v127
	v_mov_b32_e32 v27, v127
	v_mov_b32_e32 v26, v127
	v_mov_b32_e32 v25, v127
	v_mov_b32_e32 v24, v127
	v_mov_b32_e32 v15, v127
	v_mov_b32_e32 v14, v127
	v_mov_b32_e32 v13, v127
	v_mov_b32_e32 v12, v127
	v_mov_b32_e32 v11, v127
	v_mov_b32_e32 v10, v127
	v_mov_b32_e32 v9, v127
	v_mov_b32_e32 v8, v127
	v_mov_b32_e32 v55, v127
	v_mov_b32_e32 v54, v127
	v_mov_b32_e32 v53, v127
	v_mov_b32_e32 v52, v127
	v_mov_b32_e32 v51, v127
	v_mov_b32_e32 v50, v127
	v_mov_b32_e32 v49, v127
	v_mov_b32_e32 v48, v127
	v_mov_b32_e32 v39, v127
	v_mov_b32_e32 v38, v127
	v_mov_b32_e32 v37, v127
	v_mov_b32_e32 v36, v127
	v_mov_b32_e32 v35, v127
	v_mov_b32_e32 v34, v127
	v_mov_b32_e32 v33, v127
	v_mov_b32_e32 v32, v127
	v_mov_b32_e32 v23, v127
	v_mov_b32_e32 v22, v127
	v_mov_b32_e32 v21, v127
	v_mov_b32_e32 v20, v127
	v_mov_b32_e32 v19, v127
	v_mov_b32_e32 v18, v127
	v_mov_b32_e32 v17, v127
	v_mov_b32_e32 v16, v127
	v_mov_b32_e32 v7, v127
	v_mov_b32_e32 v6, v127
	v_mov_b32_e32 v5, v127
	v_mov_b32_e32 v4, v127
	v_mov_b32_e32 v3, v127
	v_mov_b32_e32 v2, v127
	v_mov_b32_e32 v1, v127
	v_mov_b32_e32 v0, v127
	s_branch .LBB0_876
.Lcz_go_875:
	s_add_u32 s50, s50, 0x80
	s_addc_u32 s51, s51, 0
	s_add_u32 s78, s52, 0x100
	s_addc_u32 s79, s53, 0
	s_mov_b32 s52, 0
	ds_read_b128 v[144:147], v151
	ds_read_b128 v[156:159], v151 offset:1024
	ds_read_b128 v[160:163], v151 offset:2048
	ds_read_b128 v[164:167], v151 offset:3072
	ds_read_b128 v[168:171], v152
	ds_read_b128 v[172:175], v152 offset:1024
	ds_read_b128 v[176:179], v152 offset:2048
	ds_read_b128 v[180:183], v152 offset:3072
	s_add_i32 s80, s52, 2
	s_add_u32 s16, s50, 0x80
	s_addc_u32 s17, s51, 0
	s_cmp_eq_u32 s68, s52
	s_cselect_b32 s52, s0, s16
	s_cselect_b32 s53, s1, s17
	s_cselect_b32 s83, s49, s79
	s_cselect_b32 s82, s48, s78
	v_lshl_add_u64 v[218:219], s[50:51], 0, v[136:137]
	s_add_i32 m0, s56, 0xc000
	ds_read_b128 v[184:187], v153
	ds_read_b128 v[188:191], v153 offset:1024
	ds_read_b128 v[192:195], v153 offset:2048
	ds_read_b128 v[196:199], v153 offset:3072
	ds_read_b128 v[202:205], v153 offset:4096
	ds_read_b128 v[206:209], v153 offset:5120
	ds_read_b128 v[210:213], v153 offset:6144
	ds_read_b128 v[214:217], v153 offset:7168
	global_load_lds_dwordx4 v[218:219], off
	v_lshl_add_u64 v[218:219], s[50:51], 0, v[138:139]
	s_add_i32 m0, s56, 0xe000
	s_nop 0
	global_load_lds_dwordx4 v[218:219], off
	s_waitcnt vmcnt(8)
	s_waitcnt lgkmcnt(0)
	s_barrier
; #define PG8_STAGE(bufoff, gbase, voff) do { _Pragma("unroll") for (int _i = 0; _i < 2; ++_i) \
;         __builtin_amdgcn_global_load_lds((const unsigned*)((const char*)(gbase) + (voff)[_i]), (PG8_LAS unsigned*)(lds + (bufoff) + ldsw + _i * 8192), 16, 0, 0); } while (0)
; #define PG8_LDA(dst, b, h) do { _Pragma("unroll") for (int m = 0; m < 4; ++m) _Pragma("unroll") for (int k = 0; k < 2; ++k) dst[m][k] = *(const PG8_LAS bf16x8*)(lds + PG8_SA(b, h) + aoff + m * 2048 + k * 1024); } while (0)
; #define PG8_MMA(ai, bj, At, Bt) do { __builtin_amdgcn_s_setprio(1); _Pragma("unroll") for (int m = 0; m < 4; ++m) _Pragma("unroll") for (int n = 0; n < 2; ++n) _Pragma("unroll") for (int k = 0; k < 2; ++k) \
;         acc[ai][bj][m][n] = __builtin_amdgcn_mfma_f32_16x16x32_bf16(Bt[n][k], At[m][k], acc[ai][bj][m][n], 0, 0, 0); __builtin_amdgcn_s_setprio(0); } while (0)
; #define PG8_WAIT_V(n) asm volatile("s_waitcnt vmcnt(" #n ")" ::: "memory")
; #define PG8_WAIT_L(n) asm volatile("s_waitcnt lgkmcnt(" #n ")" ::: "memory")
; #define PG8_BAR __builtin_amdgcn_s_barrier()
; #define PG8_SCHED __builtin_amdgcn_sched_barrier(0)
; template <class Epi, class Sched, bool ALIGN_EPI = false, bool SP2 = false>
; __device__ __forceinline__ void gemm_phase(PG8_LAS unsigned char* lds, const Gemm g, const Sched& S, const Epi& E) {
;     ...
;             PG8_WAIT_V(8); PG8_WAIT_L(0); PG8_BAR; PG8_MMA(0, 0, At, B0); PG8_MMA(0, 1, At, B1); PG8_BAR; PG8_SCHED;
;             PG8_LDA(At, 0, 1); PG8_STAGE(PG8_SB(0, 0), b2, voffB); PG8_STAGE(PG8_SB(0, 1), b2 + hstep, voffB); PG8_STAGE(PG8_SA(0, 0), a2, voffA);
;             PG8_WAIT_V(8); PG8_WAIT_L(0); PG8_BAR; PG8_MMA(1, 0, At, B0); PG8_MMA(1, 1, At, B1); PG8_BAR; PG8_SCHED;
	s_setprio 1
	s_waitcnt lgkmcnt(0)
	v_mfma_f32_16x16x32_bf16 v[124:127], v[144:147], v[184:187], 0
	v_mfma_f32_16x16x32_bf16 v[120:123], v[160:163], v[184:187], 0
	v_mfma_f32_16x16x32_bf16 v[108:111], v[144:147], v[192:195], 0
	v_mfma_f32_16x16x32_bf16 v[104:107], v[160:163], v[192:195], 0
	v_mfma_f32_16x16x32_bf16 v[92:95], v[144:147], v[202:205], 0
	v_mfma_f32_16x16x32_bf16 v[88:91], v[160:163], v[202:205], 0
	v_mfma_f32_16x16x32_bf16 v[76:79], v[144:147], v[210:213], 0
	v_mfma_f32_16x16x32_bf16 v[72:75], v[160:163], v[210:213], 0
	v_mfma_f32_16x16x32_bf16 v[124:127], v[156:159], v[188:191], v[124:127]
	v_mfma_f32_16x16x32_bf16 v[120:123], v[164:167], v[188:191], v[120:123]
	v_mfma_f32_16x16x32_bf16 v[108:111], v[156:159], v[196:199], v[108:111]
	v_mfma_f32_16x16x32_bf16 v[104:107], v[164:167], v[196:199], v[104:107]
	v_mfma_f32_16x16x32_bf16 v[92:95], v[156:159], v[206:209], v[92:95]
	v_mfma_f32_16x16x32_bf16 v[88:91], v[164:167], v[206:209], v[88:91]
	v_mfma_f32_16x16x32_bf16 v[76:79], v[156:159], v[214:217], v[76:79]
	v_mfma_f32_16x16x32_bf16 v[72:75], v[164:167], v[214:217], v[72:75]
	s_setprio 0
	s_setprio 1
	v_mfma_f32_16x16x32_bf16 v[116:119], v[168:171], v[184:187], 0
	v_mfma_f32_16x16x32_bf16 v[112:115], v[176:179], v[184:187], 0
	v_mfma_f32_16x16x32_bf16 v[100:103], v[168:171], v[192:195], 0
	v_mfma_f32_16x16x32_bf16 v[96:99], v[176:179], v[192:195], 0
	v_mfma_f32_16x16x32_bf16 v[84:87], v[168:171], v[202:205], 0
	v_mfma_f32_16x16x32_bf16 v[80:83], v[176:179], v[202:205], 0
	v_mfma_f32_16x16x32_bf16 v[68:71], v[168:171], v[210:213], 0
	v_mfma_f32_16x16x32_bf16 v[64:67], v[176:179], v[210:213], 0
	v_mfma_f32_16x16x32_bf16 v[116:119], v[172:175], v[188:191], v[116:119]
	v_mfma_f32_16x16x32_bf16 v[112:115], v[180:183], v[188:191], v[112:115]
	v_mfma_f32_16x16x32_bf16 v[100:103], v[172:175], v[196:199], v[100:103]
	v_mfma_f32_16x16x32_bf16 v[96:99], v[180:183], v[196:199], v[96:99]
	v_mfma_f32_16x16x32_bf16 v[84:87], v[172:175], v[206:209], v[84:87]
	v_mfma_f32_16x16x32_bf16 v[80:83], v[180:183], v[206:209], v[80:83]
	v_mfma_f32_16x16x32_bf16 v[68:71], v[172:175], v[214:217], v[68:71]
	v_mfma_f32_16x16x32_bf16 v[64:67], v[180:183], v[214:217], v[64:67]
	s_setprio 0
	s_barrier
	s_add_i32 s16, s72, s55
	v_lshl_add_u64 v[218:219], s[82:83], 0, v[130:131]
	s_mov_b32 m0, s16
	ds_read_b128 v[184:187], v153 offset:16384
	ds_read_b128 v[188:191], v153 offset:17408
	ds_read_b128 v[192:195], v153 offset:18432
	ds_read_b128 v[196:199], v153 offset:19456
	ds_read_b128 v[202:205], v153 offset:20480
	ds_read_b128 v[206:209], v153 offset:21504
	ds_read_b128 v[210:213], v153 offset:22528
	ds_read_b128 v[214:217], v153 offset:23552
	global_load_lds_dwordx4 v[218:219], off
	s_add_i32 m0, s16, 0x2000
	v_lshl_add_u64 v[220:221], s[82:83], 0, v[134:135]
	s_add_u32 s82, s82, s12
	s_addc_u32 s83, s83, s13
	s_add_i32 s16, s73, s55
	global_load_lds_dwordx4 v[220:221], off
	v_lshl_add_u64 v[222:223], s[82:83], 0, v[130:131]
	s_mov_b32 m0, s16
	v_lshl_add_u64 v[224:225], s[82:83], 0, v[134:135]
	global_load_lds_dwordx4 v[222:223], off
	s_add_i32 m0, s16, 0x2000
	v_lshl_add_u64 v[226:227], s[52:53], 0, v[128:129]
	global_load_lds_dwordx4 v[224:225], off
	s_mov_b32 m0, s56
	v_lshl_add_u64 v[228:229], s[52:53], 0, v[132:133]
	global_load_lds_dwordx4 v[226:227], off
	s_mov_b32 m0, s57
	s_nop 0
	global_load_lds_dwordx4 v[228:229], off
	s_waitcnt vmcnt(8)
	s_waitcnt lgkmcnt(0)
	s_barrier
	s_setprio 1
	s_waitcnt lgkmcnt(0)
	v_mfma_f32_16x16x32_bf16 v[60:63], v[144:147], v[184:187], 0
	v_mfma_f32_16x16x32_bf16 v[56:59], v[160:163], v[184:187], 0
	v_mfma_f32_16x16x32_bf16 v[44:47], v[144:147], v[192:195], 0
	v_mfma_f32_16x16x32_bf16 v[40:43], v[160:163], v[192:195], 0
	v_mfma_f32_16x16x32_bf16 v[28:31], v[144:147], v[202:205], 0
	v_mfma_f32_16x16x32_bf16 v[24:27], v[160:163], v[202:205], 0
	v_mfma_f32_16x16x32_bf16 v[12:15], v[144:147], v[210:213], 0
	v_mfma_f32_16x16x32_bf16 v[8:11], v[160:163], v[210:213], 0
	v_mfma_f32_16x16x32_bf16 v[60:63], v[156:159], v[188:191], v[60:63]
	v_mfma_f32_16x16x32_bf16 v[56:59], v[164:167], v[188:191], v[56:59]
	v_mfma_f32_16x16x32_bf16 v[44:47], v[156:159], v[196:199], v[44:47]
	v_mfma_f32_16x16x32_bf16 v[40:43], v[164:167], v[196:199], v[40:43]
	v_mfma_f32_16x16x32_bf16 v[28:31], v[156:159], v[206:209], v[28:31]
	v_mfma_f32_16x16x32_bf16 v[24:27], v[164:167], v[206:209], v[24:27]
	v_mfma_f32_16x16x32_bf16 v[12:15], v[156:159], v[214:217], v[12:15]
	v_mfma_f32_16x16x32_bf16 v[8:11], v[164:167], v[214:217], v[8:11]
	s_setprio 0
	s_setprio 1
	v_mfma_f32_16x16x32_bf16 v[52:55], v[168:171], v[184:187], 0
	v_mfma_f32_16x16x32_bf16 v[48:51], v[176:179], v[184:187], 0
	v_mfma_f32_16x16x32_bf16 v[36:39], v[168:171], v[192:195], 0
	v_mfma_f32_16x16x32_bf16 v[32:35], v[176:179], v[192:195], 0
	v_mfma_f32_16x16x32_bf16 v[20:23], v[168:171], v[202:205], 0
	v_mfma_f32_16x16x32_bf16 v[16:19], v[176:179], v[202:205], 0
	v_mfma_f32_16x16x32_bf16 v[4:7], v[168:171], v[210:213], 0
	v_mfma_f32_16x16x32_bf16 v[0:3], v[176:179], v[210:213], 0
	v_mfma_f32_16x16x32_bf16 v[52:55], v[172:175], v[188:191], v[52:55]
	v_mfma_f32_16x16x32_bf16 v[48:51], v[180:183], v[188:191], v[48:51]
	v_mfma_f32_16x16x32_bf16 v[36:39], v[172:175], v[196:199], v[36:39]
	v_mfma_f32_16x16x32_bf16 v[32:35], v[180:183], v[196:199], v[32:35]
	v_mfma_f32_16x16x32_bf16 v[20:23], v[172:175], v[206:209], v[20:23]
	v_mfma_f32_16x16x32_bf16 v[16:19], v[180:183], v[206:209], v[16:19]
	v_mfma_f32_16x16x32_bf16 v[4:7], v[172:175], v[214:217], v[4:7]
	v_mfma_f32_16x16x32_bf16 v[0:3], v[180:183], v[214:217], v[0:3]
	s_setprio 0
	s_barrier
; #define PG8_STAGE(bufoff, gbase, voff) do { _Pragma("unroll") for (int _i = 0; _i < 2; ++_i) \
;         __builtin_amdgcn_global_load_lds((const unsigned*)((const char*)(gbase) + (voff)[_i]), (PG8_LAS unsigned*)(lds + (bufoff) + ldsw + _i * 8192), 16, 0, 0); } while (0)
; #define PG8_LDA(dst, b, h) do { _Pragma("unroll") for (int m = 0; m < 4; ++m) _Pragma("unroll") for (int k = 0; k < 2; ++k) dst[m][k] = *(const PG8_LAS bf16x8*)(lds + PG8_SA(b, h) + aoff + m * 2048 + k * 1024); } while (0)
; #define PG8_LDB(dst, b, h) do { _Pragma("unroll") for (int n = 0; n < 2; ++n) _Pragma("unroll") for (int k = 0; k < 2; ++k) dst[n][k] = *(const PG8_LAS bf16x8*)(lds + PG8_SB(b, h) + boff + n * 2048 + k * 1024); } while (0)
; #define PG8_MMA(ai, bj, At, Bt) do { __builtin_amdgcn_s_setprio(1); _Pragma("unroll") for (int m = 0; m < 4; ++m) _Pragma("unroll") for (int n = 0; n < 2; ++n) _Pragma("unroll") for (int k = 0; k < 2; ++k) \
;         acc[ai][bj][m][n] = __builtin_amdgcn_mfma_f32_16x16x32_bf16(Bt[n][k], At[m][k], acc[ai][bj][m][n], 0, 0, 0); __builtin_amdgcn_s_setprio(0); } while (0)
; #define PG8_WAIT_V(n) asm volatile("s_waitcnt vmcnt(" #n ")" ::: "memory")
; #define PG8_WAIT_L(n) asm volatile("s_waitcnt lgkmcnt(" #n ")" ::: "memory")
; #define PG8_BAR __builtin_amdgcn_s_barrier()
; #define PG8_SCHED __builtin_amdgcn_sched_barrier(0)
; template <class Epi, class Sched, bool ALIGN_EPI = false, bool SP2 = false>
; __device__ __forceinline__ void gemm_phase(PG8_LAS unsigned char* lds, const Gemm g, const Sched& S, const Epi& E) {
;     ...
;             PG8_LDB(B0, 1, 0); PG8_LDB(B1, 1, 1); PG8_SCHED; PG8_LDA(At, 1, 0); PG8_STAGE(PG8_SA(0, 1), a2 + hstep, voffA);
;             PG8_WAIT_V(8); PG8_WAIT_L(0); PG8_BAR; PG8_MMA(0, 0, At, B0); PG8_MMA(0, 1, At, B1); PG8_BAR; PG8_SCHED;
	s_add_i32 s16, 0, 0x18000
	v_add_u32_e32 v155, s16, v149
	s_add_i32 s17, 0, 0x1c000
	ds_read_b128 v[144:147], v155
	ds_read_b128 v[156:159], v155 offset:1024
	ds_read_b128 v[160:163], v155 offset:2048
	ds_read_b128 v[164:167], v155 offset:3072
	v_add_u32_e32 v155, s17, v149
	ds_read_b128 v[168:171], v155
	ds_read_b128 v[172:175], v155 offset:1024
	ds_read_b128 v[176:179], v155 offset:2048
	ds_read_b128 v[180:183], v155 offset:3072
	s_add_u32 s52, s52, s12
	s_addc_u32 s53, s53, s13
	s_mov_b32 m0, s58
	v_lshl_add_u64 v[230:231], s[52:53], 0, v[128:129]
	ds_read_b128 v[184:187], v153 offset:32768
	ds_read_b128 v[188:191], v153 offset:33792
	ds_read_b128 v[192:195], v153 offset:34816
	ds_read_b128 v[196:199], v153 offset:35840
	ds_read_b128 v[202:205], v153 offset:36864
	ds_read_b128 v[206:209], v153 offset:37888
	ds_read_b128 v[210:213], v153 offset:38912
	ds_read_b128 v[214:217], v153 offset:39936
	global_load_lds_dwordx4 v[230:231], off
	v_lshl_add_u64 v[230:231], s[52:53], 0, v[132:133]
	s_mov_b32 m0, s59
	s_nop 0
	global_load_lds_dwordx4 v[230:231], off
	s_waitcnt vmcnt(8)
	s_waitcnt lgkmcnt(0)
	s_barrier
	s_setprio 1
	s_waitcnt lgkmcnt(0)
	v_mfma_f32_16x16x32_bf16 v[124:127], v[144:147], v[184:187], v[124:127]
	v_mfma_f32_16x16x32_bf16 v[120:123], v[160:163], v[184:187], v[120:123]
	v_mfma_f32_16x16x32_bf16 v[108:111], v[144:147], v[192:195], v[108:111]
	v_mfma_f32_16x16x32_bf16 v[104:107], v[160:163], v[192:195], v[104:107]
	v_mfma_f32_16x16x32_bf16 v[92:95], v[144:147], v[202:205], v[92:95]
	v_mfma_f32_16x16x32_bf16 v[88:91], v[160:163], v[202:205], v[88:91]
	v_mfma_f32_16x16x32_bf16 v[76:79], v[144:147], v[210:213], v[76:79]
	v_mfma_f32_16x16x32_bf16 v[72:75], v[160:163], v[210:213], v[72:75]
	v_mfma_f32_16x16x32_bf16 v[124:127], v[156:159], v[188:191], v[124:127]
	v_mfma_f32_16x16x32_bf16 v[120:123], v[164:167], v[188:191], v[120:123]
	v_mfma_f32_16x16x32_bf16 v[108:111], v[156:159], v[196:199], v[108:111]
	v_mfma_f32_16x16x32_bf16 v[104:107], v[164:167], v[196:199], v[104:107]
	v_mfma_f32_16x16x32_bf16 v[92:95], v[156:159], v[206:209], v[92:95]
	v_mfma_f32_16x16x32_bf16 v[88:91], v[164:167], v[206:209], v[88:91]
	v_mfma_f32_16x16x32_bf16 v[76:79], v[156:159], v[214:217], v[76:79]
	v_mfma_f32_16x16x32_bf16 v[72:75], v[164:167], v[214:217], v[72:75]
	s_setprio 0
	s_setprio 1
	v_mfma_f32_16x16x32_bf16 v[116:119], v[168:171], v[184:187], v[116:119]
	v_mfma_f32_16x16x32_bf16 v[112:115], v[176:179], v[184:187], v[112:115]
	v_mfma_f32_16x16x32_bf16 v[100:103], v[168:171], v[192:195], v[100:103]
	v_mfma_f32_16x16x32_bf16 v[96:99], v[176:179], v[192:195], v[96:99]
	v_mfma_f32_16x16x32_bf16 v[84:87], v[168:171], v[202:205], v[84:87]
	v_mfma_f32_16x16x32_bf16 v[80:83], v[176:179], v[202:205], v[80:83]
	v_mfma_f32_16x16x32_bf16 v[68:71], v[168:171], v[210:213], v[68:71]
	v_mfma_f32_16x16x32_bf16 v[64:67], v[176:179], v[210:213], v[64:67]
	v_mfma_f32_16x16x32_bf16 v[116:119], v[172:175], v[188:191], v[116:119]
	v_mfma_f32_16x16x32_bf16 v[112:115], v[180:183], v[188:191], v[112:115]
	v_mfma_f32_16x16x32_bf16 v[100:103], v[172:175], v[196:199], v[100:103]
	v_mfma_f32_16x16x32_bf16 v[96:99], v[180:183], v[196:199], v[96:99]
	v_mfma_f32_16x16x32_bf16 v[84:87], v[172:175], v[206:209], v[84:87]
	v_mfma_f32_16x16x32_bf16 v[80:83], v[180:183], v[206:209], v[80:83]
	v_mfma_f32_16x16x32_bf16 v[68:71], v[172:175], v[214:217], v[68:71]
	v_mfma_f32_16x16x32_bf16 v[64:67], v[180:183], v[214:217], v[64:67]
	s_setprio 0
	s_barrier
; #define PG8_STAGE(bufoff, gbase, voff) do { _Pragma("unroll") for (int _i = 0; _i < 2; ++_i) \
;         __builtin_amdgcn_global_load_lds((const unsigned*)((const char*)(gbase) + (voff)[_i]), (PG8_LAS unsigned*)(lds + (bufoff) + ldsw + _i * 8192), 16, 0, 0); } while (0)
; #define PG8_LDA(dst, b, h) do { _Pragma("unroll") for (int m = 0; m < 4; ++m) _Pragma("unroll") for (int k = 0; k < 2; ++k) dst[m][k] = *(const PG8_LAS bf16x8*)(lds + PG8_SA(b, h) + aoff + m * 2048 + k * 1024); } while (0)
; #define PG8_MMA(ai, bj, At, Bt) do { __builtin_amdgcn_s_setprio(1); _Pragma("unroll") for (int m = 0; m < 4; ++m) _Pragma("unroll") for (int n = 0; n < 2; ++n) _Pragma("unroll") for (int k = 0; k < 2; ++k) \
;         acc[ai][bj][m][n] = __builtin_amdgcn_mfma_f32_16x16x32_bf16(Bt[n][k], At[m][k], acc[ai][bj][m][n], 0, 0, 0); __builtin_amdgcn_s_setprio(0); } while (0)
; #define PG8_WAIT_V(n) asm volatile("s_waitcnt vmcnt(" #n ")" ::: "memory")
; #define PG8_WAIT_L(n) asm volatile("s_waitcnt lgkmcnt(" #n ")" ::: "memory")
; #define PG8_BAR __builtin_amdgcn_s_barrier()
; #define PG8_SCHED __builtin_amdgcn_sched_barrier(0)
; template <class Epi, class Sched, bool ALIGN_EPI = false, bool SP2 = false>
; __device__ __forceinline__ void gemm_phase(PG8_LAS unsigned char* lds, const Gemm g, const Sched& S, const Epi& E) {
;     ...
;         for (int t = 0; t < nt; t += 2) {
;             const bool last = (t == nt - 2);
;     ...
;             PG8_LDA(At, 1, 1); PG8_STAGE(PG8_SB(1, 0), b3, voffB); PG8_STAGE(PG8_SB(1, 1), b3 + hstep, voffB); PG8_STAGE(PG8_SA(1, 0), a3, voffA);
;             PG8_WAIT_V(8); PG8_WAIT_L(0); PG8_BAR; PG8_MMA(1, 0, At, B0); PG8_MMA(1, 1, At, B1); PG8_BAR; PG8_SCHED;
	s_add_i32 s16, s16, s55
	v_lshl_add_u64 v[218:219], v[218:219], 0, s[42:43]
	s_mov_b32 m0, s16
	ds_read_b128 v[184:187], v153 offset:49152
	ds_read_b128 v[188:191], v153 offset:50176
	ds_read_b128 v[192:195], v153 offset:51200
	ds_read_b128 v[196:199], v153 offset:52224
	ds_read_b128 v[202:205], v153 offset:53248
	ds_read_b128 v[206:209], v153 offset:54272
	ds_read_b128 v[210:213], v153 offset:55296
	ds_read_b128 v[214:217], v153 offset:56320
	global_load_lds_dwordx4 v[218:219], off
	v_lshl_add_u64 v[218:219], v[220:221], 0, s[42:43]
	s_add_i32 m0, s16, 0x2000
	s_add_i32 s16, s17, s55
	global_load_lds_dwordx4 v[218:219], off
	v_lshl_add_u64 v[218:219], v[222:223], 0, s[42:43]
	s_mov_b32 m0, s16
	s_nop 0
	global_load_lds_dwordx4 v[218:219], off
	v_lshl_add_u64 v[218:219], v[224:225], 0, s[42:43]
	s_add_i32 m0, s16, 0x2000
	s_nop 0
	global_load_lds_dwordx4 v[218:219], off
	v_lshl_add_u64 v[218:219], v[226:227], 0, s[42:43]
	s_mov_b32 m0, s60
	s_nop 0
	global_load_lds_dwordx4 v[218:219], off
	v_lshl_add_u64 v[218:219], v[228:229], 0, s[42:43]
	s_mov_b32 m0, s61
	s_nop 0
	global_load_lds_dwordx4 v[218:219], off
	s_waitcnt vmcnt(8)
	s_waitcnt lgkmcnt(0)
	s_barrier
	s_setprio 1
	s_waitcnt lgkmcnt(0)
	v_mfma_f32_16x16x32_bf16 v[60:63], v[144:147], v[184:187], v[60:63]
	v_mfma_f32_16x16x32_bf16 v[56:59], v[160:163], v[184:187], v[56:59]
	v_mfma_f32_16x16x32_bf16 v[44:47], v[144:147], v[192:195], v[44:47]
	v_mfma_f32_16x16x32_bf16 v[40:43], v[160:163], v[192:195], v[40:43]
	v_mfma_f32_16x16x32_bf16 v[28:31], v[144:147], v[202:205], v[28:31]
	v_mfma_f32_16x16x32_bf16 v[24:27], v[160:163], v[202:205], v[24:27]
	v_mfma_f32_16x16x32_bf16 v[12:15], v[144:147], v[210:213], v[12:15]
	v_mfma_f32_16x16x32_bf16 v[8:11], v[160:163], v[210:213], v[8:11]
	v_mfma_f32_16x16x32_bf16 v[60:63], v[156:159], v[188:191], v[60:63]
	v_mfma_f32_16x16x32_bf16 v[56:59], v[164:167], v[188:191], v[56:59]
	v_mfma_f32_16x16x32_bf16 v[44:47], v[156:159], v[196:199], v[44:47]
	v_mfma_f32_16x16x32_bf16 v[40:43], v[164:167], v[196:199], v[40:43]
	v_mfma_f32_16x16x32_bf16 v[28:31], v[156:159], v[206:209], v[28:31]
	v_mfma_f32_16x16x32_bf16 v[24:27], v[164:167], v[206:209], v[24:27]
	v_mfma_f32_16x16x32_bf16 v[12:15], v[156:159], v[214:217], v[12:15]
	v_mfma_f32_16x16x32_bf16 v[8:11], v[164:167], v[214:217], v[8:11]
	s_setprio 0
	s_setprio 1
	v_mfma_f32_16x16x32_bf16 v[52:55], v[168:171], v[184:187], v[52:55]
	v_mfma_f32_16x16x32_bf16 v[48:51], v[176:179], v[184:187], v[48:51]
	v_mfma_f32_16x16x32_bf16 v[36:39], v[168:171], v[192:195], v[36:39]
	v_mfma_f32_16x16x32_bf16 v[32:35], v[176:179], v[192:195], v[32:35]
	v_mfma_f32_16x16x32_bf16 v[20:23], v[168:171], v[202:205], v[20:23]
	v_mfma_f32_16x16x32_bf16 v[16:19], v[176:179], v[202:205], v[16:19]
	v_mfma_f32_16x16x32_bf16 v[4:7], v[168:171], v[210:213], v[4:7]
	v_mfma_f32_16x16x32_bf16 v[0:3], v[176:179], v[210:213], v[0:3]
	v_mfma_f32_16x16x32_bf16 v[52:55], v[172:175], v[188:191], v[52:55]
	v_mfma_f32_16x16x32_bf16 v[48:51], v[180:183], v[188:191], v[48:51]
	v_mfma_f32_16x16x32_bf16 v[36:39], v[172:175], v[196:199], v[36:39]
	v_mfma_f32_16x16x32_bf16 v[32:35], v[180:183], v[196:199], v[32:35]
	v_mfma_f32_16x16x32_bf16 v[20:23], v[172:175], v[206:209], v[20:23]
	v_mfma_f32_16x16x32_bf16 v[16:19], v[180:183], v[206:209], v[16:19]
	v_mfma_f32_16x16x32_bf16 v[4:7], v[172:175], v[214:217], v[4:7]
	v_mfma_f32_16x16x32_bf16 v[0:3], v[180:183], v[214:217], v[0:3]
	s_setprio 0
	s_barrier
	s_add_u32 s50, s50, 0x100
	s_addc_u32 s51, s51, 0
	s_add_u32 s78, s78, 0x100
	s_addc_u32 s79, s79, 0
	s_cmp_ge_i32 s80, s63
	s_mov_b32 s52, s80
	s_cbranch_scc1 .LBB0_876

; #define PG8_STAGE(bufoff, gbase, voff) do { _Pragma("unroll") for (int _i = 0; _i < 2; ++_i) \
;         __builtin_amdgcn_global_load_lds((const unsigned*)((const char*)(gbase) + (voff)[_i]), (PG8_LAS unsigned*)(lds + (bufoff) + ldsw + _i * 8192), 16, 0, 0); } while (0)
; #define PG8_LDA(dst, b, h) do { _Pragma("unroll") for (int m = 0; m < 4; ++m) _Pragma("unroll") for (int k = 0; k < 2; ++k) dst[m][k] = *(const PG8_LAS bf16x8*)(lds + PG8_SA(b, h) + aoff + m * 2048 + k * 1024); } while (0)
; #define PG8_LDB(dst, b, h) do { _Pragma("unroll") for (int n = 0; n < 2; ++n) _Pragma("unroll") for (int k = 0; k < 2; ++k) dst[n][k] = *(const PG8_LAS bf16x8*)(lds + PG8_SB(b, h) + boff + n * 2048 + k * 1024); } while (0)
; #define PG8_MMA(ai, bj, At, Bt) do { __builtin_amdgcn_s_setprio(1); _Pragma("unroll") for (int m = 0; m < 4; ++m) _Pragma("unroll") for (int n = 0; n < 2; ++n) _Pragma("unroll") for (int k = 0; k < 2; ++k) \
;         acc[ai][bj][m][n] = __builtin_amdgcn_mfma_f32_16x16x32_bf16(Bt[n][k], At[m][k], acc[ai][bj][m][n], 0, 0, 0); __builtin_amdgcn_s_setprio(0); } while (0)
; #define PG8_WAIT_V(n) asm volatile("s_waitcnt vmcnt(" #n ")" ::: "memory")
; #define PG8_BAR __builtin_amdgcn_s_barrier()
; template <class Epi, class Sched, bool ALIGN_EPI = false, bool SP2 = false>
; __device__ __forceinline__ void gemm_phase(PG8_LAS unsigned char* lds, const Gemm g, const Sched& S, const Epi& E) {
;     ...
;         for (int t = 0; t < nt; t += 2) {
;             const bool last = (t == nt - 2);
;             const char* a1 = cA + (size_t)(t + 1) * kstep;
;             const char* a2 = last ? nA : cA + (size_t)(t + 2) * kstep; const char* b2 = last ? nB : cB + (size_t)(t + 2) * kstep;
;             const char* a3 = a2 + kstep; const char* b3 = b2 + kstep;
;             if (last && has_next) S.a_ready(nxt);
;             if constexpr (SP2) {
;             PG8_LDB(B0, 0, 0); PG8_LDB(B1, 0, 1); PG8_SCHED; PG8_LDA(At, 0, 0); PG8_STAGE(PG8_SA(1, 1), a1 + hstep, voffA);
;             PG8_WAIT_V(8); PG8_WAIT_L(0); PG8_BAR; PG8_MMA(0, 0, At, B0); PG8_MMA(0, 1, At, B1); PG8_BAR; PG8_SCHED;
;     ...
; #pragma unroll
;         for (int a = 0; a < 2; ++a)
; #pragma unroll
;             for (int b = 0; b < 2; ++b)
; #pragma unroll
;                 for (int m = 0; m < 4; ++m)
; #pragma unroll
;                     for (int n = 0; n < 2; ++n) acc[a][b][m][n] = (f32x4){0.f, 0.f, 0.f, 0.f};
.LBB0_1019:
	s_and_b64 vcc, exec, s[4:5]
	s_cbranch_vccz .Lcz_go_1021
	v_mov_b32_e32 v127, 0
	v_mov_b32_e32 v126, v127
	v_mov_b32_e32 v125, v127
	v_mov_b32_e32 v124, v127
	v_mov_b32_e32 v119, v127
	v_mov_b32_e32 v118, v127
	v_mov_b32_e32 v117, v127
	v_mov_b32_e32 v116, v127
	v_mov_b32_e32 v111, v127
	v_mov_b32_e32 v110, v127
	v_mov_b32_e32 v109, v127
	v_mov_b32_e32 v108, v127
	v_mov_b32_e32 v103, v127
	v_mov_b32_e32 v102, v127
	v_mov_b32_e32 v101, v127
	v_mov_b32_e32 v100, v127
	v_mov_b32_e32 v95, v127
	v_mov_b32_e32 v94, v127
	v_mov_b32_e32 v93, v127
	v_mov_b32_e32 v92, v127
	v_mov_b32_e32 v87, v127
	v_mov_b32_e32 v86, v127
	v_mov_b32_e32 v85, v127
	v_mov_b32_e32 v84, v127
	v_mov_b32_e32 v79, v127
	v_mov_b32_e32 v78, v127
	v_mov_b32_e32 v77, v127
	v_mov_b32_e32 v76, v127
	v_mov_b32_e32 v71, v127
	v_mov_b32_e32 v70, v127
	v_mov_b32_e32 v69, v127
	v_mov_b32_e32 v68, v127
	v_mov_b32_e32 v123, v127
	v_mov_b32_e32 v122, v127
	v_mov_b32_e32 v121, v127
	v_mov_b32_e32 v120, v127
	v_mov_b32_e32 v115, v127
	v_mov_b32_e32 v114, v127
	v_mov_b32_e32 v113, v127
	v_mov_b32_e32 v112, v127
	v_mov_b32_e32 v107, v127
	v_mov_b32_e32 v106, v127
	v_mov_b32_e32 v105, v127
	v_mov_b32_e32 v104, v127
	v_mov_b32_e32 v99, v127
	v_mov_b32_e32 v98, v127
	v_mov_b32_e32 v97, v127
	v_mov_b32_e32 v96, v127
	v_mov_b32_e32 v91, v127
	v_mov_b32_e32 v90, v127
	v_mov_b32_e32 v89, v127
	v_mov_b32_e32 v88, v127
	v_mov_b32_e32 v83, v127
	v_mov_b32_e32 v82, v127
	v_mov_b32_e32 v81, v127
	v_mov_b32_e32 v80, v127
	v_mov_b32_e32 v75, v127
	v_mov_b32_e32 v74, v127
	v_mov_b32_e32 v73, v127
	v_mov_b32_e32 v72, v127
	v_mov_b32_e32 v67, v127
	v_mov_b32_e32 v66, v127
	v_mov_b32_e32 v65, v127
	v_mov_b32_e32 v64, v127
	v_mov_b32_e32 v63, v127
	v_mov_b32_e32 v62, v127
	v_mov_b32_e32 v61, v127
	v_mov_b32_e32 v60, v127
	v_mov_b32_e32 v55, v127
	v_mov_b32_e32 v54, v127
	v_mov_b32_e32 v53, v127
	v_mov_b32_e32 v52, v127
	v_mov_b32_e32 v47, v127
	v_mov_b32_e32 v46, v127
	v_mov_b32_e32 v45, v127
	v_mov_b32_e32 v44, v127
	v_mov_b32_e32 v39, v127
	v_mov_b32_e32 v38, v127
	v_mov_b32_e32 v37, v127
	v_mov_b32_e32 v36, v127
	v_mov_b32_e32 v31, v127
	v_mov_b32_e32 v30, v127
	v_mov_b32_e32 v29, v127
	v_mov_b32_e32 v28, v127
	v_mov_b32_e32 v23, v127
	v_mov_b32_e32 v22, v127
	v_mov_b32_e32 v21, v127
	v_mov_b32_e32 v20, v127
	v_mov_b32_e32 v15, v127
	v_mov_b32_e32 v14, v127
	v_mov_b32_e32 v13, v127
	v_mov_b32_e32 v12, v127
	v_mov_b32_e32 v7, v127
	v_mov_b32_e32 v6, v127
	v_mov_b32_e32 v5, v127
	v_mov_b32_e32 v4, v127
	v_mov_b32_e32 v59, v127
	v_mov_b32_e32 v58, v127
	v_mov_b32_e32 v57, v127
	v_mov_b32_e32 v56, v127
	v_mov_b32_e32 v51, v127
	v_mov_b32_e32 v50, v127
	v_mov_b32_e32 v49, v127
	v_mov_b32_e32 v48, v127
	v_mov_b32_e32 v43, v127
	v_mov_b32_e32 v42, v127
	v_mov_b32_e32 v41, v127
	v_mov_b32_e32 v40, v127
	v_mov_b32_e32 v35, v127
	v_mov_b32_e32 v34, v127
	v_mov_b32_e32 v33, v127
	v_mov_b32_e32 v32, v127
	v_mov_b32_e32 v27, v127
	v_mov_b32_e32 v26, v127
	v_mov_b32_e32 v25, v127
	v_mov_b32_e32 v24, v127
	v_mov_b32_e32 v19, v127
	v_mov_b32_e32 v18, v127
	v_mov_b32_e32 v17, v127
	v_mov_b32_e32 v16, v127
	v_mov_b32_e32 v11, v127
	v_mov_b32_e32 v10, v127
	v_mov_b32_e32 v9, v127
	v_mov_b32_e32 v8, v127
	v_mov_b32_e32 v3, v127
	v_mov_b32_e32 v2, v127
	v_mov_b32_e32 v1, v127
	v_mov_b32_e32 v0, v127
	s_branch .LBB0_1022
.Lcz_go_1021:
	s_add_u32 s42, s42, 0x80
	s_addc_u32 s43, s43, 0
	s_add_u32 s68, s44, 0x100
	s_addc_u32 s69, s45, 0
	s_mov_b32 s44, 0
	ds_read_b128 v[150:153], v147
	ds_read_b128 v[154:157], v147 offset:1024
	ds_read_b128 v[158:161], v147 offset:2048
	ds_read_b128 v[162:165], v147 offset:3072
	ds_read_b128 v[166:169], v148
	ds_read_b128 v[170:173], v148 offset:1024
	ds_read_b128 v[174:177], v148 offset:2048
	ds_read_b128 v[178:181], v148 offset:3072
	s_add_i32 s70, s44, 2
	s_add_u32 s16, s42, 0x80
	s_addc_u32 s17, s43, 0
	s_cmp_eq_u32 s58, s44
	s_cselect_b32 s44, s0, s16
	s_cselect_b32 s45, s1, s17
	s_cselect_b32 s73, s41, s69
	s_cselect_b32 s72, s40, s68
	v_lshl_add_u64 v[198:199], s[42:43], 0, v[136:137]
	s_add_i32 m0, s50, 0xc000
	ds_read_b128 v[182:185], v149
	ds_read_b128 v[186:189], v149 offset:1024
	ds_read_b128 v[190:193], v149 offset:2048
	ds_read_b128 v[194:197], v149 offset:3072
	ds_read_b128 v[202:205], v149 offset:4096
	ds_read_b128 v[206:209], v149 offset:5120
	ds_read_b128 v[210:213], v149 offset:6144
	ds_read_b128 v[214:217], v149 offset:7168
	global_load_lds_dwordx4 v[198:199], off
	v_lshl_add_u64 v[198:199], s[42:43], 0, v[138:139]
	s_add_i32 m0, s50, 0xe000
	s_nop 0
	global_load_lds_dwordx4 v[198:199], off
	s_waitcnt vmcnt(8)
	s_waitcnt lgkmcnt(0)
	s_barrier
; #define PG8_STAGE(bufoff, gbase, voff) do { _Pragma("unroll") for (int _i = 0; _i < 2; ++_i) \
;         __builtin_amdgcn_global_load_lds((const unsigned*)((const char*)(gbase) + (voff)[_i]), (PG8_LAS unsigned*)(lds + (bufoff) + ldsw + _i * 8192), 16, 0, 0); } while (0)
; #define PG8_LDA(dst, b, h) do { _Pragma("unroll") for (int m = 0; m < 4; ++m) _Pragma("unroll") for (int k = 0; k < 2; ++k) dst[m][k] = *(const PG8_LAS bf16x8*)(lds + PG8_SA(b, h) + aoff + m * 2048 + k * 1024); } while (0)
; #define PG8_MMA(ai, bj, At, Bt) do { __builtin_amdgcn_s_setprio(1); _Pragma("unroll") for (int m = 0; m < 4; ++m) _Pragma("unroll") for (int n = 0; n < 2; ++n) _Pragma("unroll") for (int k = 0; k < 2; ++k) \
;         acc[ai][bj][m][n] = __builtin_amdgcn_mfma_f32_16x16x32_bf16(Bt[n][k], At[m][k], acc[ai][bj][m][n], 0, 0, 0); __builtin_amdgcn_s_setprio(0); } while (0)
; #define PG8_WAIT_V(n) asm volatile("s_waitcnt vmcnt(" #n ")" ::: "memory")
; #define PG8_WAIT_L(n) asm volatile("s_waitcnt lgkmcnt(" #n ")" ::: "memory")
; #define PG8_BAR __builtin_amdgcn_s_barrier()
; #define PG8_SCHED __builtin_amdgcn_sched_barrier(0)
; template <class Epi, class Sched, bool ALIGN_EPI = false, bool SP2 = false>
; __device__ __forceinline__ void gemm_phase(PG8_LAS unsigned char* lds, const Gemm g, const Sched& S, const Epi& E) {
;     ...
;             PG8_WAIT_V(8); PG8_WAIT_L(0); PG8_BAR; PG8_MMA(0, 0, At, B0); PG8_MMA(0, 1, At, B1); PG8_BAR; PG8_SCHED;
;             PG8_LDA(At, 0, 1); PG8_STAGE(PG8_SB(0, 0), b2, voffB); PG8_STAGE(PG8_SB(0, 1), b2 + hstep, voffB); PG8_STAGE(PG8_SA(0, 0), a2, voffA);
;             PG8_WAIT_V(8); PG8_WAIT_L(0); PG8_BAR; PG8_MMA(1, 0, At, B0); PG8_MMA(1, 1, At, B1); PG8_BAR; PG8_SCHED;
	s_setprio 1
	s_waitcnt lgkmcnt(0)
	v_mfma_f32_16x16x32_bf16 v[124:127], v[150:153], v[182:185], 0
	v_mfma_f32_16x16x32_bf16 v[116:119], v[158:161], v[182:185], 0
	v_mfma_f32_16x16x32_bf16 v[108:111], v[150:153], v[190:193], 0
	v_mfma_f32_16x16x32_bf16 v[100:103], v[158:161], v[190:193], 0
	v_mfma_f32_16x16x32_bf16 v[92:95], v[150:153], v[202:205], 0
	v_mfma_f32_16x16x32_bf16 v[84:87], v[158:161], v[202:205], 0
	v_mfma_f32_16x16x32_bf16 v[76:79], v[150:153], v[210:213], 0
	v_mfma_f32_16x16x32_bf16 v[68:71], v[158:161], v[210:213], 0
	v_mfma_f32_16x16x32_bf16 v[124:127], v[154:157], v[186:189], v[124:127]
	v_mfma_f32_16x16x32_bf16 v[116:119], v[162:165], v[186:189], v[116:119]
	v_mfma_f32_16x16x32_bf16 v[108:111], v[154:157], v[194:197], v[108:111]
	v_mfma_f32_16x16x32_bf16 v[100:103], v[162:165], v[194:197], v[100:103]
	v_mfma_f32_16x16x32_bf16 v[92:95], v[154:157], v[206:209], v[92:95]
	v_mfma_f32_16x16x32_bf16 v[84:87], v[162:165], v[206:209], v[84:87]
	v_mfma_f32_16x16x32_bf16 v[76:79], v[154:157], v[214:217], v[76:79]
	v_mfma_f32_16x16x32_bf16 v[68:71], v[162:165], v[214:217], v[68:71]
	s_setprio 0
	s_setprio 1
	v_mfma_f32_16x16x32_bf16 v[120:123], v[166:169], v[182:185], 0
	v_mfma_f32_16x16x32_bf16 v[112:115], v[174:177], v[182:185], 0
	v_mfma_f32_16x16x32_bf16 v[104:107], v[166:169], v[190:193], 0
	v_mfma_f32_16x16x32_bf16 v[96:99], v[174:177], v[190:193], 0
	v_mfma_f32_16x16x32_bf16 v[88:91], v[166:169], v[202:205], 0
	v_mfma_f32_16x16x32_bf16 v[80:83], v[174:177], v[202:205], 0
	v_mfma_f32_16x16x32_bf16 v[72:75], v[166:169], v[210:213], 0
	v_mfma_f32_16x16x32_bf16 v[64:67], v[174:177], v[210:213], 0
	v_mfma_f32_16x16x32_bf16 v[120:123], v[170:173], v[186:189], v[120:123]
	v_mfma_f32_16x16x32_bf16 v[112:115], v[178:181], v[186:189], v[112:115]
	v_mfma_f32_16x16x32_bf16 v[104:107], v[170:173], v[194:197], v[104:107]
	v_mfma_f32_16x16x32_bf16 v[96:99], v[178:181], v[194:197], v[96:99]
	v_mfma_f32_16x16x32_bf16 v[88:91], v[170:173], v[206:209], v[88:91]
	v_mfma_f32_16x16x32_bf16 v[80:83], v[178:181], v[206:209], v[80:83]
	v_mfma_f32_16x16x32_bf16 v[72:75], v[170:173], v[214:217], v[72:75]
	v_mfma_f32_16x16x32_bf16 v[64:67], v[178:181], v[214:217], v[64:67]
	s_setprio 0
	s_barrier
	s_add_i32 s16, s61, s47
	v_lshl_add_u64 v[198:199], s[72:73], 0, v[132:133]
	s_mov_b32 m0, s16
	ds_read_b128 v[182:185], v149 offset:16384
	ds_read_b128 v[186:189], v149 offset:17408
	ds_read_b128 v[190:193], v149 offset:18432
	ds_read_b128 v[194:197], v149 offset:19456
	ds_read_b128 v[202:205], v149 offset:20480
	ds_read_b128 v[206:209], v149 offset:21504
	ds_read_b128 v[210:213], v149 offset:22528
	ds_read_b128 v[214:217], v149 offset:23552
	global_load_lds_dwordx4 v[198:199], off
	s_add_i32 m0, s16, 0x2000
	v_lshl_add_u64 v[218:219], s[72:73], 0, v[128:129]
	s_add_u32 s72, s72, s10
	s_addc_u32 s73, s73, s11
	s_add_i32 s16, s62, s47
	global_load_lds_dwordx4 v[218:219], off
	v_lshl_add_u64 v[220:221], s[72:73], 0, v[132:133]
	s_mov_b32 m0, s16
	v_lshl_add_u64 v[222:223], s[72:73], 0, v[128:129]
	global_load_lds_dwordx4 v[220:221], off
	s_add_i32 m0, s16, 0x2000
	v_lshl_add_u64 v[224:225], s[44:45], 0, v[134:135]
	global_load_lds_dwordx4 v[222:223], off
	s_mov_b32 m0, s50
	v_lshl_add_u64 v[226:227], s[44:45], 0, v[130:131]
	global_load_lds_dwordx4 v[224:225], off
	s_mov_b32 m0, s51
	s_nop 0
	global_load_lds_dwordx4 v[226:227], off
	s_waitcnt vmcnt(8)
	s_waitcnt lgkmcnt(0)
	s_barrier
	s_setprio 1
	s_waitcnt lgkmcnt(0)
	v_mfma_f32_16x16x32_bf16 v[60:63], v[150:153], v[182:185], 0
	v_mfma_f32_16x16x32_bf16 v[52:55], v[158:161], v[182:185], 0
	v_mfma_f32_16x16x32_bf16 v[44:47], v[150:153], v[190:193], 0
	v_mfma_f32_16x16x32_bf16 v[36:39], v[158:161], v[190:193], 0
	v_mfma_f32_16x16x32_bf16 v[28:31], v[150:153], v[202:205], 0
	v_mfma_f32_16x16x32_bf16 v[20:23], v[158:161], v[202:205], 0
	v_mfma_f32_16x16x32_bf16 v[12:15], v[150:153], v[210:213], 0
	v_mfma_f32_16x16x32_bf16 v[4:7], v[158:161], v[210:213], 0
	v_mfma_f32_16x16x32_bf16 v[60:63], v[154:157], v[186:189], v[60:63]
	v_mfma_f32_16x16x32_bf16 v[52:55], v[162:165], v[186:189], v[52:55]
	v_mfma_f32_16x16x32_bf16 v[44:47], v[154:157], v[194:197], v[44:47]
	v_mfma_f32_16x16x32_bf16 v[36:39], v[162:165], v[194:197], v[36:39]
	v_mfma_f32_16x16x32_bf16 v[28:31], v[154:157], v[206:209], v[28:31]
	v_mfma_f32_16x16x32_bf16 v[20:23], v[162:165], v[206:209], v[20:23]
	v_mfma_f32_16x16x32_bf16 v[12:15], v[154:157], v[214:217], v[12:15]
	v_mfma_f32_16x16x32_bf16 v[4:7], v[162:165], v[214:217], v[4:7]
	s_setprio 0
	s_setprio 1
	v_mfma_f32_16x16x32_bf16 v[56:59], v[166:169], v[182:185], 0
	v_mfma_f32_16x16x32_bf16 v[48:51], v[174:177], v[182:185], 0
	v_mfma_f32_16x16x32_bf16 v[40:43], v[166:169], v[190:193], 0
	v_mfma_f32_16x16x32_bf16 v[32:35], v[174:177], v[190:193], 0
	v_mfma_f32_16x16x32_bf16 v[24:27], v[166:169], v[202:205], 0
	v_mfma_f32_16x16x32_bf16 v[16:19], v[174:177], v[202:205], 0
	v_mfma_f32_16x16x32_bf16 v[8:11], v[166:169], v[210:213], 0
	v_mfma_f32_16x16x32_bf16 v[0:3], v[174:177], v[210:213], 0
	v_mfma_f32_16x16x32_bf16 v[56:59], v[170:173], v[186:189], v[56:59]
	v_mfma_f32_16x16x32_bf16 v[48:51], v[178:181], v[186:189], v[48:51]
	v_mfma_f32_16x16x32_bf16 v[40:43], v[170:173], v[194:197], v[40:43]
	v_mfma_f32_16x16x32_bf16 v[32:35], v[178:181], v[194:197], v[32:35]
	v_mfma_f32_16x16x32_bf16 v[24:27], v[170:173], v[206:209], v[24:27]
	v_mfma_f32_16x16x32_bf16 v[16:19], v[178:181], v[206:209], v[16:19]
	v_mfma_f32_16x16x32_bf16 v[8:11], v[170:173], v[214:217], v[8:11]
	v_mfma_f32_16x16x32_bf16 v[0:3], v[178:181], v[214:217], v[0:3]
	s_setprio 0
	s_barrier
; #define PG8_STAGE(bufoff, gbase, voff) do { _Pragma("unroll") for (int _i = 0; _i < 2; ++_i) \
;         __builtin_amdgcn_global_load_lds((const unsigned*)((const char*)(gbase) + (voff)[_i]), (PG8_LAS unsigned*)(lds + (bufoff) + ldsw + _i * 8192), 16, 0, 0); } while (0)
; #define PG8_LDA(dst, b, h) do { _Pragma("unroll") for (int m = 0; m < 4; ++m) _Pragma("unroll") for (int k = 0; k < 2; ++k) dst[m][k] = *(const PG8_LAS bf16x8*)(lds + PG8_SA(b, h) + aoff + m * 2048 + k * 1024); } while (0)
; #define PG8_LDB(dst, b, h) do { _Pragma("unroll") for (int n = 0; n < 2; ++n) _Pragma("unroll") for (int k = 0; k < 2; ++k) dst[n][k] = *(const PG8_LAS bf16x8*)(lds + PG8_SB(b, h) + boff + n * 2048 + k * 1024); } while (0)
; #define PG8_MMA(ai, bj, At, Bt) do { __builtin_amdgcn_s_setprio(1); _Pragma("unroll") for (int m = 0; m < 4; ++m) _Pragma("unroll") for (int n = 0; n < 2; ++n) _Pragma("unroll") for (int k = 0; k < 2; ++k) \
;         acc[ai][bj][m][n] = __builtin_amdgcn_mfma_f32_16x16x32_bf16(Bt[n][k], At[m][k], acc[ai][bj][m][n], 0, 0, 0); __builtin_amdgcn_s_setprio(0); } while (0)
; #define PG8_WAIT_V(n) asm volatile("s_waitcnt vmcnt(" #n ")" ::: "memory")
; #define PG8_WAIT_L(n) asm volatile("s_waitcnt lgkmcnt(" #n ")" ::: "memory")
; #define PG8_BAR __builtin_amdgcn_s_barrier()
; #define PG8_SCHED __builtin_amdgcn_sched_barrier(0)
; template <class Epi, class Sched, bool ALIGN_EPI = false, bool SP2 = false>
; __device__ __forceinline__ void gemm_phase(PG8_LAS unsigned char* lds, const Gemm g, const Sched& S, const Epi& E) {
;     ...
;             PG8_LDB(B0, 1, 0); PG8_LDB(B1, 1, 1); PG8_SCHED; PG8_LDA(At, 1, 0); PG8_STAGE(PG8_SA(0, 1), a2 + hstep, voffA);
;             PG8_WAIT_V(8); PG8_WAIT_L(0); PG8_BAR; PG8_MMA(0, 0, At, B0); PG8_MMA(0, 1, At, B1); PG8_BAR; PG8_SCHED;
	s_add_i32 s16, 0, 0x18000
	s_add_i32 s17, 0, 0x1c000
	v_add_u32_e32 v162, s16, v145
	v_add_u32_e32 v178, s17, v145
	ds_read_b128 v[150:153], v162
	ds_read_b128 v[154:157], v162 offset:1024
	ds_read_b128 v[158:161], v162 offset:2048
	ds_read_b128 v[162:165], v162 offset:3072
	ds_read_b128 v[166:169], v178
	ds_read_b128 v[170:173], v178 offset:1024
	ds_read_b128 v[174:177], v178 offset:2048
	ds_read_b128 v[178:181], v178 offset:3072
	s_add_u32 s44, s44, s10
	s_addc_u32 s45, s45, s11
	s_mov_b32 m0, s52
	v_lshl_add_u64 v[228:229], s[44:45], 0, v[134:135]
	ds_read_b128 v[182:185], v149 offset:32768
	ds_read_b128 v[186:189], v149 offset:33792
	ds_read_b128 v[190:193], v149 offset:34816
	ds_read_b128 v[194:197], v149 offset:35840
	ds_read_b128 v[202:205], v149 offset:36864
	ds_read_b128 v[206:209], v149 offset:37888
	ds_read_b128 v[210:213], v149 offset:38912
	ds_read_b128 v[214:217], v149 offset:39936
	global_load_lds_dwordx4 v[228:229], off
	v_lshl_add_u64 v[228:229], s[44:45], 0, v[130:131]
	s_mov_b32 m0, s53
	s_nop 0
	global_load_lds_dwordx4 v[228:229], off
	s_waitcnt vmcnt(8)
	s_waitcnt lgkmcnt(0)
	s_barrier
	s_setprio 1
	s_waitcnt lgkmcnt(0)
	v_mfma_f32_16x16x32_bf16 v[124:127], v[150:153], v[182:185], v[124:127]
	v_mfma_f32_16x16x32_bf16 v[116:119], v[158:161], v[182:185], v[116:119]
	v_mfma_f32_16x16x32_bf16 v[108:111], v[150:153], v[190:193], v[108:111]
	v_mfma_f32_16x16x32_bf16 v[100:103], v[158:161], v[190:193], v[100:103]
	v_mfma_f32_16x16x32_bf16 v[92:95], v[150:153], v[202:205], v[92:95]
	v_mfma_f32_16x16x32_bf16 v[84:87], v[158:161], v[202:205], v[84:87]
	v_mfma_f32_16x16x32_bf16 v[76:79], v[150:153], v[210:213], v[76:79]
	v_mfma_f32_16x16x32_bf16 v[68:71], v[158:161], v[210:213], v[68:71]
	v_mfma_f32_16x16x32_bf16 v[124:127], v[154:157], v[186:189], v[124:127]
	v_mfma_f32_16x16x32_bf16 v[116:119], v[162:165], v[186:189], v[116:119]
	v_mfma_f32_16x16x32_bf16 v[108:111], v[154:157], v[194:197], v[108:111]
	v_mfma_f32_16x16x32_bf16 v[100:103], v[162:165], v[194:197], v[100:103]
	v_mfma_f32_16x16x32_bf16 v[92:95], v[154:157], v[206:209], v[92:95]
	v_mfma_f32_16x16x32_bf16 v[84:87], v[162:165], v[206:209], v[84:87]
	v_mfma_f32_16x16x32_bf16 v[76:79], v[154:157], v[214:217], v[76:79]
	v_mfma_f32_16x16x32_bf16 v[68:71], v[162:165], v[214:217], v[68:71]
	s_setprio 0
	s_setprio 1
	v_mfma_f32_16x16x32_bf16 v[120:123], v[166:169], v[182:185], v[120:123]
	v_mfma_f32_16x16x32_bf16 v[112:115], v[174:177], v[182:185], v[112:115]
	v_mfma_f32_16x16x32_bf16 v[104:107], v[166:169], v[190:193], v[104:107]
	v_mfma_f32_16x16x32_bf16 v[96:99], v[174:177], v[190:193], v[96:99]
	v_mfma_f32_16x16x32_bf16 v[88:91], v[166:169], v[202:205], v[88:91]
	v_mfma_f32_16x16x32_bf16 v[80:83], v[174:177], v[202:205], v[80:83]
	v_mfma_f32_16x16x32_bf16 v[72:75], v[166:169], v[210:213], v[72:75]
	v_mfma_f32_16x16x32_bf16 v[64:67], v[174:177], v[210:213], v[64:67]
	v_mfma_f32_16x16x32_bf16 v[120:123], v[170:173], v[186:189], v[120:123]
	v_mfma_f32_16x16x32_bf16 v[112:115], v[178:181], v[186:189], v[112:115]
	v_mfma_f32_16x16x32_bf16 v[104:107], v[170:173], v[194:197], v[104:107]
	v_mfma_f32_16x16x32_bf16 v[96:99], v[178:181], v[194:197], v[96:99]
	v_mfma_f32_16x16x32_bf16 v[88:91], v[170:173], v[206:209], v[88:91]
	v_mfma_f32_16x16x32_bf16 v[80:83], v[178:181], v[206:209], v[80:83]
	v_mfma_f32_16x16x32_bf16 v[72:75], v[170:173], v[214:217], v[72:75]
	v_mfma_f32_16x16x32_bf16 v[64:67], v[178:181], v[214:217], v[64:67]
	s_setprio 0
	s_barrier
; #define PG8_STAGE(bufoff, gbase, voff) do { _Pragma("unroll") for (int _i = 0; _i < 2; ++_i) \
;         __builtin_amdgcn_global_load_lds((const unsigned*)((const char*)(gbase) + (voff)[_i]), (PG8_LAS unsigned*)(lds + (bufoff) + ldsw + _i * 8192), 16, 0, 0); } while (0)
; #define PG8_LDA(dst, b, h) do { _Pragma("unroll") for (int m = 0; m < 4; ++m) _Pragma("unroll") for (int k = 0; k < 2; ++k) dst[m][k] = *(const PG8_LAS bf16x8*)(lds + PG8_SA(b, h) + aoff + m * 2048 + k * 1024); } while (0)
; #define PG8_MMA(ai, bj, At, Bt) do { __builtin_amdgcn_s_setprio(1); _Pragma("unroll") for (int m = 0; m < 4; ++m) _Pragma("unroll") for (int n = 0; n < 2; ++n) _Pragma("unroll") for (int k = 0; k < 2; ++k) \
;         acc[ai][bj][m][n] = __builtin_amdgcn_mfma_f32_16x16x32_bf16(Bt[n][k], At[m][k], acc[ai][bj][m][n], 0, 0, 0); __builtin_amdgcn_s_setprio(0); } while (0)
; #define PG8_WAIT_V(n) asm volatile("s_waitcnt vmcnt(" #n ")" ::: "memory")
; #define PG8_WAIT_L(n) asm volatile("s_waitcnt lgkmcnt(" #n ")" ::: "memory")
; #define PG8_BAR __builtin_amdgcn_s_barrier()
; #define PG8_SCHED __builtin_amdgcn_sched_barrier(0)
; template <class Epi, class Sched, bool ALIGN_EPI = false, bool SP2 = false>
; __device__ __forceinline__ void gemm_phase(PG8_LAS unsigned char* lds, const Gemm g, const Sched& S, const Epi& E) {
;     ...
;         for (int t = 0; t < nt; t += 2) {
;             const bool last = (t == nt - 2);
;     ...
;             PG8_LDA(At, 1, 1); PG8_STAGE(PG8_SB(1, 0), b3, voffB); PG8_STAGE(PG8_SB(1, 1), b3 + hstep, voffB); PG8_STAGE(PG8_SA(1, 0), a3, voffA);
;             PG8_WAIT_V(8); PG8_WAIT_L(0); PG8_BAR; PG8_MMA(1, 0, At, B0); PG8_MMA(1, 1, At, B1); PG8_BAR; PG8_SCHED;
	s_add_i32 s16, s16, s47
	v_lshl_add_u64 v[198:199], v[198:199], 0, s[36:37]
	s_mov_b32 m0, s16
	ds_read_b128 v[182:185], v149 offset:49152
	ds_read_b128 v[186:189], v149 offset:50176
	ds_read_b128 v[190:193], v149 offset:51200
	ds_read_b128 v[194:197], v149 offset:52224
	ds_read_b128 v[202:205], v149 offset:53248
	ds_read_b128 v[206:209], v149 offset:54272
	ds_read_b128 v[210:213], v149 offset:55296
	ds_read_b128 v[214:217], v149 offset:56320
	global_load_lds_dwordx4 v[198:199], off
	v_lshl_add_u64 v[198:199], v[218:219], 0, s[36:37]
	s_add_i32 m0, s16, 0x2000
	s_add_i32 s16, s17, s47
	global_load_lds_dwordx4 v[198:199], off
	v_lshl_add_u64 v[198:199], v[220:221], 0, s[36:37]
	s_mov_b32 m0, s16
	s_nop 0
	global_load_lds_dwordx4 v[198:199], off
	v_lshl_add_u64 v[198:199], v[222:223], 0, s[36:37]
	s_add_i32 m0, s16, 0x2000
	s_nop 0
	global_load_lds_dwordx4 v[198:199], off
	v_lshl_add_u64 v[198:199], v[224:225], 0, s[36:37]
	s_mov_b32 m0, s55
	s_nop 0
	global_load_lds_dwordx4 v[198:199], off
	v_lshl_add_u64 v[198:199], v[226:227], 0, s[36:37]
	s_mov_b32 m0, s56
	s_nop 0
	global_load_lds_dwordx4 v[198:199], off
	s_waitcnt vmcnt(8)
	s_waitcnt lgkmcnt(0)
	s_barrier
	s_setprio 1
	s_waitcnt lgkmcnt(0)
	v_mfma_f32_16x16x32_bf16 v[60:63], v[150:153], v[182:185], v[60:63]
	v_mfma_f32_16x16x32_bf16 v[52:55], v[158:161], v[182:185], v[52:55]
	v_mfma_f32_16x16x32_bf16 v[44:47], v[150:153], v[190:193], v[44:47]
	v_mfma_f32_16x16x32_bf16 v[36:39], v[158:161], v[190:193], v[36:39]
	v_mfma_f32_16x16x32_bf16 v[28:31], v[150:153], v[202:205], v[28:31]
	v_mfma_f32_16x16x32_bf16 v[20:23], v[158:161], v[202:205], v[20:23]
	v_mfma_f32_16x16x32_bf16 v[12:15], v[150:153], v[210:213], v[12:15]
	v_mfma_f32_16x16x32_bf16 v[4:7], v[158:161], v[210:213], v[4:7]
	v_mfma_f32_16x16x32_bf16 v[60:63], v[154:157], v[186:189], v[60:63]
	v_mfma_f32_16x16x32_bf16 v[52:55], v[162:165], v[186:189], v[52:55]
	v_mfma_f32_16x16x32_bf16 v[44:47], v[154:157], v[194:197], v[44:47]
	v_mfma_f32_16x16x32_bf16 v[36:39], v[162:165], v[194:197], v[36:39]
	v_mfma_f32_16x16x32_bf16 v[28:31], v[154:157], v[206:209], v[28:31]
	v_mfma_f32_16x16x32_bf16 v[20:23], v[162:165], v[206:209], v[20:23]
	v_mfma_f32_16x16x32_bf16 v[12:15], v[154:157], v[214:217], v[12:15]
	v_mfma_f32_16x16x32_bf16 v[4:7], v[162:165], v[214:217], v[4:7]
	s_setprio 0
	s_setprio 1
	v_mfma_f32_16x16x32_bf16 v[56:59], v[166:169], v[182:185], v[56:59]
	v_mfma_f32_16x16x32_bf16 v[48:51], v[174:177], v[182:185], v[48:51]
	v_mfma_f32_16x16x32_bf16 v[40:43], v[166:169], v[190:193], v[40:43]
	v_mfma_f32_16x16x32_bf16 v[32:35], v[174:177], v[190:193], v[32:35]
	v_mfma_f32_16x16x32_bf16 v[24:27], v[166:169], v[202:205], v[24:27]
	v_mfma_f32_16x16x32_bf16 v[16:19], v[174:177], v[202:205], v[16:19]
	v_mfma_f32_16x16x32_bf16 v[8:11], v[166:169], v[210:213], v[8:11]
	v_mfma_f32_16x16x32_bf16 v[0:3], v[174:177], v[210:213], v[0:3]
	v_mfma_f32_16x16x32_bf16 v[56:59], v[170:173], v[186:189], v[56:59]
	v_mfma_f32_16x16x32_bf16 v[48:51], v[178:181], v[186:189], v[48:51]
	v_mfma_f32_16x16x32_bf16 v[40:43], v[170:173], v[194:197], v[40:43]
	v_mfma_f32_16x16x32_bf16 v[32:35], v[178:181], v[194:197], v[32:35]
	v_mfma_f32_16x16x32_bf16 v[24:27], v[170:173], v[206:209], v[24:27]
	v_mfma_f32_16x16x32_bf16 v[16:19], v[178:181], v[206:209], v[16:19]
	v_mfma_f32_16x16x32_bf16 v[8:11], v[170:173], v[214:217], v[8:11]
	v_mfma_f32_16x16x32_bf16 v[0:3], v[178:181], v[214:217], v[0:3]
	s_setprio 0
	s_barrier
	s_add_u32 s42, s42, 0x100
	s_addc_u32 s43, s43, 0
	s_add_u32 s68, s68, 0x100
	s_addc_u32 s69, s69, 0
	s_cmp_ge_i32 s70, s57
	s_mov_b32 s44, s70
	s_cbranch_scc1 .LBB0_1022

; #define PG8_STAGE(bufoff, gbase, voff) do { _Pragma("unroll") for (int _i = 0; _i < 2; ++_i) \
;         __builtin_amdgcn_global_load_lds((const unsigned*)((const char*)(gbase) + (voff)[_i]), (PG8_LAS unsigned*)(lds + (bufoff) + ldsw + _i * 8192), 16, 0, 0); } while (0)
; #define PG8_LDA(dst, b, h) do { _Pragma("unroll") for (int m = 0; m < 4; ++m) _Pragma("unroll") for (int k = 0; k < 2; ++k) dst[m][k] = *(const PG8_LAS bf16x8*)(lds + PG8_SA(b, h) + aoff + m * 2048 + k * 1024); } while (0)
; #define PG8_LDB(dst, b, h) do { _Pragma("unroll") for (int n = 0; n < 2; ++n) _Pragma("unroll") for (int k = 0; k < 2; ++k) dst[n][k] = *(const PG8_LAS bf16x8*)(lds + PG8_SB(b, h) + boff + n * 2048 + k * 1024); } while (0)
; #define PG8_MMA(ai, bj, At, Bt) do { __builtin_amdgcn_s_setprio(1); _Pragma("unroll") for (int m = 0; m < 4; ++m) _Pragma("unroll") for (int n = 0; n < 2; ++n) _Pragma("unroll") for (int k = 0; k < 2; ++k) \
;         acc[ai][bj][m][n] = __builtin_amdgcn_mfma_f32_16x16x32_bf16(Bt[n][k], At[m][k], acc[ai][bj][m][n], 0, 0, 0); __builtin_amdgcn_s_setprio(0); } while (0)
; #define PG8_WAIT_V(n) asm volatile("s_waitcnt vmcnt(" #n ")" ::: "memory")
; #define PG8_BAR __builtin_amdgcn_s_barrier()
; template <class Epi, class Sched, bool ALIGN_EPI = false, bool SP2 = false>
; __device__ __forceinline__ void gemm_phase(PG8_LAS unsigned char* lds, const Gemm g, const Sched& S, const Epi& E) {
;     ...
;         for (int t = 0; t < nt; t += 2) {
;             const bool last = (t == nt - 2);
;             const char* a1 = cA + (size_t)(t + 1) * kstep;
;             const char* a2 = last ? nA : cA + (size_t)(t + 2) * kstep; const char* b2 = last ? nB : cB + (size_t)(t + 2) * kstep;
;             const char* a3 = a2 + kstep; const char* b3 = b2 + kstep;
;             if (last && has_next) S.a_ready(nxt);
;             if constexpr (SP2) {
;             PG8_LDB(B0, 0, 0); PG8_LDB(B1, 0, 1); PG8_SCHED; PG8_LDA(At, 0, 0); PG8_STAGE(PG8_SA(1, 1), a1 + hstep, voffA);
;             PG8_WAIT_V(8); PG8_WAIT_L(0); PG8_BAR; PG8_MMA(0, 0, At, B0); PG8_MMA(0, 1, At, B1); PG8_BAR; PG8_SCHED;
;     ...
; #pragma unroll
;         for (int a = 0; a < 2; ++a)
; #pragma unroll
;             for (int b = 0; b < 2; ++b)
; #pragma unroll
;                 for (int m = 0; m < 4; ++m)
; #pragma unroll
;                     for (int n = 0; n < 2; ++n) acc[a][b][m][n] = (f32x4){0.f, 0.f, 0.f, 0.f};
.LBB0_1102:
	s_andn2_b64 vcc, exec, s[38:39]
	s_waitcnt lgkmcnt(0)
	s_cbranch_vccz .Lcz_go_1104
	v_mov_b32_e32 v127, 0
	v_mov_b32_e32 v126, v127
	v_mov_b32_e32 v125, v127
	v_mov_b32_e32 v124, v127
	v_mov_b32_e32 v123, v127
	v_mov_b32_e32 v122, v127
	v_mov_b32_e32 v121, v127
	v_mov_b32_e32 v120, v127
	v_mov_b32_e32 v111, v127
	v_mov_b32_e32 v110, v127
	v_mov_b32_e32 v109, v127
	v_mov_b32_e32 v108, v127
	v_mov_b32_e32 v107, v127
	v_mov_b32_e32 v106, v127
	v_mov_b32_e32 v105, v127
	v_mov_b32_e32 v104, v127
	v_mov_b32_e32 v95, v127
	v_mov_b32_e32 v94, v127
	v_mov_b32_e32 v93, v127
	v_mov_b32_e32 v92, v127
	v_mov_b32_e32 v91, v127
	v_mov_b32_e32 v90, v127
	v_mov_b32_e32 v89, v127
	v_mov_b32_e32 v88, v127
	v_mov_b32_e32 v79, v127
	v_mov_b32_e32 v78, v127
	v_mov_b32_e32 v77, v127
	v_mov_b32_e32 v76, v127
	v_mov_b32_e32 v75, v127
	v_mov_b32_e32 v74, v127
	v_mov_b32_e32 v73, v127
	v_mov_b32_e32 v72, v127
	v_mov_b32_e32 v119, v127
	v_mov_b32_e32 v118, v127
	v_mov_b32_e32 v117, v127
	v_mov_b32_e32 v116, v127
	v_mov_b32_e32 v115, v127
	v_mov_b32_e32 v114, v127
	v_mov_b32_e32 v113, v127
	v_mov_b32_e32 v112, v127
	v_mov_b32_e32 v103, v127
	v_mov_b32_e32 v102, v127
	v_mov_b32_e32 v101, v127
	v_mov_b32_e32 v100, v127
	v_mov_b32_e32 v99, v127
	v_mov_b32_e32 v98, v127
	v_mov_b32_e32 v97, v127
	v_mov_b32_e32 v96, v127
	v_mov_b32_e32 v87, v127
	v_mov_b32_e32 v86, v127
	v_mov_b32_e32 v85, v127
	v_mov_b32_e32 v84, v127
	v_mov_b32_e32 v83, v127
	v_mov_b32_e32 v82, v127
	v_mov_b32_e32 v81, v127
	v_mov_b32_e32 v80, v127
	v_mov_b32_e32 v71, v127
	v_mov_b32_e32 v70, v127
	v_mov_b32_e32 v69, v127
	v_mov_b32_e32 v68, v127
	v_mov_b32_e32 v67, v127
	v_mov_b32_e32 v66, v127
	v_mov_b32_e32 v65, v127
	v_mov_b32_e32 v64, v127
	v_mov_b32_e32 v63, v127
	v_mov_b32_e32 v62, v127
	v_mov_b32_e32 v61, v127
	v_mov_b32_e32 v60, v127
	v_mov_b32_e32 v59, v127
	v_mov_b32_e32 v58, v127
	v_mov_b32_e32 v57, v127
	v_mov_b32_e32 v56, v127
	v_mov_b32_e32 v47, v127
	v_mov_b32_e32 v46, v127
	v_mov_b32_e32 v45, v127
	v_mov_b32_e32 v44, v127
	v_mov_b32_e32 v43, v127
	v_mov_b32_e32 v42, v127
	v_mov_b32_e32 v41, v127
	v_mov_b32_e32 v40, v127
	v_mov_b32_e32 v31, v127
	v_mov_b32_e32 v30, v127
	v_mov_b32_e32 v29, v127
	v_mov_b32_e32 v28, v127
	v_mov_b32_e32 v27, v127
	v_mov_b32_e32 v26, v127
	v_mov_b32_e32 v25, v127
	v_mov_b32_e32 v24, v127
	v_mov_b32_e32 v15, v127
	v_mov_b32_e32 v14, v127
	v_mov_b32_e32 v13, v127
	v_mov_b32_e32 v12, v127
	v_mov_b32_e32 v11, v127
	v_mov_b32_e32 v10, v127
	v_mov_b32_e32 v9, v127
	v_mov_b32_e32 v8, v127
	v_mov_b32_e32 v55, v127
	v_mov_b32_e32 v54, v127
	v_mov_b32_e32 v53, v127
	v_mov_b32_e32 v52, v127
	v_mov_b32_e32 v51, v127
	v_mov_b32_e32 v50, v127
	v_mov_b32_e32 v49, v127
	v_mov_b32_e32 v48, v127
	v_mov_b32_e32 v39, v127
	v_mov_b32_e32 v38, v127
	v_mov_b32_e32 v37, v127
	v_mov_b32_e32 v36, v127
	v_mov_b32_e32 v35, v127
	v_mov_b32_e32 v34, v127
	v_mov_b32_e32 v33, v127
	v_mov_b32_e32 v32, v127
	v_mov_b32_e32 v23, v127
	v_mov_b32_e32 v22, v127
	v_mov_b32_e32 v21, v127
	v_mov_b32_e32 v20, v127
	v_mov_b32_e32 v19, v127
	v_mov_b32_e32 v18, v127
	v_mov_b32_e32 v17, v127
	v_mov_b32_e32 v16, v127
	v_mov_b32_e32 v7, v127
	v_mov_b32_e32 v6, v127
	v_mov_b32_e32 v5, v127
	v_mov_b32_e32 v4, v127
	v_mov_b32_e32 v3, v127
	v_mov_b32_e32 v2, v127
	v_mov_b32_e32 v1, v127
	v_mov_b32_e32 v0, v127
	s_branch .LBB0_1105
.Lcz_go_1104:
	s_add_u32 s44, s44, 0x8000
	s_addc_u32 s45, s45, 0
	s_add_u32 s68, s46, 0x100
	s_addc_u32 s69, s47, 0
	s_mov_b32 s46, 0
	ds_read_b128 v[144:147], v151
	ds_read_b128 v[156:159], v151 offset:1024
	ds_read_b128 v[160:163], v151 offset:2048
	ds_read_b128 v[164:167], v151 offset:3072
	ds_read_b128 v[168:171], v152
	ds_read_b128 v[172:175], v152 offset:1024
	ds_read_b128 v[176:179], v152 offset:2048
	ds_read_b128 v[180:183], v152 offset:3072
	s_add_i32 s70, s46, 2
	s_add_u32 s16, s44, 0x8000
	s_addc_u32 s17, s45, 0
	s_cmp_eq_u32 s58, s46
	s_cselect_b32 s46, s0, s16
	s_cselect_b32 s47, s1, s17
	s_cselect_b32 s73, s43, s69
	s_cselect_b32 s72, s42, s68
	v_lshl_add_u64 v[218:219], s[44:45], 0, v[136:137]
	s_add_i32 m0, s50, 0xc000
	ds_read_b128 v[184:187], v153
	ds_read_b128 v[188:191], v153 offset:1024
	ds_read_b128 v[192:195], v153 offset:2048
	ds_read_b128 v[196:199], v153 offset:3072
	ds_read_b128 v[202:205], v153 offset:4096
	ds_read_b128 v[206:209], v153 offset:5120
	ds_read_b128 v[210:213], v153 offset:6144
	ds_read_b128 v[214:217], v153 offset:7168
	global_load_lds_dwordx4 v[218:219], off
	v_lshl_add_u64 v[218:219], s[44:45], 0, v[138:139]
	s_add_i32 m0, s50, 0xe000
	s_nop 0
	global_load_lds_dwordx4 v[218:219], off
	s_waitcnt vmcnt(8)
	s_waitcnt lgkmcnt(0)
	s_barrier
; #define PG8_STAGE(bufoff, gbase, voff) do { _Pragma("unroll") for (int _i = 0; _i < 2; ++_i) \
;         __builtin_amdgcn_global_load_lds((const unsigned*)((const char*)(gbase) + (voff)[_i]), (PG8_LAS unsigned*)(lds + (bufoff) + ldsw + _i * 8192), 16, 0, 0); } while (0)
; #define PG8_LDA(dst, b, h) do { _Pragma("unroll") for (int m = 0; m < 4; ++m) _Pragma("unroll") for (int k = 0; k < 2; ++k) dst[m][k] = *(const PG8_LAS bf16x8*)(lds + PG8_SA(b, h) + aoff + m * 2048 + k * 1024); } while (0)
; #define PG8_MMA(ai, bj, At, Bt) do { __builtin_amdgcn_s_setprio(1); _Pragma("unroll") for (int m = 0; m < 4; ++m) _Pragma("unroll") for (int n = 0; n < 2; ++n) _Pragma("unroll") for (int k = 0; k < 2; ++k) \
;         acc[ai][bj][m][n] = __builtin_amdgcn_mfma_f32_16x16x32_bf16(Bt[n][k], At[m][k], acc[ai][bj][m][n], 0, 0, 0); __builtin_amdgcn_s_setprio(0); } while (0)
; #define PG8_WAIT_V(n) asm volatile("s_waitcnt vmcnt(" #n ")" ::: "memory")
; #define PG8_WAIT_L(n) asm volatile("s_waitcnt lgkmcnt(" #n ")" ::: "memory")
; #define PG8_BAR __builtin_amdgcn_s_barrier()
; #define PG8_SCHED __builtin_amdgcn_sched_barrier(0)
; template <class Epi, class Sched, bool ALIGN_EPI = false, bool SP2 = false>
; __device__ __forceinline__ void gemm_phase(PG8_LAS unsigned char* lds, const Gemm g, const Sched& S, const Epi& E) {
;     ...
;             PG8_WAIT_V(8); PG8_WAIT_L(0); PG8_BAR; PG8_MMA(0, 0, At, B0); PG8_MMA(0, 1, At, B1); PG8_BAR; PG8_SCHED;
;             PG8_LDA(At, 0, 1); PG8_STAGE(PG8_SB(0, 0), b2, voffB); PG8_STAGE(PG8_SB(0, 1), b2 + hstep, voffB); PG8_STAGE(PG8_SA(0, 0), a2, voffA);
;             PG8_WAIT_V(8); PG8_WAIT_L(0); PG8_BAR; PG8_MMA(1, 0, At, B0); PG8_MMA(1, 1, At, B1); PG8_BAR; PG8_SCHED;
	s_setprio 1
	s_waitcnt lgkmcnt(0)
	v_mfma_f32_16x16x32_bf16 v[124:127], v[144:147], v[184:187], 0
	v_mfma_f32_16x16x32_bf16 v[120:123], v[160:163], v[184:187], 0
	v_mfma_f32_16x16x32_bf16 v[108:111], v[144:147], v[192:195], 0
	v_mfma_f32_16x16x32_bf16 v[104:107], v[160:163], v[192:195], 0
	v_mfma_f32_16x16x32_bf16 v[92:95], v[144:147], v[202:205], 0
	v_mfma_f32_16x16x32_bf16 v[88:91], v[160:163], v[202:205], 0
	v_mfma_f32_16x16x32_bf16 v[76:79], v[144:147], v[210:213], 0
	v_mfma_f32_16x16x32_bf16 v[72:75], v[160:163], v[210:213], 0
	v_mfma_f32_16x16x32_bf16 v[124:127], v[156:159], v[188:191], v[124:127]
	v_mfma_f32_16x16x32_bf16 v[120:123], v[164:167], v[188:191], v[120:123]
	v_mfma_f32_16x16x32_bf16 v[108:111], v[156:159], v[196:199], v[108:111]
	v_mfma_f32_16x16x32_bf16 v[104:107], v[164:167], v[196:199], v[104:107]
	v_mfma_f32_16x16x32_bf16 v[92:95], v[156:159], v[206:209], v[92:95]
	v_mfma_f32_16x16x32_bf16 v[88:91], v[164:167], v[206:209], v[88:91]
	v_mfma_f32_16x16x32_bf16 v[76:79], v[156:159], v[214:217], v[76:79]
	v_mfma_f32_16x16x32_bf16 v[72:75], v[164:167], v[214:217], v[72:75]
	s_setprio 0
	s_setprio 1
	v_mfma_f32_16x16x32_bf16 v[116:119], v[168:171], v[184:187], 0
	v_mfma_f32_16x16x32_bf16 v[112:115], v[176:179], v[184:187], 0
	v_mfma_f32_16x16x32_bf16 v[100:103], v[168:171], v[192:195], 0
	v_mfma_f32_16x16x32_bf16 v[96:99], v[176:179], v[192:195], 0
	v_mfma_f32_16x16x32_bf16 v[84:87], v[168:171], v[202:205], 0
	v_mfma_f32_16x16x32_bf16 v[80:83], v[176:179], v[202:205], 0
	v_mfma_f32_16x16x32_bf16 v[68:71], v[168:171], v[210:213], 0
	v_mfma_f32_16x16x32_bf16 v[64:67], v[176:179], v[210:213], 0
	v_mfma_f32_16x16x32_bf16 v[116:119], v[172:175], v[188:191], v[116:119]
	v_mfma_f32_16x16x32_bf16 v[112:115], v[180:183], v[188:191], v[112:115]
	v_mfma_f32_16x16x32_bf16 v[100:103], v[172:175], v[196:199], v[100:103]
	v_mfma_f32_16x16x32_bf16 v[96:99], v[180:183], v[196:199], v[96:99]
	v_mfma_f32_16x16x32_bf16 v[84:87], v[172:175], v[206:209], v[84:87]
	v_mfma_f32_16x16x32_bf16 v[80:83], v[180:183], v[206:209], v[80:83]
	v_mfma_f32_16x16x32_bf16 v[68:71], v[172:175], v[214:217], v[68:71]
	v_mfma_f32_16x16x32_bf16 v[64:67], v[180:183], v[214:217], v[64:67]
	s_setprio 0
	s_barrier
	s_add_i32 s16, s62, s49
	v_lshl_add_u64 v[218:219], s[72:73], 0, v[130:131]
	s_mov_b32 m0, s16
	ds_read_b128 v[184:187], v153 offset:16384
	ds_read_b128 v[188:191], v153 offset:17408
	ds_read_b128 v[192:195], v153 offset:18432
	ds_read_b128 v[196:199], v153 offset:19456
	ds_read_b128 v[202:205], v153 offset:20480
	ds_read_b128 v[206:209], v153 offset:21504
	ds_read_b128 v[210:213], v153 offset:22528
	ds_read_b128 v[214:217], v153 offset:23552
	global_load_lds_dwordx4 v[218:219], off
	s_add_i32 m0, s16, 0x2000
	v_lshl_add_u64 v[220:221], s[72:73], 0, v[134:135]
	s_add_u32 s72, s72, s8
	s_addc_u32 s73, s73, s9
	s_add_i32 s16, s63, s49
	global_load_lds_dwordx4 v[220:221], off
	v_lshl_add_u64 v[222:223], s[72:73], 0, v[130:131]
	s_mov_b32 m0, s16
	v_lshl_add_u64 v[224:225], s[72:73], 0, v[134:135]
	global_load_lds_dwordx4 v[222:223], off
	s_add_i32 m0, s16, 0x2000
	v_lshl_add_u64 v[226:227], s[46:47], 0, v[128:129]
	global_load_lds_dwordx4 v[224:225], off
	s_mov_b32 m0, s50
	v_lshl_add_u64 v[228:229], s[46:47], 0, v[132:133]
	global_load_lds_dwordx4 v[226:227], off
	s_mov_b32 m0, s51
	s_nop 0
	global_load_lds_dwordx4 v[228:229], off
	s_waitcnt vmcnt(8)
	s_waitcnt lgkmcnt(0)
	s_barrier
	s_setprio 1
	s_waitcnt lgkmcnt(0)
	v_mfma_f32_16x16x32_bf16 v[60:63], v[144:147], v[184:187], 0
	v_mfma_f32_16x16x32_bf16 v[56:59], v[160:163], v[184:187], 0
	v_mfma_f32_16x16x32_bf16 v[44:47], v[144:147], v[192:195], 0
	v_mfma_f32_16x16x32_bf16 v[40:43], v[160:163], v[192:195], 0
	v_mfma_f32_16x16x32_bf16 v[28:31], v[144:147], v[202:205], 0
	v_mfma_f32_16x16x32_bf16 v[24:27], v[160:163], v[202:205], 0
	v_mfma_f32_16x16x32_bf16 v[12:15], v[144:147], v[210:213], 0
	v_mfma_f32_16x16x32_bf16 v[8:11], v[160:163], v[210:213], 0
	v_mfma_f32_16x16x32_bf16 v[60:63], v[156:159], v[188:191], v[60:63]
	v_mfma_f32_16x16x32_bf16 v[56:59], v[164:167], v[188:191], v[56:59]
	v_mfma_f32_16x16x32_bf16 v[44:47], v[156:159], v[196:199], v[44:47]
	v_mfma_f32_16x16x32_bf16 v[40:43], v[164:167], v[196:199], v[40:43]
	v_mfma_f32_16x16x32_bf16 v[28:31], v[156:159], v[206:209], v[28:31]
	v_mfma_f32_16x16x32_bf16 v[24:27], v[164:167], v[206:209], v[24:27]
	v_mfma_f32_16x16x32_bf16 v[12:15], v[156:159], v[214:217], v[12:15]
	v_mfma_f32_16x16x32_bf16 v[8:11], v[164:167], v[214:217], v[8:11]
	s_setprio 0
	s_setprio 1
	v_mfma_f32_16x16x32_bf16 v[52:55], v[168:171], v[184:187], 0
	v_mfma_f32_16x16x32_bf16 v[48:51], v[176:179], v[184:187], 0
	v_mfma_f32_16x16x32_bf16 v[36:39], v[168:171], v[192:195], 0
	v_mfma_f32_16x16x32_bf16 v[32:35], v[176:179], v[192:195], 0
	v_mfma_f32_16x16x32_bf16 v[20:23], v[168:171], v[202:205], 0
	v_mfma_f32_16x16x32_bf16 v[16:19], v[176:179], v[202:205], 0
	v_mfma_f32_16x16x32_bf16 v[4:7], v[168:171], v[210:213], 0
	v_mfma_f32_16x16x32_bf16 v[0:3], v[176:179], v[210:213], 0
	v_mfma_f32_16x16x32_bf16 v[52:55], v[172:175], v[188:191], v[52:55]
	v_mfma_f32_16x16x32_bf16 v[48:51], v[180:183], v[188:191], v[48:51]
	v_mfma_f32_16x16x32_bf16 v[36:39], v[172:175], v[196:199], v[36:39]
	v_mfma_f32_16x16x32_bf16 v[32:35], v[180:183], v[196:199], v[32:35]
	v_mfma_f32_16x16x32_bf16 v[20:23], v[172:175], v[206:209], v[20:23]
	v_mfma_f32_16x16x32_bf16 v[16:19], v[180:183], v[206:209], v[16:19]
	v_mfma_f32_16x16x32_bf16 v[4:7], v[172:175], v[214:217], v[4:7]
	v_mfma_f32_16x16x32_bf16 v[0:3], v[180:183], v[214:217], v[0:3]
	s_setprio 0
	s_barrier
; #define PG8_STAGE(bufoff, gbase, voff) do { _Pragma("unroll") for (int _i = 0; _i < 2; ++_i) \
;         __builtin_amdgcn_global_load_lds((const unsigned*)((const char*)(gbase) + (voff)[_i]), (PG8_LAS unsigned*)(lds + (bufoff) + ldsw + _i * 8192), 16, 0, 0); } while (0)
; #define PG8_LDA(dst, b, h) do { _Pragma("unroll") for (int m = 0; m < 4; ++m) _Pragma("unroll") for (int k = 0; k < 2; ++k) dst[m][k] = *(const PG8_LAS bf16x8*)(lds + PG8_SA(b, h) + aoff + m * 2048 + k * 1024); } while (0)
; #define PG8_LDB(dst, b, h) do { _Pragma("unroll") for (int n = 0; n < 2; ++n) _Pragma("unroll") for (int k = 0; k < 2; ++k) dst[n][k] = *(const PG8_LAS bf16x8*)(lds + PG8_SB(b, h) + boff + n * 2048 + k * 1024); } while (0)
; #define PG8_MMA(ai, bj, At, Bt) do { __builtin_amdgcn_s_setprio(1); _Pragma("unroll") for (int m = 0; m < 4; ++m) _Pragma("unroll") for (int n = 0; n < 2; ++n) _Pragma("unroll") for (int k = 0; k < 2; ++k) \
;         acc[ai][bj][m][n] = __builtin_amdgcn_mfma_f32_16x16x32_bf16(Bt[n][k], At[m][k], acc[ai][bj][m][n], 0, 0, 0); __builtin_amdgcn_s_setprio(0); } while (0)
; #define PG8_WAIT_V(n) asm volatile("s_waitcnt vmcnt(" #n ")" ::: "memory")
; #define PG8_WAIT_L(n) asm volatile("s_waitcnt lgkmcnt(" #n ")" ::: "memory")
; #define PG8_BAR __builtin_amdgcn_s_barrier()
; #define PG8_SCHED __builtin_amdgcn_sched_barrier(0)
; template <class Epi, class Sched, bool ALIGN_EPI = false, bool SP2 = false>
; __device__ __forceinline__ void gemm_phase(PG8_LAS unsigned char* lds, const Gemm g, const Sched& S, const Epi& E) {
;     ...
;             PG8_LDB(B0, 1, 0); PG8_LDB(B1, 1, 1); PG8_SCHED; PG8_LDA(At, 1, 0); PG8_STAGE(PG8_SA(0, 1), a2 + hstep, voffA);
;             PG8_WAIT_V(8); PG8_WAIT_L(0); PG8_BAR; PG8_MMA(0, 0, At, B0); PG8_MMA(0, 1, At, B1); PG8_BAR; PG8_SCHED;
	s_add_i32 s16, 0, 0x18000
	v_add_u32_e32 v155, s16, v149
	s_add_i32 s17, 0, 0x1c000
	ds_read_b128 v[144:147], v155
	ds_read_b128 v[156:159], v155 offset:1024
	ds_read_b128 v[160:163], v155 offset:2048
	ds_read_b128 v[164:167], v155 offset:3072
	v_add_u32_e32 v155, s17, v149
	ds_read_b128 v[168:171], v155
	ds_read_b128 v[172:175], v155 offset:1024
	ds_read_b128 v[176:179], v155 offset:2048
	ds_read_b128 v[180:183], v155 offset:3072
	s_add_u32 s46, s46, 0x2000
	s_addc_u32 s47, s47, 0
	s_mov_b32 m0, s52
	v_lshl_add_u64 v[230:231], s[46:47], 0, v[128:129]
	ds_read_b128 v[184:187], v153 offset:32768
	ds_read_b128 v[188:191], v153 offset:33792
	ds_read_b128 v[192:195], v153 offset:34816
	ds_read_b128 v[196:199], v153 offset:35840
	ds_read_b128 v[202:205], v153 offset:36864
	ds_read_b128 v[206:209], v153 offset:37888
	ds_read_b128 v[210:213], v153 offset:38912
	ds_read_b128 v[214:217], v153 offset:39936
	global_load_lds_dwordx4 v[230:231], off
	v_lshl_add_u64 v[230:231], s[46:47], 0, v[132:133]
	s_mov_b32 m0, s53
	s_nop 0
	global_load_lds_dwordx4 v[230:231], off
	s_waitcnt vmcnt(8)
	s_waitcnt lgkmcnt(0)
	s_barrier
	s_setprio 1
	s_waitcnt lgkmcnt(0)
	v_mfma_f32_16x16x32_bf16 v[124:127], v[144:147], v[184:187], v[124:127]
	v_mfma_f32_16x16x32_bf16 v[120:123], v[160:163], v[184:187], v[120:123]
	v_mfma_f32_16x16x32_bf16 v[108:111], v[144:147], v[192:195], v[108:111]
	v_mfma_f32_16x16x32_bf16 v[104:107], v[160:163], v[192:195], v[104:107]
	v_mfma_f32_16x16x32_bf16 v[92:95], v[144:147], v[202:205], v[92:95]
	v_mfma_f32_16x16x32_bf16 v[88:91], v[160:163], v[202:205], v[88:91]
	v_mfma_f32_16x16x32_bf16 v[76:79], v[144:147], v[210:213], v[76:79]
	v_mfma_f32_16x16x32_bf16 v[72:75], v[160:163], v[210:213], v[72:75]
	v_mfma_f32_16x16x32_bf16 v[124:127], v[156:159], v[188:191], v[124:127]
	v_mfma_f32_16x16x32_bf16 v[120:123], v[164:167], v[188:191], v[120:123]
	v_mfma_f32_16x16x32_bf16 v[108:111], v[156:159], v[196:199], v[108:111]
	v_mfma_f32_16x16x32_bf16 v[104:107], v[164:167], v[196:199], v[104:107]
	v_mfma_f32_16x16x32_bf16 v[92:95], v[156:159], v[206:209], v[92:95]
	v_mfma_f32_16x16x32_bf16 v[88:91], v[164:167], v[206:209], v[88:91]
	v_mfma_f32_16x16x32_bf16 v[76:79], v[156:159], v[214:217], v[76:79]
	v_mfma_f32_16x16x32_bf16 v[72:75], v[164:167], v[214:217], v[72:75]
	s_setprio 0
	s_setprio 1
	v_mfma_f32_16x16x32_bf16 v[116:119], v[168:171], v[184:187], v[116:119]
	v_mfma_f32_16x16x32_bf16 v[112:115], v[176:179], v[184:187], v[112:115]
	v_mfma_f32_16x16x32_bf16 v[100:103], v[168:171], v[192:195], v[100:103]
	v_mfma_f32_16x16x32_bf16 v[96:99], v[176:179], v[192:195], v[96:99]
	v_mfma_f32_16x16x32_bf16 v[84:87], v[168:171], v[202:205], v[84:87]
	v_mfma_f32_16x16x32_bf16 v[80:83], v[176:179], v[202:205], v[80:83]
	v_mfma_f32_16x16x32_bf16 v[68:71], v[168:171], v[210:213], v[68:71]
	v_mfma_f32_16x16x32_bf16 v[64:67], v[176:179], v[210:213], v[64:67]
	v_mfma_f32_16x16x32_bf16 v[116:119], v[172:175], v[188:191], v[116:119]
	v_mfma_f32_16x16x32_bf16 v[112:115], v[180:183], v[188:191], v[112:115]
	v_mfma_f32_16x16x32_bf16 v[100:103], v[172:175], v[196:199], v[100:103]
	v_mfma_f32_16x16x32_bf16 v[96:99], v[180:183], v[196:199], v[96:99]
	v_mfma_f32_16x16x32_bf16 v[84:87], v[172:175], v[206:209], v[84:87]
	v_mfma_f32_16x16x32_bf16 v[80:83], v[180:183], v[206:209], v[80:83]
	v_mfma_f32_16x16x32_bf16 v[68:71], v[172:175], v[214:217], v[68:71]
	v_mfma_f32_16x16x32_bf16 v[64:67], v[180:183], v[214:217], v[64:67]
	s_setprio 0
	s_barrier
; #define PG8_STAGE(bufoff, gbase, voff) do { _Pragma("unroll") for (int _i = 0; _i < 2; ++_i) \
;         __builtin_amdgcn_global_load_lds((const unsigned*)((const char*)(gbase) + (voff)[_i]), (PG8_LAS unsigned*)(lds + (bufoff) + ldsw + _i * 8192), 16, 0, 0); } while (0)
; #define PG8_LDA(dst, b, h) do { _Pragma("unroll") for (int m = 0; m < 4; ++m) _Pragma("unroll") for (int k = 0; k < 2; ++k) dst[m][k] = *(const PG8_LAS bf16x8*)(lds + PG8_SA(b, h) + aoff + m * 2048 + k * 1024); } while (0)
; #define PG8_MMA(ai, bj, At, Bt) do { __builtin_amdgcn_s_setprio(1); _Pragma("unroll") for (int m = 0; m < 4; ++m) _Pragma("unroll") for (int n = 0; n < 2; ++n) _Pragma("unroll") for (int k = 0; k < 2; ++k) \
;         acc[ai][bj][m][n] = __builtin_amdgcn_mfma_f32_16x16x32_bf16(Bt[n][k], At[m][k], acc[ai][bj][m][n], 0, 0, 0); __builtin_amdgcn_s_setprio(0); } while (0)
; #define PG8_WAIT_V(n) asm volatile("s_waitcnt vmcnt(" #n ")" ::: "memory")
; #define PG8_WAIT_L(n) asm volatile("s_waitcnt lgkmcnt(" #n ")" ::: "memory")
; #define PG8_BAR __builtin_amdgcn_s_barrier()
; #define PG8_SCHED __builtin_amdgcn_sched_barrier(0)
; template <class Epi, class Sched, bool ALIGN_EPI = false, bool SP2 = false>
; __device__ __forceinline__ void gemm_phase(PG8_LAS unsigned char* lds, const Gemm g, const Sched& S, const Epi& E) {
;     ...
;         for (int t = 0; t < nt; t += 2) {
;             const bool last = (t == nt - 2);
;     ...
;             PG8_LDA(At, 1, 1); PG8_STAGE(PG8_SB(1, 0), b3, voffB); PG8_STAGE(PG8_SB(1, 1), b3 + hstep, voffB); PG8_STAGE(PG8_SA(1, 0), a3, voffA);
;             PG8_WAIT_V(8); PG8_WAIT_L(0); PG8_BAR; PG8_MMA(1, 0, At, B0); PG8_MMA(1, 1, At, B1); PG8_BAR; PG8_SCHED;
	s_add_i32 s16, s16, s49
	v_lshl_add_u64 v[218:219], v[218:219], 0, s[36:37]
	s_mov_b32 m0, s16
	ds_read_b128 v[184:187], v153 offset:49152
	ds_read_b128 v[188:191], v153 offset:50176
	ds_read_b128 v[192:195], v153 offset:51200
	ds_read_b128 v[196:199], v153 offset:52224
	ds_read_b128 v[202:205], v153 offset:53248
	ds_read_b128 v[206:209], v153 offset:54272
	ds_read_b128 v[210:213], v153 offset:55296
	ds_read_b128 v[214:217], v153 offset:56320
	global_load_lds_dwordx4 v[218:219], off
	v_lshl_add_u64 v[218:219], v[220:221], 0, s[36:37]
	s_add_i32 m0, s16, 0x2000
	s_add_i32 s16, s17, s49
	global_load_lds_dwordx4 v[218:219], off
	v_lshl_add_u64 v[218:219], v[222:223], 0, s[36:37]
	s_mov_b32 m0, s16
	s_nop 0
	global_load_lds_dwordx4 v[218:219], off
	v_lshl_add_u64 v[218:219], v[224:225], 0, s[36:37]
	s_add_i32 m0, s16, 0x2000
	s_nop 0
	global_load_lds_dwordx4 v[218:219], off
	v_lshl_add_u64 v[218:219], v[226:227], 0, s[100:101]
	s_mov_b32 m0, s54
	s_nop 0
	global_load_lds_dwordx4 v[218:219], off
	v_lshl_add_u64 v[218:219], v[228:229], 0, s[100:101]
	s_mov_b32 m0, s55
	s_nop 0
	global_load_lds_dwordx4 v[218:219], off
	s_waitcnt vmcnt(8)
	s_waitcnt lgkmcnt(0)
	s_barrier
	s_setprio 1
	s_waitcnt lgkmcnt(0)
	v_mfma_f32_16x16x32_bf16 v[60:63], v[144:147], v[184:187], v[60:63]
	v_mfma_f32_16x16x32_bf16 v[56:59], v[160:163], v[184:187], v[56:59]
	v_mfma_f32_16x16x32_bf16 v[44:47], v[144:147], v[192:195], v[44:47]
	v_mfma_f32_16x16x32_bf16 v[40:43], v[160:163], v[192:195], v[40:43]
	v_mfma_f32_16x16x32_bf16 v[28:31], v[144:147], v[202:205], v[28:31]
	v_mfma_f32_16x16x32_bf16 v[24:27], v[160:163], v[202:205], v[24:27]
	v_mfma_f32_16x16x32_bf16 v[12:15], v[144:147], v[210:213], v[12:15]
	v_mfma_f32_16x16x32_bf16 v[8:11], v[160:163], v[210:213], v[8:11]
	v_mfma_f32_16x16x32_bf16 v[60:63], v[156:159], v[188:191], v[60:63]
	v_mfma_f32_16x16x32_bf16 v[56:59], v[164:167], v[188:191], v[56:59]
	v_mfma_f32_16x16x32_bf16 v[44:47], v[156:159], v[196:199], v[44:47]
	v_mfma_f32_16x16x32_bf16 v[40:43], v[164:167], v[196:199], v[40:43]
	v_mfma_f32_16x16x32_bf16 v[28:31], v[156:159], v[206:209], v[28:31]
	v_mfma_f32_16x16x32_bf16 v[24:27], v[164:167], v[206:209], v[24:27]
	v_mfma_f32_16x16x32_bf16 v[12:15], v[156:159], v[214:217], v[12:15]
	v_mfma_f32_16x16x32_bf16 v[8:11], v[164:167], v[214:217], v[8:11]
	s_setprio 0
	s_setprio 1
	v_mfma_f32_16x16x32_bf16 v[52:55], v[168:171], v[184:187], v[52:55]
	v_mfma_f32_16x16x32_bf16 v[48:51], v[176:179], v[184:187], v[48:51]
	v_mfma_f32_16x16x32_bf16 v[36:39], v[168:171], v[192:195], v[36:39]
	v_mfma_f32_16x16x32_bf16 v[32:35], v[176:179], v[192:195], v[32:35]
	v_mfma_f32_16x16x32_bf16 v[20:23], v[168:171], v[202:205], v[20:23]
	v_mfma_f32_16x16x32_bf16 v[16:19], v[176:179], v[202:205], v[16:19]
	v_mfma_f32_16x16x32_bf16 v[4:7], v[168:171], v[210:213], v[4:7]
	v_mfma_f32_16x16x32_bf16 v[0:3], v[176:179], v[210:213], v[0:3]
	v_mfma_f32_16x16x32_bf16 v[52:55], v[172:175], v[188:191], v[52:55]
	v_mfma_f32_16x16x32_bf16 v[48:51], v[180:183], v[188:191], v[48:51]
	v_mfma_f32_16x16x32_bf16 v[36:39], v[172:175], v[196:199], v[36:39]
	v_mfma_f32_16x16x32_bf16 v[32:35], v[180:183], v[196:199], v[32:35]
	v_mfma_f32_16x16x32_bf16 v[20:23], v[172:175], v[206:209], v[20:23]
	v_mfma_f32_16x16x32_bf16 v[16:19], v[180:183], v[206:209], v[16:19]
	v_mfma_f32_16x16x32_bf16 v[4:7], v[172:175], v[214:217], v[4:7]
	v_mfma_f32_16x16x32_bf16 v[0:3], v[180:183], v[214:217], v[0:3]
	s_setprio 0
	s_barrier
	s_add_u32 s44, s44, 0x10000
	s_addc_u32 s45, s45, 0
	s_add_u32 s68, s68, 0x100
	s_addc_u32 s69, s69, 0
	s_cmp_ge_i32 s70, s57
	s_mov_b32 s46, s70
	s_cbranch_scc1 .LBB0_1105
